# v44 + phases 2/6: fragment-read wait taken before the MMA-opening barrier (nothing between release and first MFMA)
# speedup vs baseline: 1.0053x; 1.0053x over previous
.LBB0_127:
	s_add_u32 s22, s20, 0xfff80080
	s_addc_u32 s23, s21, -1
	s_add_i32 s50, 0, 0x10000
	s_cmp_eq_u32 s49, 4
	s_cselect_b32 s23, s81, s23
	s_cselect_b32 s22, s80, s22
	s_cselect_b32 s39, s19, s48
	s_cselect_b32 s38, s31, s47
	v_lshl_add_u64 v[178:179], s[20:21], 0, v[138:139]
	s_add_i32 m0, s27, 0xc000
	ds_read_b128 v[162:165], v144
	ds_read_b128 v[166:169], v144 offset:1024
	ds_read_b128 v[170:173], v144 offset:2048
	ds_read_b128 v[174:177], v144 offset:3072
	ds_read_b128 v[192:195], v144 offset:4096
	ds_read_b128 v[196:199], v144 offset:5120
	ds_read_b128 v[200:203], v144 offset:6144
	ds_read_b128 v[204:207], v144 offset:7168
	global_load_lds_dwordx4 v[178:179], off
	v_lshl_add_u64 v[178:179], s[20:21], 0, v[140:141]
	s_add_i32 m0, s27, 0xe000
	s_nop 0
	global_load_lds_dwordx4 v[178:179], off
	s_waitcnt lgkmcnt(8)
	s_barrier
	s_waitcnt lgkmcnt(0)
	v_mfma_f32_16x16x32_bf16 v[126:129], v[146:149], v[162:165], v[126:129]
	v_mfma_f32_16x16x32_bf16 v[122:125], v[154:157], v[162:165], v[122:125]
	v_mfma_f32_16x16x32_bf16 v[118:121], v[146:149], v[170:173], v[118:121]
	v_mfma_f32_16x16x32_bf16 v[114:117], v[154:157], v[170:173], v[114:117]
	v_mfma_f32_16x16x32_bf16 v[102:105], v[146:149], v[192:195], v[102:105]
	v_mfma_f32_16x16x32_bf16 v[98:101], v[154:157], v[192:195], v[98:101]
	v_mfma_f32_16x16x32_bf16 v[86:89], v[146:149], v[200:203], v[86:89]
	v_mfma_f32_16x16x32_bf16 v[82:85], v[154:157], v[200:203], v[82:85]
	v_mfma_f32_16x16x32_bf16 v[126:129], v[150:153], v[166:169], v[126:129]
	v_mfma_f32_16x16x32_bf16 v[122:125], v[158:161], v[166:169], v[122:125]
	v_mfma_f32_16x16x32_bf16 v[118:121], v[150:153], v[174:177], v[118:121]
	v_mfma_f32_16x16x32_bf16 v[114:117], v[158:161], v[174:177], v[114:117]
	v_mfma_f32_16x16x32_bf16 v[102:105], v[150:153], v[196:199], v[102:105]
	v_mfma_f32_16x16x32_bf16 v[98:101], v[158:161], v[196:199], v[98:101]
	v_mfma_f32_16x16x32_bf16 v[86:89], v[150:153], v[204:207], v[86:89]
	v_mfma_f32_16x16x32_bf16 v[82:85], v[158:161], v[204:207], v[82:85]
	s_barrier
	s_add_i32 s52, 0, 0x14000
	s_add_i32 s50, s50, s26
	v_add_u32_e32 v145, s52, v142
	v_lshl_add_u64 v[178:179], s[38:39], 0, v[134:135]
	s_mov_b32 m0, s50
	ds_read_b128 v[208:211], v145
	ds_read_b128 v[224:227], v145 offset:1024
	ds_read_b128 v[228:231], v145 offset:2048
	ds_read_b128 v[232:235], v145 offset:3072
	global_load_lds_dwordx4 v[178:179], off
	v_lshl_add_u64 v[212:213], s[38:39], 0, v[130:131]
	s_add_i32 m0, s50, 0x2000
	s_nop 0
	global_load_lds_dwordx4 v[212:213], off
	s_mov_b32 m0, s27
	v_lshl_add_u64 v[236:237], s[22:23], 0, v[136:137]
	s_waitcnt lgkmcnt(0)
	s_barrier
	v_mfma_f32_16x16x32_bf16 v[110:113], v[208:211], v[162:165], v[110:113]
	v_mfma_f32_16x16x32_bf16 v[106:109], v[228:231], v[162:165], v[106:109]
	v_mfma_f32_16x16x32_bf16 v[94:97], v[208:211], v[170:173], v[94:97]
	v_mfma_f32_16x16x32_bf16 v[90:93], v[228:231], v[170:173], v[90:93]
	v_mfma_f32_16x16x32_bf16 v[78:81], v[208:211], v[192:195], v[78:81]
	v_mfma_f32_16x16x32_bf16 v[74:77], v[228:231], v[192:195], v[74:77]
	v_mfma_f32_16x16x32_bf16 v[70:73], v[208:211], v[200:203], v[70:73]
	v_mfma_f32_16x16x32_bf16 v[66:69], v[228:231], v[200:203], v[66:69]
	v_mfma_f32_16x16x32_bf16 v[110:113], v[224:227], v[166:169], v[110:113]
	v_mfma_f32_16x16x32_bf16 v[106:109], v[232:235], v[166:169], v[106:109]
	v_mfma_f32_16x16x32_bf16 v[94:97], v[224:227], v[174:177], v[94:97]
	v_mfma_f32_16x16x32_bf16 v[90:93], v[232:235], v[174:177], v[90:93]
	v_mfma_f32_16x16x32_bf16 v[78:81], v[224:227], v[196:199], v[78:81]
	v_mfma_f32_16x16x32_bf16 v[74:77], v[232:235], v[196:199], v[74:77]
	v_mfma_f32_16x16x32_bf16 v[70:73], v[224:227], v[204:207], v[70:73]
	v_mfma_f32_16x16x32_bf16 v[66:69], v[232:235], v[204:207], v[66:69]
	s_barrier
	ds_read_b128 v[162:165], v144 offset:16384
	ds_read_b128 v[166:169], v144 offset:17408
	ds_read_b128 v[170:173], v144 offset:18432
	ds_read_b128 v[174:177], v144 offset:19456
	ds_read_b128 v[192:195], v144 offset:20480
	ds_read_b128 v[196:199], v144 offset:21504
	ds_read_b128 v[200:203], v144 offset:22528
	ds_read_b128 v[204:207], v144 offset:23552
	global_load_lds_dwordx4 v[236:237], off
	v_lshl_add_u64 v[238:239], s[22:23], 0, v[132:133]
	s_mov_b32 m0, s28
	s_nop 0
	global_load_lds_dwordx4 v[238:239], off
	s_waitcnt vmcnt(10)
	s_barrier
	s_waitcnt lgkmcnt(0)
	v_mfma_f32_16x16x32_bf16 v[62:65], v[146:149], v[162:165], v[62:65]
	v_mfma_f32_16x16x32_bf16 v[58:61], v[154:157], v[162:165], v[58:61]
	v_mfma_f32_16x16x32_bf16 v[54:57], v[146:149], v[170:173], v[54:57]
	v_mfma_f32_16x16x32_bf16 v[50:53], v[154:157], v[170:173], v[50:53]
	v_mfma_f32_16x16x32_bf16 v[38:41], v[146:149], v[192:195], v[38:41]
	v_mfma_f32_16x16x32_bf16 v[34:37], v[154:157], v[192:195], v[34:37]
	v_mfma_f32_16x16x32_bf16 v[22:25], v[146:149], v[200:203], v[22:25]
	v_mfma_f32_16x16x32_bf16 v[18:21], v[154:157], v[200:203], v[18:21]
	v_mfma_f32_16x16x32_bf16 v[62:65], v[150:153], v[166:169], v[62:65]
	v_mfma_f32_16x16x32_bf16 v[58:61], v[158:161], v[166:169], v[58:61]
	v_mfma_f32_16x16x32_bf16 v[54:57], v[150:153], v[174:177], v[54:57]
	v_mfma_f32_16x16x32_bf16 v[50:53], v[158:161], v[174:177], v[50:53]
	v_mfma_f32_16x16x32_bf16 v[38:41], v[150:153], v[196:199], v[38:41]
	v_mfma_f32_16x16x32_bf16 v[34:37], v[158:161], v[196:199], v[34:37]
	v_mfma_f32_16x16x32_bf16 v[22:25], v[150:153], v[204:207], v[22:25]
	v_mfma_f32_16x16x32_bf16 v[18:21], v[158:161], v[204:207], v[18:21]
	s_barrier
	s_add_u32 s50, s38, 0x20000
	s_addc_u32 s51, s39, 0
	s_add_i32 s52, s52, s26
	v_lshl_add_u64 v[146:147], s[50:51], 0, v[134:135]
	s_mov_b32 m0, s52
	s_nop 0
	global_load_lds_dwordx4 v[146:147], off
	v_lshl_add_u64 v[146:147], s[50:51], 0, v[130:131]
	s_add_i32 m0, s52, 0x2000
	s_nop 0
	global_load_lds_dwordx4 v[146:147], off
	v_add_u32_e32 v145, 0x18000, v142
	ds_read_b128 v[146:149], v145
	ds_read_b128 v[150:153], v145 offset:1024
	ds_read_b128 v[154:157], v145 offset:2048
	ds_read_b128 v[158:161], v145 offset:3072
	s_add_i32 s50, 0, 0x18000
	s_waitcnt vmcnt(6)
	s_barrier
	v_mfma_f32_16x16x32_bf16 v[46:49], v[208:211], v[162:165], v[46:49]
	v_mfma_f32_16x16x32_bf16 v[42:45], v[228:231], v[162:165], v[42:45]
	v_mfma_f32_16x16x32_bf16 v[30:33], v[208:211], v[170:173], v[30:33]
	v_mfma_f32_16x16x32_bf16 v[26:29], v[228:231], v[170:173], v[26:29]
	v_mfma_f32_16x16x32_bf16 v[14:17], v[208:211], v[192:195], v[14:17]
	v_mfma_f32_16x16x32_bf16 v[10:13], v[228:231], v[192:195], v[10:13]
	v_mfma_f32_16x16x32_bf16 v[6:9], v[208:211], v[200:203], v[6:9]
	v_mfma_f32_16x16x32_bf16 v[2:5], v[228:231], v[200:203], v[2:5]
	v_mfma_f32_16x16x32_bf16 v[46:49], v[224:227], v[166:169], v[46:49]
	v_mfma_f32_16x16x32_bf16 v[42:45], v[232:235], v[166:169], v[42:45]
	v_mfma_f32_16x16x32_bf16 v[30:33], v[224:227], v[174:177], v[30:33]
	v_mfma_f32_16x16x32_bf16 v[26:29], v[232:235], v[174:177], v[26:29]
	v_mfma_f32_16x16x32_bf16 v[14:17], v[224:227], v[196:199], v[14:17]
	v_mfma_f32_16x16x32_bf16 v[10:13], v[232:235], v[196:199], v[10:13]
	v_mfma_f32_16x16x32_bf16 v[6:9], v[224:227], v[204:207], v[6:9]
	v_mfma_f32_16x16x32_bf16 v[2:5], v[232:235], v[204:207], v[2:5]
	s_barrier
	s_add_u32 s22, s22, 0x80000
	s_addc_u32 s23, s23, 0
	s_mov_b32 m0, s29
	v_lshl_add_u64 v[208:209], s[22:23], 0, v[136:137]
	ds_read_b128 v[162:165], v144 offset:32768
	ds_read_b128 v[166:169], v144 offset:33792
	ds_read_b128 v[170:173], v144 offset:34816
	ds_read_b128 v[174:177], v144 offset:35840
	ds_read_b128 v[192:195], v144 offset:36864
	ds_read_b128 v[196:199], v144 offset:37888
	ds_read_b128 v[200:203], v144 offset:38912
	ds_read_b128 v[204:207], v144 offset:39936
	global_load_lds_dwordx4 v[208:209], off
	v_lshl_add_u64 v[208:209], s[22:23], 0, v[132:133]
	s_mov_b32 m0, s36
	s_nop 0
	global_load_lds_dwordx4 v[208:209], off
	s_waitcnt lgkmcnt(8)
	s_barrier
	s_waitcnt lgkmcnt(0)
	v_mfma_f32_16x16x32_bf16 v[126:129], v[146:149], v[162:165], v[126:129]
	v_mfma_f32_16x16x32_bf16 v[122:125], v[154:157], v[162:165], v[122:125]
	v_mfma_f32_16x16x32_bf16 v[118:121], v[146:149], v[170:173], v[118:121]
	v_mfma_f32_16x16x32_bf16 v[114:117], v[154:157], v[170:173], v[114:117]
	v_mfma_f32_16x16x32_bf16 v[102:105], v[146:149], v[192:195], v[102:105]
	v_mfma_f32_16x16x32_bf16 v[98:101], v[154:157], v[192:195], v[98:101]
	v_mfma_f32_16x16x32_bf16 v[86:89], v[146:149], v[200:203], v[86:89]
	v_mfma_f32_16x16x32_bf16 v[82:85], v[154:157], v[200:203], v[82:85]
	v_mfma_f32_16x16x32_bf16 v[126:129], v[150:153], v[166:169], v[126:129]
	v_mfma_f32_16x16x32_bf16 v[122:125], v[158:161], v[166:169], v[122:125]
	v_mfma_f32_16x16x32_bf16 v[118:121], v[150:153], v[174:177], v[118:121]
	v_mfma_f32_16x16x32_bf16 v[114:117], v[158:161], v[174:177], v[114:117]
	v_mfma_f32_16x16x32_bf16 v[102:105], v[150:153], v[196:199], v[102:105]
	v_mfma_f32_16x16x32_bf16 v[98:101], v[158:161], v[196:199], v[98:101]
	v_mfma_f32_16x16x32_bf16 v[86:89], v[150:153], v[204:207], v[86:89]
	v_mfma_f32_16x16x32_bf16 v[82:85], v[158:161], v[204:207], v[82:85]
	s_barrier
	s_add_i32 s51, 0, 0x1c000
	s_add_i32 s22, s50, s26
	v_add_u32_e32 v145, s51, v142
	v_lshl_add_u64 v[178:179], v[178:179], 0, s[78:79]
	s_mov_b32 m0, s22
	ds_read_b128 v[208:211], v145
	ds_read_b128 v[224:227], v145 offset:1024
	ds_read_b128 v[228:231], v145 offset:2048
	ds_read_b128 v[232:235], v145 offset:3072
	global_load_lds_dwordx4 v[178:179], off
	v_lshl_add_u64 v[178:179], v[212:213], 0, s[78:79]
	s_add_i32 m0, s22, 0x2000
	s_nop 0
	global_load_lds_dwordx4 v[178:179], off
	s_mov_b32 m0, s42
	v_lshl_add_u64 v[178:179], v[236:237], 0, s[78:79]
	s_waitcnt lgkmcnt(0)
	s_barrier
	v_mfma_f32_16x16x32_bf16 v[110:113], v[208:211], v[162:165], v[110:113]
	v_mfma_f32_16x16x32_bf16 v[106:109], v[228:231], v[162:165], v[106:109]
	v_mfma_f32_16x16x32_bf16 v[94:97], v[208:211], v[170:173], v[94:97]
	v_mfma_f32_16x16x32_bf16 v[90:93], v[228:231], v[170:173], v[90:93]
	v_mfma_f32_16x16x32_bf16 v[78:81], v[208:211], v[192:195], v[78:81]
	v_mfma_f32_16x16x32_bf16 v[74:77], v[228:231], v[192:195], v[74:77]
	v_mfma_f32_16x16x32_bf16 v[70:73], v[208:211], v[200:203], v[70:73]
	v_mfma_f32_16x16x32_bf16 v[66:69], v[228:231], v[200:203], v[66:69]
	v_mfma_f32_16x16x32_bf16 v[110:113], v[224:227], v[166:169], v[110:113]
	v_mfma_f32_16x16x32_bf16 v[106:109], v[232:235], v[166:169], v[106:109]
	v_mfma_f32_16x16x32_bf16 v[94:97], v[224:227], v[174:177], v[94:97]
	v_mfma_f32_16x16x32_bf16 v[90:93], v[232:235], v[174:177], v[90:93]
	v_mfma_f32_16x16x32_bf16 v[78:81], v[224:227], v[196:199], v[78:81]
	v_mfma_f32_16x16x32_bf16 v[74:77], v[232:235], v[196:199], v[74:77]
	v_mfma_f32_16x16x32_bf16 v[70:73], v[224:227], v[204:207], v[70:73]
	v_mfma_f32_16x16x32_bf16 v[66:69], v[232:235], v[204:207], v[66:69]
	s_barrier
	ds_read_b128 v[162:165], v144 offset:49152
	ds_read_b128 v[166:169], v144 offset:50176
	ds_read_b128 v[170:173], v144 offset:51200
	ds_read_b128 v[174:177], v144 offset:52224
	ds_read_b128 v[192:195], v144 offset:53248
	ds_read_b128 v[196:199], v144 offset:54272
	ds_read_b128 v[200:203], v144 offset:55296
	ds_read_b128 v[204:207], v144 offset:56320
	global_load_lds_dwordx4 v[178:179], off
	v_lshl_add_u64 v[178:179], v[238:239], 0, s[78:79]
	s_mov_b32 m0, s43
	s_nop 0
	global_load_lds_dwordx4 v[178:179], off
	s_waitcnt vmcnt(10)
	s_barrier
	s_waitcnt lgkmcnt(0)
	v_mfma_f32_16x16x32_bf16 v[62:65], v[146:149], v[162:165], v[62:65]
	v_mfma_f32_16x16x32_bf16 v[58:61], v[154:157], v[162:165], v[58:61]
	v_mfma_f32_16x16x32_bf16 v[54:57], v[146:149], v[170:173], v[54:57]
	v_mfma_f32_16x16x32_bf16 v[50:53], v[154:157], v[170:173], v[50:53]
	v_mfma_f32_16x16x32_bf16 v[38:41], v[146:149], v[192:195], v[38:41]
	v_mfma_f32_16x16x32_bf16 v[34:37], v[154:157], v[192:195], v[34:37]
	v_mfma_f32_16x16x32_bf16 v[22:25], v[146:149], v[200:203], v[22:25]
	v_mfma_f32_16x16x32_bf16 v[18:21], v[154:157], v[200:203], v[18:21]
	v_mfma_f32_16x16x32_bf16 v[62:65], v[150:153], v[166:169], v[62:65]
	v_mfma_f32_16x16x32_bf16 v[58:61], v[158:161], v[166:169], v[58:61]
	v_mfma_f32_16x16x32_bf16 v[54:57], v[150:153], v[174:177], v[54:57]
	v_mfma_f32_16x16x32_bf16 v[50:53], v[158:161], v[174:177], v[50:53]
	v_mfma_f32_16x16x32_bf16 v[38:41], v[150:153], v[196:199], v[38:41]
	v_mfma_f32_16x16x32_bf16 v[34:37], v[158:161], v[196:199], v[34:37]
	v_mfma_f32_16x16x32_bf16 v[22:25], v[150:153], v[204:207], v[22:25]
	v_mfma_f32_16x16x32_bf16 v[18:21], v[158:161], v[204:207], v[18:21]
	s_barrier
	s_add_u32 s22, s38, 0x20080
	s_addc_u32 s23, s39, 0
	s_add_i32 s38, s51, s26
	v_lshl_add_u64 v[146:147], s[22:23], 0, v[134:135]
	s_mov_b32 m0, s38
	s_nop 0
	global_load_lds_dwordx4 v[146:147], off
	v_lshl_add_u64 v[146:147], s[22:23], 0, v[130:131]
	s_add_i32 m0, s38, 0x2000
	s_nop 0
	global_load_lds_dwordx4 v[146:147], off
	v_add_u32_e32 v145, 0x10000, v142
	ds_read_b128 v[146:149], v145
	ds_read_b128 v[150:153], v145 offset:1024
	ds_read_b128 v[154:157], v145 offset:2048
	ds_read_b128 v[158:161], v145 offset:3072
	s_add_i32 s49, s49, 2
	s_add_u32 s20, s20, 0x100
	s_addc_u32 s21, s21, 0
	s_add_u32 s47, s47, 0x100
	s_addc_u32 s48, s48, 0
	s_cmp_gt_u32 s49, 5
	s_waitcnt vmcnt(6)
	s_barrier
	v_mfma_f32_16x16x32_bf16 v[46:49], v[208:211], v[162:165], v[46:49]
	v_mfma_f32_16x16x32_bf16 v[42:45], v[228:231], v[162:165], v[42:45]
	v_mfma_f32_16x16x32_bf16 v[30:33], v[208:211], v[170:173], v[30:33]
	v_mfma_f32_16x16x32_bf16 v[26:29], v[228:231], v[170:173], v[26:29]
	v_mfma_f32_16x16x32_bf16 v[14:17], v[208:211], v[192:195], v[14:17]
	v_mfma_f32_16x16x32_bf16 v[10:13], v[228:231], v[192:195], v[10:13]
	v_mfma_f32_16x16x32_bf16 v[6:9], v[208:211], v[200:203], v[6:9]
	v_mfma_f32_16x16x32_bf16 v[2:5], v[228:231], v[200:203], v[2:5]
	v_mfma_f32_16x16x32_bf16 v[46:49], v[224:227], v[166:169], v[46:49]
	v_mfma_f32_16x16x32_bf16 v[42:45], v[232:235], v[166:169], v[42:45]
	v_mfma_f32_16x16x32_bf16 v[30:33], v[224:227], v[174:177], v[30:33]
	v_mfma_f32_16x16x32_bf16 v[26:29], v[232:235], v[174:177], v[26:29]
	v_mfma_f32_16x16x32_bf16 v[14:17], v[224:227], v[196:199], v[14:17]
	v_mfma_f32_16x16x32_bf16 v[10:13], v[232:235], v[196:199], v[10:13]
	v_mfma_f32_16x16x32_bf16 v[6:9], v[224:227], v[204:207], v[6:9]
	v_mfma_f32_16x16x32_bf16 v[2:5], v[232:235], v[204:207], v[2:5]
	s_barrier
	s_cbranch_scc0 .LBB0_127
	s_waitcnt lgkmcnt(0)
	v_lshl_add_u32 v146, s46, 8, v1
	v_lshl_or_b32 v148, s45, 8, v143
	v_ashrrev_i32_e32 v147, 31, v146
	v_readlane_b32 s48, v254, 40
	v_ashrrev_i32_e32 v149, 31, v148
	v_lshlrev_b64 v[150:151], 12, v[146:147]
	v_readlane_b32 s52, v254, 44
	v_readlane_b32 s53, v254, 45
	v_lshlrev_b64 v[148:149], 1, v[148:149]
	s_mov_b32 s19, 0x80000
	v_lshl_add_u64 v[150:151], s[52:53], 0, v[150:151]
	v_lshl_add_u64 v[150:151], v[150:151], 0, v[148:149]
	s_mov_b64 s[20:21], 0x80000
	v_cvt_pk_bf16_f32 v62, v62, v63
	v_cvt_pk_bf16_f32 v63, v64, v65
	v_cvt_pk_bf16_f32 v64, v58, v59
	v_add_co_u32_e32 v58, vcc, s19, v150
	v_cvt_pk_bf16_f32 v70, v70, v71
	v_cvt_pk_bf16_f32 v71, v72, v73
	v_cvt_pk_bf16_f32 v72, v66, v67
	v_lshl_add_u64 v[66:67], v[150:151], 0, s[20:21]
	v_addc_co_u32_e32 v59, vcc, 0, v151, vcc
	v_cvt_pk_bf16_f32 v46, v46, v47
	v_cvt_pk_bf16_f32 v47, v48, v49
	v_cvt_pk_bf16_f32 v48, v42, v43
	v_cvt_pk_bf16_f32 v49, v44, v45
	s_mov_b32 s19, 0x90000
	v_cvt_pk_bf16_f32 v110, v110, v111
	v_cvt_pk_bf16_f32 v111, v112, v113
	v_cvt_pk_bf16_f32 v112, v106, v107
	v_or_b32_e32 v106, 16, v146
	global_store_dwordx4 v[66:67], v[46:49], off offset:256
	s_mov_b64 s[20:21], 0x90000
	v_ashrrev_i32_e32 v107, 31, v106
	v_add_co_u32_e32 v48, vcc, s19, v150
	v_cvt_pk_bf16_f32 v94, v94, v95
	v_cvt_pk_bf16_f32 v95, v96, v97
	v_cvt_pk_bf16_f32 v96, v90, v91
	v_or_b32_e32 v90, 32, v146
	v_lshl_add_u64 v[46:47], v[150:151], 0, s[20:21]
	v_addc_co_u32_e32 v49, vcc, 0, v151, vcc
	v_cvt_pk_bf16_f32 v30, v30, v31
	v_cvt_pk_bf16_f32 v31, v32, v33
	v_cvt_pk_bf16_f32 v32, v26, v27
	v_cvt_pk_bf16_f32 v33, v28, v29
	s_mov_b32 s19, 0xa0000
	v_lshlrev_b64 v[106:107], 12, v[106:107]
	v_ashrrev_i32_e32 v91, 31, v90
	v_cvt_pk_bf16_f32 v78, v78, v79
	v_cvt_pk_bf16_f32 v79, v80, v81
	v_cvt_pk_bf16_f32 v80, v74, v75
	v_or_b32_e32 v74, 48, v146
	global_store_dwordx4 v[46:47], v[30:33], off offset:256
	s_mov_b64 s[20:21], 0xa0000
	v_cvt_pk_bf16_f32 v113, v108, v109
	v_add_co_u32_e32 v32, vcc, s19, v150
	v_lshl_add_u64 v[106:107], s[52:53], 0, v[106:107]
	v_lshlrev_b64 v[90:91], 12, v[90:91]
	v_ashrrev_i32_e32 v75, 31, v74
	v_lshl_add_u64 v[30:31], v[150:151], 0, s[20:21]
	v_addc_co_u32_e32 v33, vcc, 0, v151, vcc
	v_cvt_pk_bf16_f32 v14, v14, v15
	v_cvt_pk_bf16_f32 v15, v16, v17
	v_cvt_pk_bf16_f32 v16, v10, v11
	v_cvt_pk_bf16_f32 v17, v12, v13
	s_mov_b32 s19, 0xb0000
	global_store_dwordx4 v[150:151], v[110:113], off offset:256
	v_cvt_pk_bf16_f32 v97, v92, v93
	v_lshl_add_u64 v[90:91], s[52:53], 0, v[90:91]
	v_lshl_add_u64 v[110:111], v[106:107], 0, v[148:149]
	v_lshlrev_b64 v[74:75], 12, v[74:75]
	global_store_dwordx4 v[30:31], v[14:17], off offset:256
	global_store_dwordx4 v[110:111], v[94:97], off offset:256
	v_cvt_pk_bf16_f32 v81, v76, v77
	v_add_co_u32_e32 v16, vcc, s19, v150
	v_lshl_add_u64 v[94:95], v[90:91], 0, v[148:149]
	v_lshl_add_u64 v[74:75], s[52:53], 0, v[74:75]
	s_mov_b64 s[20:21], 0xb0000
	v_addc_co_u32_e32 v17, vcc, 0, v151, vcc
	v_cvt_pk_bf16_f32 v126, v126, v127
	v_cvt_pk_bf16_f32 v127, v128, v129
	v_cvt_pk_bf16_f32 v128, v122, v123
	v_cvt_pk_bf16_f32 v129, v124, v125
	v_cvt_pk_bf16_f32 v106, v118, v119
	v_cvt_pk_bf16_f32 v107, v120, v121
	v_cvt_pk_bf16_f32 v108, v114, v115
	v_cvt_pk_bf16_f32 v109, v116, v117
	v_cvt_pk_bf16_f32 v90, v102, v103
	v_cvt_pk_bf16_f32 v91, v104, v105
	v_cvt_pk_bf16_f32 v92, v98, v99
	v_cvt_pk_bf16_f32 v93, v100, v101
	global_store_dwordx4 v[94:95], v[78:81], off offset:256
	v_cvt_pk_bf16_f32 v76, v82, v83
	v_cvt_pk_bf16_f32 v77, v84, v85
	v_lshl_add_u64 v[78:79], v[74:75], 0, v[148:149]
	v_cvt_pk_bf16_f32 v74, v86, v87
	v_cvt_pk_bf16_f32 v75, v88, v89
	v_cvt_pk_bf16_f32 v73, v68, v69
	v_cvt_pk_bf16_f32 v65, v60, v61
	v_cvt_pk_bf16_f32 v42, v54, v55
	v_cvt_pk_bf16_f32 v43, v56, v57
	v_cvt_pk_bf16_f32 v44, v50, v51
	v_cvt_pk_bf16_f32 v45, v52, v53
	v_cvt_pk_bf16_f32 v26, v38, v39
	v_cvt_pk_bf16_f32 v27, v40, v41
	v_cvt_pk_bf16_f32 v28, v34, v35
	v_cvt_pk_bf16_f32 v29, v36, v37
	v_lshl_add_u64 v[14:15], v[150:151], 0, s[20:21]
	v_cvt_pk_bf16_f32 v10, v22, v23
	v_cvt_pk_bf16_f32 v11, v24, v25
	v_cvt_pk_bf16_f32 v12, v18, v19
	v_cvt_pk_bf16_f32 v13, v20, v21
	v_cvt_pk_bf16_f32 v6, v6, v7
	v_cvt_pk_bf16_f32 v7, v8, v9
	v_cvt_pk_bf16_f32 v8, v2, v3
	v_cvt_pk_bf16_f32 v9, v4, v5
	s_and_b64 vcc, exec, s[0:1]
	s_mov_b32 s45, s18
	s_mov_b32 s46, s30
	s_mov_b64 s[22:23], s[82:83]
	s_mov_b64 s[20:21], s[80:81]
	s_mov_b32 s64, 0x800000
	s_movk_i32 s65, 0x1fff
	v_readlane_b32 s49, v254, 41
	v_readlane_b32 s50, v254, 42
	v_readlane_b32 s51, v254, 43
	v_readlane_b32 s54, v254, 46
	v_readlane_b32 s55, v254, 47
	v_readlane_b32 s56, v254, 48
	v_readlane_b32 s57, v254, 49
	v_readlane_b32 s58, v254, 50
	v_readlane_b32 s59, v254, 51
	v_readlane_b32 s60, v254, 52
	v_readlane_b32 s61, v254, 53
	v_readlane_b32 s62, v254, 54
	v_readlane_b32 s63, v254, 55
	global_store_dwordx4 v[150:151], v[126:129], off
	global_store_dwordx4 v[110:111], v[106:109], off
	global_store_dwordx4 v[94:95], v[90:93], off
	global_store_dwordx4 v[78:79], v[74:77], off
	global_store_dwordx4 v[78:79], v[70:73], off offset:256
	global_store_dwordx4 v[58:59], v[62:65], off
	global_store_dwordx4 v[48:49], v[42:45], off
	global_store_dwordx4 v[32:33], v[26:29], off
	global_store_dwordx4 v[16:17], v[10:13], off
	global_store_dwordx4 v[14:15], v[6:9], off offset:256
	s_cbranch_vccz .LBB0_118
	s_waitcnt vmcnt(0)
	v_readlane_b32 s44, v255, 30
	s_mov_b32 s66, s90
	s_cmpk_gt_u32 s25, 0xff
	v_readlane_b32 s45, v255, 31
	v_readlane_b32 s42, v255, 32
	s_cbranch_scc1 .LBB0_131
	s_barrier

.LBB0_240:
	s_add_u32 s22, s80, 0xfff80080
	s_addc_u32 s23, s81, -1
	s_add_i32 s52, 0, 0x10000
	s_cmp_eq_u32 s51, 28
	s_cselect_b32 s23, s21, s23
	s_cselect_b32 s22, s47, s22
	s_cselect_b32 s83, s19, s50
	s_cselect_b32 s82, s48, s49
	v_lshl_add_u64 v[178:179], s[80:81], 0, v[134:135]
	s_add_i32 m0, s27, 0xc000
	ds_read_b128 v[158:161], v140
	ds_read_b128 v[162:165], v140 offset:1024
	ds_read_b128 v[166:169], v140 offset:2048
	ds_read_b128 v[170:173], v140 offset:3072
	ds_read_b128 v[174:177], v140 offset:4096
	ds_read_b128 v[192:195], v140 offset:5120
	ds_read_b128 v[196:199], v140 offset:6144
	ds_read_b128 v[200:203], v140 offset:7168
	global_load_lds_dwordx4 v[178:179], off
	v_lshl_add_u64 v[178:179], s[80:81], 0, v[136:137]
	s_add_i32 m0, s27, 0xe000
	s_nop 0
	global_load_lds_dwordx4 v[178:179], off
	s_waitcnt lgkmcnt(8)
	s_barrier
	s_waitcnt lgkmcnt(0)
	v_mfma_f32_16x16x32_bf16 v[126:129], v[142:145], v[158:161], v[126:129]
	v_mfma_f32_16x16x32_bf16 v[122:125], v[150:153], v[158:161], v[122:125]
	v_mfma_f32_16x16x32_bf16 v[118:121], v[142:145], v[166:169], v[118:121]
	v_mfma_f32_16x16x32_bf16 v[114:117], v[150:153], v[166:169], v[114:117]
	v_mfma_f32_16x16x32_bf16 v[110:113], v[142:145], v[174:177], v[110:113]
	v_mfma_f32_16x16x32_bf16 v[102:105], v[150:153], v[174:177], v[102:105]
	v_mfma_f32_16x16x32_bf16 v[94:97], v[142:145], v[196:199], v[94:97]
	v_mfma_f32_16x16x32_bf16 v[86:89], v[150:153], v[196:199], v[86:89]
	v_mfma_f32_16x16x32_bf16 v[126:129], v[146:149], v[162:165], v[126:129]
	v_mfma_f32_16x16x32_bf16 v[122:125], v[154:157], v[162:165], v[122:125]
	v_mfma_f32_16x16x32_bf16 v[118:121], v[146:149], v[170:173], v[118:121]
	v_mfma_f32_16x16x32_bf16 v[114:117], v[154:157], v[170:173], v[114:117]
	v_mfma_f32_16x16x32_bf16 v[110:113], v[146:149], v[192:195], v[110:113]
	v_mfma_f32_16x16x32_bf16 v[102:105], v[154:157], v[192:195], v[102:105]
	v_mfma_f32_16x16x32_bf16 v[94:97], v[146:149], v[200:203], v[94:97]
	v_mfma_f32_16x16x32_bf16 v[86:89], v[154:157], v[200:203], v[86:89]
	s_barrier
	s_add_i32 s54, 0, 0x14000
	s_add_i32 s52, s52, s26
	v_add_u32_e32 v141, s54, v138
	v_lshl_add_u64 v[178:179], s[82:83], 0, v[132:133]
	s_mov_b32 m0, s52
	ds_read_b128 v[204:207], v141
	ds_read_b128 v[208:211], v141 offset:1024
	ds_read_b128 v[224:227], v141 offset:2048
	ds_read_b128 v[228:231], v141 offset:3072
	global_load_lds_dwordx4 v[178:179], off
	v_lshl_add_u64 v[212:213], s[82:83], 0, v[130:131]
	s_add_i32 m0, s52, 0x2000
	s_nop 0
	global_load_lds_dwordx4 v[212:213], off
	s_mov_b32 m0, s27
	v_lshl_add_u64 v[232:233], s[22:23], 0, v[132:133]
	s_waitcnt lgkmcnt(0)
	s_barrier
	v_mfma_f32_16x16x32_bf16 v[106:109], v[204:207], v[158:161], v[106:109]
	v_mfma_f32_16x16x32_bf16 v[98:101], v[224:227], v[158:161], v[98:101]
	v_mfma_f32_16x16x32_bf16 v[90:93], v[204:207], v[166:169], v[90:93]
	v_mfma_f32_16x16x32_bf16 v[82:85], v[224:227], v[166:169], v[82:85]
	v_mfma_f32_16x16x32_bf16 v[78:81], v[204:207], v[174:177], v[78:81]
	v_mfma_f32_16x16x32_bf16 v[74:77], v[224:227], v[174:177], v[74:77]
	v_mfma_f32_16x16x32_bf16 v[70:73], v[204:207], v[196:199], v[70:73]
	v_mfma_f32_16x16x32_bf16 v[66:69], v[224:227], v[196:199], v[66:69]
	v_mfma_f32_16x16x32_bf16 v[106:109], v[208:211], v[162:165], v[106:109]
	v_mfma_f32_16x16x32_bf16 v[98:101], v[228:231], v[162:165], v[98:101]
	v_mfma_f32_16x16x32_bf16 v[90:93], v[208:211], v[170:173], v[90:93]
	v_mfma_f32_16x16x32_bf16 v[82:85], v[228:231], v[170:173], v[82:85]
	v_mfma_f32_16x16x32_bf16 v[78:81], v[208:211], v[192:195], v[78:81]
	v_mfma_f32_16x16x32_bf16 v[74:77], v[228:231], v[192:195], v[74:77]
	v_mfma_f32_16x16x32_bf16 v[70:73], v[208:211], v[200:203], v[70:73]
	v_mfma_f32_16x16x32_bf16 v[66:69], v[228:231], v[200:203], v[66:69]
	s_barrier
	ds_read_b128 v[158:161], v140 offset:16384
	ds_read_b128 v[162:165], v140 offset:17408
	ds_read_b128 v[166:169], v140 offset:18432
	ds_read_b128 v[170:173], v140 offset:19456
	ds_read_b128 v[174:177], v140 offset:20480
	ds_read_b128 v[192:195], v140 offset:21504
	ds_read_b128 v[196:199], v140 offset:22528
	ds_read_b128 v[200:203], v140 offset:23552
	global_load_lds_dwordx4 v[232:233], off
	v_lshl_add_u64 v[234:235], s[22:23], 0, v[130:131]
	s_mov_b32 m0, s28
	s_nop 0
	global_load_lds_dwordx4 v[234:235], off
	s_waitcnt vmcnt(10)
	s_barrier
	s_waitcnt lgkmcnt(0)
	v_mfma_f32_16x16x32_bf16 v[62:65], v[142:145], v[158:161], v[62:65]
	v_mfma_f32_16x16x32_bf16 v[58:61], v[150:153], v[158:161], v[58:61]
	v_mfma_f32_16x16x32_bf16 v[54:57], v[142:145], v[166:169], v[54:57]
	v_mfma_f32_16x16x32_bf16 v[50:53], v[150:153], v[166:169], v[50:53]
	v_mfma_f32_16x16x32_bf16 v[46:49], v[142:145], v[174:177], v[46:49]
	v_mfma_f32_16x16x32_bf16 v[38:41], v[150:153], v[174:177], v[38:41]
	v_mfma_f32_16x16x32_bf16 v[30:33], v[142:145], v[196:199], v[30:33]
	v_mfma_f32_16x16x32_bf16 v[22:25], v[150:153], v[196:199], v[22:25]
	v_mfma_f32_16x16x32_bf16 v[62:65], v[146:149], v[162:165], v[62:65]
	v_mfma_f32_16x16x32_bf16 v[58:61], v[154:157], v[162:165], v[58:61]
	v_mfma_f32_16x16x32_bf16 v[54:57], v[146:149], v[170:173], v[54:57]
	v_mfma_f32_16x16x32_bf16 v[50:53], v[154:157], v[170:173], v[50:53]
	v_mfma_f32_16x16x32_bf16 v[46:49], v[146:149], v[192:195], v[46:49]
	v_mfma_f32_16x16x32_bf16 v[38:41], v[154:157], v[192:195], v[38:41]
	v_mfma_f32_16x16x32_bf16 v[30:33], v[146:149], v[200:203], v[30:33]
	v_mfma_f32_16x16x32_bf16 v[22:25], v[154:157], v[200:203], v[22:25]
	s_barrier
	s_add_u32 s52, s82, 0x80000
	s_addc_u32 s53, s83, 0
	s_add_i32 s54, s54, s26
	v_lshl_add_u64 v[142:143], s[52:53], 0, v[132:133]
	s_mov_b32 m0, s54
	s_nop 0
	global_load_lds_dwordx4 v[142:143], off
	v_lshl_add_u64 v[142:143], s[52:53], 0, v[130:131]
	s_add_i32 m0, s54, 0x2000
	s_nop 0
	global_load_lds_dwordx4 v[142:143], off
	v_add_u32_e32 v141, 0x18000, v138
	ds_read_b128 v[142:145], v141
	ds_read_b128 v[146:149], v141 offset:1024
	ds_read_b128 v[150:153], v141 offset:2048
	ds_read_b128 v[154:157], v141 offset:3072
	s_add_i32 s52, 0, 0x18000
	s_waitcnt vmcnt(6)
	s_barrier
	v_mfma_f32_16x16x32_bf16 v[42:45], v[204:207], v[158:161], v[42:45]
	v_mfma_f32_16x16x32_bf16 v[34:37], v[224:227], v[158:161], v[34:37]
	v_mfma_f32_16x16x32_bf16 v[26:29], v[204:207], v[166:169], v[26:29]
	v_mfma_f32_16x16x32_bf16 v[18:21], v[224:227], v[166:169], v[18:21]
	v_mfma_f32_16x16x32_bf16 v[14:17], v[204:207], v[174:177], v[14:17]
	v_mfma_f32_16x16x32_bf16 v[10:13], v[224:227], v[174:177], v[10:13]
	v_mfma_f32_16x16x32_bf16 v[6:9], v[204:207], v[196:199], v[6:9]
	v_mfma_f32_16x16x32_bf16 v[2:5], v[224:227], v[196:199], v[2:5]
	v_mfma_f32_16x16x32_bf16 v[42:45], v[208:211], v[162:165], v[42:45]
	v_mfma_f32_16x16x32_bf16 v[34:37], v[228:231], v[162:165], v[34:37]
	v_mfma_f32_16x16x32_bf16 v[26:29], v[208:211], v[170:173], v[26:29]
	v_mfma_f32_16x16x32_bf16 v[18:21], v[228:231], v[170:173], v[18:21]
	v_mfma_f32_16x16x32_bf16 v[14:17], v[208:211], v[192:195], v[14:17]
	v_mfma_f32_16x16x32_bf16 v[10:13], v[228:231], v[192:195], v[10:13]
	v_mfma_f32_16x16x32_bf16 v[6:9], v[208:211], v[200:203], v[6:9]
	v_mfma_f32_16x16x32_bf16 v[2:5], v[228:231], v[200:203], v[2:5]
	s_barrier
	s_add_u32 s22, s22, 0x80000
	s_addc_u32 s23, s23, 0
	s_mov_b32 m0, s29
	v_lshl_add_u64 v[204:205], s[22:23], 0, v[132:133]
	ds_read_b128 v[158:161], v140 offset:32768
	ds_read_b128 v[162:165], v140 offset:33792
	ds_read_b128 v[166:169], v140 offset:34816
	ds_read_b128 v[170:173], v140 offset:35840
	ds_read_b128 v[174:177], v140 offset:36864
	ds_read_b128 v[192:195], v140 offset:37888
	ds_read_b128 v[196:199], v140 offset:38912
	ds_read_b128 v[200:203], v140 offset:39936
	global_load_lds_dwordx4 v[204:205], off
	v_lshl_add_u64 v[204:205], s[22:23], 0, v[130:131]
	s_mov_b32 m0, s36
	s_nop 0
	global_load_lds_dwordx4 v[204:205], off
	s_waitcnt lgkmcnt(8)
	s_barrier
	s_waitcnt lgkmcnt(0)
	v_mfma_f32_16x16x32_bf16 v[126:129], v[142:145], v[158:161], v[126:129]
	v_mfma_f32_16x16x32_bf16 v[122:125], v[150:153], v[158:161], v[122:125]
	v_mfma_f32_16x16x32_bf16 v[118:121], v[142:145], v[166:169], v[118:121]
	v_mfma_f32_16x16x32_bf16 v[114:117], v[150:153], v[166:169], v[114:117]
	v_mfma_f32_16x16x32_bf16 v[110:113], v[142:145], v[174:177], v[110:113]
	v_mfma_f32_16x16x32_bf16 v[102:105], v[150:153], v[174:177], v[102:105]
	v_mfma_f32_16x16x32_bf16 v[94:97], v[142:145], v[196:199], v[94:97]
	v_mfma_f32_16x16x32_bf16 v[86:89], v[150:153], v[196:199], v[86:89]
	v_mfma_f32_16x16x32_bf16 v[126:129], v[146:149], v[162:165], v[126:129]
	v_mfma_f32_16x16x32_bf16 v[122:125], v[154:157], v[162:165], v[122:125]
	v_mfma_f32_16x16x32_bf16 v[118:121], v[146:149], v[170:173], v[118:121]
	v_mfma_f32_16x16x32_bf16 v[114:117], v[154:157], v[170:173], v[114:117]
	v_mfma_f32_16x16x32_bf16 v[110:113], v[146:149], v[192:195], v[110:113]
	v_mfma_f32_16x16x32_bf16 v[102:105], v[154:157], v[192:195], v[102:105]
	v_mfma_f32_16x16x32_bf16 v[94:97], v[146:149], v[200:203], v[94:97]
	v_mfma_f32_16x16x32_bf16 v[86:89], v[154:157], v[200:203], v[86:89]
	s_barrier
	s_add_i32 s53, 0, 0x1c000
	s_add_i32 s22, s52, s26
	v_add_u32_e32 v141, s53, v138
	v_lshl_add_u64 v[178:179], v[178:179], 0, s[78:79]
	s_mov_b32 m0, s22
	ds_read_b128 v[204:207], v141
	ds_read_b128 v[208:211], v141 offset:1024
	ds_read_b128 v[224:227], v141 offset:2048
	ds_read_b128 v[228:231], v141 offset:3072
	global_load_lds_dwordx4 v[178:179], off
	v_lshl_add_u64 v[178:179], v[212:213], 0, s[78:79]
	s_add_i32 m0, s22, 0x2000
	s_nop 0
	global_load_lds_dwordx4 v[178:179], off
	s_mov_b32 m0, s42
	v_lshl_add_u64 v[178:179], v[232:233], 0, s[78:79]
	s_waitcnt lgkmcnt(0)
	s_barrier
	v_mfma_f32_16x16x32_bf16 v[106:109], v[204:207], v[158:161], v[106:109]
	v_mfma_f32_16x16x32_bf16 v[98:101], v[224:227], v[158:161], v[98:101]
	v_mfma_f32_16x16x32_bf16 v[90:93], v[204:207], v[166:169], v[90:93]
	v_mfma_f32_16x16x32_bf16 v[82:85], v[224:227], v[166:169], v[82:85]
	v_mfma_f32_16x16x32_bf16 v[78:81], v[204:207], v[174:177], v[78:81]
	v_mfma_f32_16x16x32_bf16 v[74:77], v[224:227], v[174:177], v[74:77]
	v_mfma_f32_16x16x32_bf16 v[70:73], v[204:207], v[196:199], v[70:73]
	v_mfma_f32_16x16x32_bf16 v[66:69], v[224:227], v[196:199], v[66:69]
	v_mfma_f32_16x16x32_bf16 v[106:109], v[208:211], v[162:165], v[106:109]
	v_mfma_f32_16x16x32_bf16 v[98:101], v[228:231], v[162:165], v[98:101]
	v_mfma_f32_16x16x32_bf16 v[90:93], v[208:211], v[170:173], v[90:93]
	v_mfma_f32_16x16x32_bf16 v[82:85], v[228:231], v[170:173], v[82:85]
	v_mfma_f32_16x16x32_bf16 v[78:81], v[208:211], v[192:195], v[78:81]
	v_mfma_f32_16x16x32_bf16 v[74:77], v[228:231], v[192:195], v[74:77]
	v_mfma_f32_16x16x32_bf16 v[70:73], v[208:211], v[200:203], v[70:73]
	v_mfma_f32_16x16x32_bf16 v[66:69], v[228:231], v[200:203], v[66:69]
	s_barrier
	ds_read_b128 v[158:161], v140 offset:49152
	ds_read_b128 v[162:165], v140 offset:50176
	ds_read_b128 v[166:169], v140 offset:51200
	ds_read_b128 v[170:173], v140 offset:52224
	ds_read_b128 v[174:177], v140 offset:53248
	ds_read_b128 v[192:195], v140 offset:54272
	ds_read_b128 v[196:199], v140 offset:55296
	ds_read_b128 v[200:203], v140 offset:56320
	global_load_lds_dwordx4 v[178:179], off
	v_lshl_add_u64 v[178:179], v[234:235], 0, s[78:79]
	s_mov_b32 m0, s43
	s_nop 0
	global_load_lds_dwordx4 v[178:179], off
	s_waitcnt vmcnt(10)
	s_barrier
	s_waitcnt lgkmcnt(0)
	v_mfma_f32_16x16x32_bf16 v[62:65], v[142:145], v[158:161], v[62:65]
	v_mfma_f32_16x16x32_bf16 v[58:61], v[150:153], v[158:161], v[58:61]
	v_mfma_f32_16x16x32_bf16 v[54:57], v[142:145], v[166:169], v[54:57]
	v_mfma_f32_16x16x32_bf16 v[50:53], v[150:153], v[166:169], v[50:53]
	v_mfma_f32_16x16x32_bf16 v[46:49], v[142:145], v[174:177], v[46:49]
	v_mfma_f32_16x16x32_bf16 v[38:41], v[150:153], v[174:177], v[38:41]
	v_mfma_f32_16x16x32_bf16 v[30:33], v[142:145], v[196:199], v[30:33]
	v_mfma_f32_16x16x32_bf16 v[22:25], v[150:153], v[196:199], v[22:25]
	v_mfma_f32_16x16x32_bf16 v[62:65], v[146:149], v[162:165], v[62:65]
	v_mfma_f32_16x16x32_bf16 v[58:61], v[154:157], v[162:165], v[58:61]
	v_mfma_f32_16x16x32_bf16 v[54:57], v[146:149], v[170:173], v[54:57]
	v_mfma_f32_16x16x32_bf16 v[50:53], v[154:157], v[170:173], v[50:53]
	v_mfma_f32_16x16x32_bf16 v[46:49], v[146:149], v[192:195], v[46:49]
	v_mfma_f32_16x16x32_bf16 v[38:41], v[154:157], v[192:195], v[38:41]
	v_mfma_f32_16x16x32_bf16 v[30:33], v[146:149], v[200:203], v[30:33]
	v_mfma_f32_16x16x32_bf16 v[22:25], v[154:157], v[200:203], v[22:25]
	s_barrier
	s_add_u32 s22, s82, 0x80080
	s_addc_u32 s23, s83, 0
	s_add_i32 s52, s53, s26
	v_lshl_add_u64 v[142:143], s[22:23], 0, v[132:133]
	s_mov_b32 m0, s52
	s_nop 0
	global_load_lds_dwordx4 v[142:143], off
	v_lshl_add_u64 v[142:143], s[22:23], 0, v[130:131]
	s_add_i32 m0, s52, 0x2000
	s_nop 0
	global_load_lds_dwordx4 v[142:143], off
	v_add_u32_e32 v141, 0x10000, v138
	ds_read_b128 v[142:145], v141
	ds_read_b128 v[146:149], v141 offset:1024
	ds_read_b128 v[150:153], v141 offset:2048
	ds_read_b128 v[154:157], v141 offset:3072
	s_add_i32 s51, s51, 2
	s_add_u32 s80, s80, 0x100
	s_addc_u32 s81, s81, 0
	s_add_u32 s49, s49, 0x100
	s_addc_u32 s50, s50, 0
	s_cmp_gt_u32 s51, 29
	s_waitcnt vmcnt(6)
	s_barrier
	v_mfma_f32_16x16x32_bf16 v[42:45], v[204:207], v[158:161], v[42:45]
	v_mfma_f32_16x16x32_bf16 v[34:37], v[224:227], v[158:161], v[34:37]
	v_mfma_f32_16x16x32_bf16 v[26:29], v[204:207], v[166:169], v[26:29]
	v_mfma_f32_16x16x32_bf16 v[18:21], v[224:227], v[166:169], v[18:21]
	v_mfma_f32_16x16x32_bf16 v[14:17], v[204:207], v[174:177], v[14:17]
	v_mfma_f32_16x16x32_bf16 v[10:13], v[224:227], v[174:177], v[10:13]
	v_mfma_f32_16x16x32_bf16 v[6:9], v[204:207], v[196:199], v[6:9]
	v_mfma_f32_16x16x32_bf16 v[2:5], v[224:227], v[196:199], v[2:5]
	v_mfma_f32_16x16x32_bf16 v[42:45], v[208:211], v[162:165], v[42:45]
	v_mfma_f32_16x16x32_bf16 v[34:37], v[228:231], v[162:165], v[34:37]
	v_mfma_f32_16x16x32_bf16 v[26:29], v[208:211], v[170:173], v[26:29]
	v_mfma_f32_16x16x32_bf16 v[18:21], v[228:231], v[170:173], v[18:21]
	v_mfma_f32_16x16x32_bf16 v[14:17], v[208:211], v[192:195], v[14:17]
	v_mfma_f32_16x16x32_bf16 v[10:13], v[228:231], v[192:195], v[10:13]
	v_mfma_f32_16x16x32_bf16 v[6:9], v[208:211], v[200:203], v[6:9]
	v_mfma_f32_16x16x32_bf16 v[2:5], v[228:231], v[200:203], v[2:5]
	s_barrier
	s_cbranch_scc0 .LBB0_240
	s_waitcnt lgkmcnt(0)
	v_readlane_b32 s48, v254, 40
	v_lshl_or_b32 v142, s45, 8, v139
	v_readlane_b32 s52, v254, 44
	v_readlane_b32 s53, v254, 45
	v_lshl_add_u32 v141, s46, 8, v1
	v_ashrrev_i32_e32 v143, 31, v142
	v_mov_b64_e32 v[144:145], s[52:53]
	s_movk_i32 s19, 0x1400
	v_mad_i64_i32 v[146:147], s[22:23], v141, s19, v[144:145]
	v_lshlrev_b64 v[142:143], 2, v[142:143]
	v_lshl_add_u64 v[146:147], v[146:147], 0, v[142:143]
	global_store_dwordx4 v[146:147], v[126:129], off
	global_store_dwordx4 v[146:147], v[122:125], off offset:64
	global_store_dwordx4 v[146:147], v[106:109], off offset:512
	global_store_dwordx4 v[146:147], v[98:101], off offset:576
	s_movk_i32 s94, 0x1400
	s_and_b64 vcc, exec, s[0:1]
	v_or_b32_e32 v98, 16, v141
	v_mad_i64_i32 v[98:99], s[22:23], v98, s19, v[144:145]
	v_lshl_add_u64 v[98:99], v[98:99], 0, v[142:143]
	global_store_dwordx4 v[98:99], v[118:121], off
	global_store_dwordx4 v[98:99], v[114:117], off offset:64
	global_store_dwordx4 v[98:99], v[90:93], off offset:512
	global_store_dwordx4 v[98:99], v[82:85], off offset:576
	s_mov_b32 s45, s18
	s_mov_b32 s46, s20
	v_or_b32_e32 v82, 32, v141
	v_mad_i64_i32 v[82:83], s[22:23], v82, s19, v[144:145]
	v_lshl_add_u64 v[82:83], v[82:83], 0, v[142:143]
	global_store_dwordx4 v[82:83], v[110:113], off
	global_store_dwordx4 v[82:83], v[102:105], off offset:64
	global_store_dwordx4 v[82:83], v[78:81], off offset:512
	global_store_dwordx4 v[82:83], v[74:77], off offset:576
	s_mov_b64 s[80:81], s[30:31]
	v_readlane_b32 s49, v254, 41
	v_or_b32_e32 v74, 48, v141
	v_mad_i64_i32 v[74:75], s[22:23], v74, s19, v[144:145]
	v_lshl_add_u64 v[74:75], v[74:75], 0, v[142:143]
	global_store_dwordx4 v[74:75], v[94:97], off
	global_store_dwordx4 v[74:75], v[86:89], off offset:64
	global_store_dwordx4 v[74:75], v[70:73], off offset:512
	global_store_dwordx4 v[74:75], v[66:69], off offset:576
	v_readlane_b32 s50, v254, 42
	v_readlane_b32 s51, v254, 43
	v_add_u32_e32 v66, 0x80, v141
	v_mad_i64_i32 v[66:67], s[22:23], v66, s19, v[144:145]
	v_lshl_add_u64 v[66:67], v[66:67], 0, v[142:143]
	global_store_dwordx4 v[66:67], v[62:65], off
	global_store_dwordx4 v[66:67], v[58:61], off offset:64
	global_store_dwordx4 v[66:67], v[42:45], off offset:512
	global_store_dwordx4 v[66:67], v[34:37], off offset:576
	v_readlane_b32 s54, v254, 46
	v_readlane_b32 s55, v254, 47
	v_add_u32_e32 v34, 0x90, v141
	v_mad_i64_i32 v[34:35], s[22:23], v34, s19, v[144:145]
	v_lshl_add_u64 v[34:35], v[34:35], 0, v[142:143]
	global_store_dwordx4 v[34:35], v[54:57], off
	global_store_dwordx4 v[34:35], v[50:53], off offset:64
	global_store_dwordx4 v[34:35], v[26:29], off offset:512
	global_store_dwordx4 v[34:35], v[18:21], off offset:576
	v_readlane_b32 s56, v254, 48
	v_readlane_b32 s57, v254, 49
	v_add_u32_e32 v18, 0xa0, v141
	v_mad_i64_i32 v[18:19], s[22:23], v18, s19, v[144:145]
	v_lshl_add_u64 v[18:19], v[18:19], 0, v[142:143]
	global_store_dwordx4 v[18:19], v[46:49], off
	global_store_dwordx4 v[18:19], v[38:41], off offset:64
	global_store_dwordx4 v[18:19], v[14:17], off offset:512
	global_store_dwordx4 v[18:19], v[10:13], off offset:576
	v_readlane_b32 s58, v254, 50
	v_readlane_b32 s59, v254, 51
	v_add_u32_e32 v10, 0xb0, v141
	v_mad_i64_i32 v[10:11], s[22:23], v10, s19, v[144:145]
	v_lshl_add_u64 v[10:11], v[10:11], 0, v[142:143]
	s_mov_b64 s[22:23], s[38:39]
	v_readlane_b32 s60, v254, 52
	v_readlane_b32 s61, v254, 53
	v_readlane_b32 s62, v254, 54
	v_readlane_b32 s63, v254, 55
	global_store_dwordx4 v[10:11], v[30:33], off
	global_store_dwordx4 v[10:11], v[22:25], off offset:64
	global_store_dwordx4 v[10:11], v[6:9], off offset:512
	global_store_dwordx4 v[10:11], v[2:5], off offset:576
	s_cbranch_vccz .LBB0_237
	s_waitcnt vmcnt(0)
	v_readlane_b32 s44, v255, 30
	s_cmpk_gt_u32 s25, 0xff
	v_readlane_b32 s45, v255, 31
	v_readlane_b32 s42, v255, 32
	s_cbranch_scc1 .LBB0_244
	s_barrier

.LBB0_357:
	s_add_u32 s22, s20, 0xfffe0080
	s_addc_u32 s23, s21, -1
	s_add_i32 s52, 0, 0x10000
	s_cmp_eq_u32 s51, 4
	s_cselect_b32 s23, s31, s23
	s_cselect_b32 s22, s47, s22
	s_cselect_b32 s85, s19, s50
	s_cselect_b32 s84, s48, s49
	v_lshl_add_u64 v[178:179], s[20:21], 0, v[138:139]
	s_add_i32 m0, s27, 0xc000
	ds_read_b128 v[162:165], v144
	ds_read_b128 v[166:169], v144 offset:1024
	ds_read_b128 v[170:173], v144 offset:2048
	ds_read_b128 v[174:177], v144 offset:3072
	ds_read_b128 v[192:195], v144 offset:4096
	ds_read_b128 v[196:199], v144 offset:5120
	ds_read_b128 v[200:203], v144 offset:6144
	ds_read_b128 v[204:207], v144 offset:7168
	global_load_lds_dwordx4 v[178:179], off
	v_lshl_add_u64 v[178:179], s[20:21], 0, v[140:141]
	s_add_i32 m0, s27, 0xe000
	s_nop 0
	global_load_lds_dwordx4 v[178:179], off
	s_waitcnt lgkmcnt(8)
	s_barrier
	s_waitcnt lgkmcnt(0)
	v_mfma_f32_16x16x32_bf16 v[126:129], v[146:149], v[162:165], v[126:129]
	v_mfma_f32_16x16x32_bf16 v[122:125], v[154:157], v[162:165], v[122:125]
	v_mfma_f32_16x16x32_bf16 v[118:121], v[146:149], v[170:173], v[118:121]
	v_mfma_f32_16x16x32_bf16 v[114:117], v[154:157], v[170:173], v[114:117]
	v_mfma_f32_16x16x32_bf16 v[102:105], v[146:149], v[192:195], v[102:105]
	v_mfma_f32_16x16x32_bf16 v[98:101], v[154:157], v[192:195], v[98:101]
	v_mfma_f32_16x16x32_bf16 v[86:89], v[146:149], v[200:203], v[86:89]
	v_mfma_f32_16x16x32_bf16 v[82:85], v[154:157], v[200:203], v[82:85]
	v_mfma_f32_16x16x32_bf16 v[126:129], v[150:153], v[166:169], v[126:129]
	v_mfma_f32_16x16x32_bf16 v[122:125], v[158:161], v[166:169], v[122:125]
	v_mfma_f32_16x16x32_bf16 v[118:121], v[150:153], v[174:177], v[118:121]
	v_mfma_f32_16x16x32_bf16 v[114:117], v[158:161], v[174:177], v[114:117]
	v_mfma_f32_16x16x32_bf16 v[102:105], v[150:153], v[196:199], v[102:105]
	v_mfma_f32_16x16x32_bf16 v[98:101], v[158:161], v[196:199], v[98:101]
	v_mfma_f32_16x16x32_bf16 v[86:89], v[150:153], v[204:207], v[86:89]
	v_mfma_f32_16x16x32_bf16 v[82:85], v[158:161], v[204:207], v[82:85]
	s_barrier
	s_add_i32 s54, 0, 0x14000
	s_add_i32 s52, s52, s26
	v_add_u32_e32 v145, s54, v142
	v_lshl_add_u64 v[178:179], s[84:85], 0, v[134:135]
	s_mov_b32 m0, s52
	ds_read_b128 v[208:211], v145
	ds_read_b128 v[224:227], v145 offset:1024
	ds_read_b128 v[228:231], v145 offset:2048
	ds_read_b128 v[232:235], v145 offset:3072
	global_load_lds_dwordx4 v[178:179], off
	v_lshl_add_u64 v[212:213], s[84:85], 0, v[130:131]
	s_add_i32 m0, s52, 0x2000
	s_nop 0
	global_load_lds_dwordx4 v[212:213], off
	s_mov_b32 m0, s27
	v_lshl_add_u64 v[236:237], s[22:23], 0, v[136:137]
	s_waitcnt lgkmcnt(0)
	s_barrier
	v_mfma_f32_16x16x32_bf16 v[110:113], v[208:211], v[162:165], v[110:113]
	v_mfma_f32_16x16x32_bf16 v[106:109], v[228:231], v[162:165], v[106:109]
	v_mfma_f32_16x16x32_bf16 v[94:97], v[208:211], v[170:173], v[94:97]
	v_mfma_f32_16x16x32_bf16 v[90:93], v[228:231], v[170:173], v[90:93]
	v_mfma_f32_16x16x32_bf16 v[78:81], v[208:211], v[192:195], v[78:81]
	v_mfma_f32_16x16x32_bf16 v[74:77], v[228:231], v[192:195], v[74:77]
	v_mfma_f32_16x16x32_bf16 v[70:73], v[208:211], v[200:203], v[70:73]
	v_mfma_f32_16x16x32_bf16 v[66:69], v[228:231], v[200:203], v[66:69]
	v_mfma_f32_16x16x32_bf16 v[110:113], v[224:227], v[166:169], v[110:113]
	v_mfma_f32_16x16x32_bf16 v[106:109], v[232:235], v[166:169], v[106:109]
	v_mfma_f32_16x16x32_bf16 v[94:97], v[224:227], v[174:177], v[94:97]
	v_mfma_f32_16x16x32_bf16 v[90:93], v[232:235], v[174:177], v[90:93]
	v_mfma_f32_16x16x32_bf16 v[78:81], v[224:227], v[196:199], v[78:81]
	v_mfma_f32_16x16x32_bf16 v[74:77], v[232:235], v[196:199], v[74:77]
	v_mfma_f32_16x16x32_bf16 v[70:73], v[224:227], v[204:207], v[70:73]
	v_mfma_f32_16x16x32_bf16 v[66:69], v[232:235], v[204:207], v[66:69]
	s_barrier
	ds_read_b128 v[162:165], v144 offset:16384
	ds_read_b128 v[166:169], v144 offset:17408
	ds_read_b128 v[170:173], v144 offset:18432
	ds_read_b128 v[174:177], v144 offset:19456
	ds_read_b128 v[192:195], v144 offset:20480
	ds_read_b128 v[196:199], v144 offset:21504
	ds_read_b128 v[200:203], v144 offset:22528
	ds_read_b128 v[204:207], v144 offset:23552
	global_load_lds_dwordx4 v[236:237], off
	v_lshl_add_u64 v[238:239], s[22:23], 0, v[132:133]
	s_mov_b32 m0, s28
	s_nop 0
	global_load_lds_dwordx4 v[238:239], off
	s_waitcnt vmcnt(10)
	s_barrier
	s_waitcnt lgkmcnt(0)
	v_mfma_f32_16x16x32_bf16 v[62:65], v[146:149], v[162:165], v[62:65]
	v_mfma_f32_16x16x32_bf16 v[58:61], v[154:157], v[162:165], v[58:61]
	v_mfma_f32_16x16x32_bf16 v[54:57], v[146:149], v[170:173], v[54:57]
	v_mfma_f32_16x16x32_bf16 v[50:53], v[154:157], v[170:173], v[50:53]
	v_mfma_f32_16x16x32_bf16 v[38:41], v[146:149], v[192:195], v[38:41]
	v_mfma_f32_16x16x32_bf16 v[34:37], v[154:157], v[192:195], v[34:37]
	v_mfma_f32_16x16x32_bf16 v[22:25], v[146:149], v[200:203], v[22:25]
	v_mfma_f32_16x16x32_bf16 v[18:21], v[154:157], v[200:203], v[18:21]
	v_mfma_f32_16x16x32_bf16 v[62:65], v[150:153], v[166:169], v[62:65]
	v_mfma_f32_16x16x32_bf16 v[58:61], v[158:161], v[166:169], v[58:61]
	v_mfma_f32_16x16x32_bf16 v[54:57], v[150:153], v[174:177], v[54:57]
	v_mfma_f32_16x16x32_bf16 v[50:53], v[158:161], v[174:177], v[50:53]
	v_mfma_f32_16x16x32_bf16 v[38:41], v[150:153], v[196:199], v[38:41]
	v_mfma_f32_16x16x32_bf16 v[34:37], v[158:161], v[196:199], v[34:37]
	v_mfma_f32_16x16x32_bf16 v[22:25], v[150:153], v[204:207], v[22:25]
	v_mfma_f32_16x16x32_bf16 v[18:21], v[158:161], v[204:207], v[18:21]
	s_barrier
	s_add_u32 s52, s84, 0x20000
	s_addc_u32 s53, s85, 0
	s_add_i32 s54, s54, s26
	v_lshl_add_u64 v[146:147], s[52:53], 0, v[134:135]
	s_mov_b32 m0, s54
	s_nop 0
	global_load_lds_dwordx4 v[146:147], off
	v_lshl_add_u64 v[146:147], s[52:53], 0, v[130:131]
	s_add_i32 m0, s54, 0x2000
	s_nop 0
	global_load_lds_dwordx4 v[146:147], off
	v_add_u32_e32 v145, 0x18000, v142
	ds_read_b128 v[146:149], v145
	ds_read_b128 v[150:153], v145 offset:1024
	ds_read_b128 v[154:157], v145 offset:2048
	ds_read_b128 v[158:161], v145 offset:3072
	s_add_i32 s52, 0, 0x18000
	s_waitcnt vmcnt(6)
	s_barrier
	v_mfma_f32_16x16x32_bf16 v[46:49], v[208:211], v[162:165], v[46:49]
	v_mfma_f32_16x16x32_bf16 v[42:45], v[228:231], v[162:165], v[42:45]
	v_mfma_f32_16x16x32_bf16 v[30:33], v[208:211], v[170:173], v[30:33]
	v_mfma_f32_16x16x32_bf16 v[26:29], v[228:231], v[170:173], v[26:29]
	v_mfma_f32_16x16x32_bf16 v[14:17], v[208:211], v[192:195], v[14:17]
	v_mfma_f32_16x16x32_bf16 v[10:13], v[228:231], v[192:195], v[10:13]
	v_mfma_f32_16x16x32_bf16 v[6:9], v[208:211], v[200:203], v[6:9]
	v_mfma_f32_16x16x32_bf16 v[2:5], v[228:231], v[200:203], v[2:5]
	v_mfma_f32_16x16x32_bf16 v[46:49], v[224:227], v[166:169], v[46:49]
	v_mfma_f32_16x16x32_bf16 v[42:45], v[232:235], v[166:169], v[42:45]
	v_mfma_f32_16x16x32_bf16 v[30:33], v[224:227], v[174:177], v[30:33]
	v_mfma_f32_16x16x32_bf16 v[26:29], v[232:235], v[174:177], v[26:29]
	v_mfma_f32_16x16x32_bf16 v[14:17], v[224:227], v[196:199], v[14:17]
	v_mfma_f32_16x16x32_bf16 v[10:13], v[232:235], v[196:199], v[10:13]
	v_mfma_f32_16x16x32_bf16 v[6:9], v[224:227], v[204:207], v[6:9]
	v_mfma_f32_16x16x32_bf16 v[2:5], v[232:235], v[204:207], v[2:5]
	s_barrier
	s_add_u32 s22, s22, 0x20000
	s_addc_u32 s23, s23, 0
	s_mov_b32 m0, s29
	v_lshl_add_u64 v[208:209], s[22:23], 0, v[136:137]
	ds_read_b128 v[162:165], v144 offset:32768
	ds_read_b128 v[166:169], v144 offset:33792
	ds_read_b128 v[170:173], v144 offset:34816
	ds_read_b128 v[174:177], v144 offset:35840
	ds_read_b128 v[192:195], v144 offset:36864
	ds_read_b128 v[196:199], v144 offset:37888
	ds_read_b128 v[200:203], v144 offset:38912
	ds_read_b128 v[204:207], v144 offset:39936
	global_load_lds_dwordx4 v[208:209], off
	v_lshl_add_u64 v[208:209], s[22:23], 0, v[132:133]
	s_mov_b32 m0, s36
	s_nop 0
	global_load_lds_dwordx4 v[208:209], off
	s_waitcnt lgkmcnt(8)
	s_barrier
	s_waitcnt lgkmcnt(0)
	v_mfma_f32_16x16x32_bf16 v[126:129], v[146:149], v[162:165], v[126:129]
	v_mfma_f32_16x16x32_bf16 v[122:125], v[154:157], v[162:165], v[122:125]
	v_mfma_f32_16x16x32_bf16 v[118:121], v[146:149], v[170:173], v[118:121]
	v_mfma_f32_16x16x32_bf16 v[114:117], v[154:157], v[170:173], v[114:117]
	v_mfma_f32_16x16x32_bf16 v[102:105], v[146:149], v[192:195], v[102:105]
	v_mfma_f32_16x16x32_bf16 v[98:101], v[154:157], v[192:195], v[98:101]
	v_mfma_f32_16x16x32_bf16 v[86:89], v[146:149], v[200:203], v[86:89]
	v_mfma_f32_16x16x32_bf16 v[82:85], v[154:157], v[200:203], v[82:85]
	v_mfma_f32_16x16x32_bf16 v[126:129], v[150:153], v[166:169], v[126:129]
	v_mfma_f32_16x16x32_bf16 v[122:125], v[158:161], v[166:169], v[122:125]
	v_mfma_f32_16x16x32_bf16 v[118:121], v[150:153], v[174:177], v[118:121]
	v_mfma_f32_16x16x32_bf16 v[114:117], v[158:161], v[174:177], v[114:117]
	v_mfma_f32_16x16x32_bf16 v[102:105], v[150:153], v[196:199], v[102:105]
	v_mfma_f32_16x16x32_bf16 v[98:101], v[158:161], v[196:199], v[98:101]
	v_mfma_f32_16x16x32_bf16 v[86:89], v[150:153], v[204:207], v[86:89]
	v_mfma_f32_16x16x32_bf16 v[82:85], v[158:161], v[204:207], v[82:85]
	s_barrier
	s_add_i32 s53, 0, 0x1c000
	s_add_i32 s22, s52, s26
	v_add_u32_e32 v145, s53, v142
	v_lshl_add_u64 v[178:179], v[178:179], 0, s[78:79]
	s_mov_b32 m0, s22
	ds_read_b128 v[208:211], v145
	ds_read_b128 v[224:227], v145 offset:1024
	ds_read_b128 v[228:231], v145 offset:2048
	ds_read_b128 v[232:235], v145 offset:3072
	global_load_lds_dwordx4 v[178:179], off
	v_lshl_add_u64 v[178:179], v[212:213], 0, s[78:79]
	s_add_i32 m0, s22, 0x2000
	s_nop 0
	global_load_lds_dwordx4 v[178:179], off
	s_mov_b32 m0, s42
	v_lshl_add_u64 v[178:179], v[236:237], 0, s[78:79]
	s_waitcnt lgkmcnt(0)
	s_barrier
	v_mfma_f32_16x16x32_bf16 v[110:113], v[208:211], v[162:165], v[110:113]
	v_mfma_f32_16x16x32_bf16 v[106:109], v[228:231], v[162:165], v[106:109]
	v_mfma_f32_16x16x32_bf16 v[94:97], v[208:211], v[170:173], v[94:97]
	v_mfma_f32_16x16x32_bf16 v[90:93], v[228:231], v[170:173], v[90:93]
	v_mfma_f32_16x16x32_bf16 v[78:81], v[208:211], v[192:195], v[78:81]
	v_mfma_f32_16x16x32_bf16 v[74:77], v[228:231], v[192:195], v[74:77]
	v_mfma_f32_16x16x32_bf16 v[70:73], v[208:211], v[200:203], v[70:73]
	v_mfma_f32_16x16x32_bf16 v[66:69], v[228:231], v[200:203], v[66:69]
	v_mfma_f32_16x16x32_bf16 v[110:113], v[224:227], v[166:169], v[110:113]
	v_mfma_f32_16x16x32_bf16 v[106:109], v[232:235], v[166:169], v[106:109]
	v_mfma_f32_16x16x32_bf16 v[94:97], v[224:227], v[174:177], v[94:97]
	v_mfma_f32_16x16x32_bf16 v[90:93], v[232:235], v[174:177], v[90:93]
	v_mfma_f32_16x16x32_bf16 v[78:81], v[224:227], v[196:199], v[78:81]
	v_mfma_f32_16x16x32_bf16 v[74:77], v[232:235], v[196:199], v[74:77]
	v_mfma_f32_16x16x32_bf16 v[70:73], v[224:227], v[204:207], v[70:73]
	v_mfma_f32_16x16x32_bf16 v[66:69], v[232:235], v[204:207], v[66:69]
	s_barrier
	ds_read_b128 v[162:165], v144 offset:49152
	ds_read_b128 v[166:169], v144 offset:50176
	ds_read_b128 v[170:173], v144 offset:51200
	ds_read_b128 v[174:177], v144 offset:52224
	ds_read_b128 v[192:195], v144 offset:53248
	ds_read_b128 v[196:199], v144 offset:54272
	ds_read_b128 v[200:203], v144 offset:55296
	ds_read_b128 v[204:207], v144 offset:56320
	global_load_lds_dwordx4 v[178:179], off
	v_lshl_add_u64 v[178:179], v[238:239], 0, s[78:79]
	s_mov_b32 m0, s43
	s_nop 0
	global_load_lds_dwordx4 v[178:179], off
	s_waitcnt vmcnt(10)
	s_barrier
	s_waitcnt lgkmcnt(0)
	v_mfma_f32_16x16x32_bf16 v[62:65], v[146:149], v[162:165], v[62:65]
	v_mfma_f32_16x16x32_bf16 v[58:61], v[154:157], v[162:165], v[58:61]
	v_mfma_f32_16x16x32_bf16 v[54:57], v[146:149], v[170:173], v[54:57]
	v_mfma_f32_16x16x32_bf16 v[50:53], v[154:157], v[170:173], v[50:53]
	v_mfma_f32_16x16x32_bf16 v[38:41], v[146:149], v[192:195], v[38:41]
	v_mfma_f32_16x16x32_bf16 v[34:37], v[154:157], v[192:195], v[34:37]
	v_mfma_f32_16x16x32_bf16 v[22:25], v[146:149], v[200:203], v[22:25]
	v_mfma_f32_16x16x32_bf16 v[18:21], v[154:157], v[200:203], v[18:21]
	v_mfma_f32_16x16x32_bf16 v[62:65], v[150:153], v[166:169], v[62:65]
	v_mfma_f32_16x16x32_bf16 v[58:61], v[158:161], v[166:169], v[58:61]
	v_mfma_f32_16x16x32_bf16 v[54:57], v[150:153], v[174:177], v[54:57]
	v_mfma_f32_16x16x32_bf16 v[50:53], v[158:161], v[174:177], v[50:53]
	v_mfma_f32_16x16x32_bf16 v[38:41], v[150:153], v[196:199], v[38:41]
	v_mfma_f32_16x16x32_bf16 v[34:37], v[158:161], v[196:199], v[34:37]
	v_mfma_f32_16x16x32_bf16 v[22:25], v[150:153], v[204:207], v[22:25]
	v_mfma_f32_16x16x32_bf16 v[18:21], v[158:161], v[204:207], v[18:21]
	s_barrier
	s_add_u32 s22, s84, 0x20080
	s_addc_u32 s23, s85, 0
	s_add_i32 s52, s53, s26
	v_lshl_add_u64 v[146:147], s[22:23], 0, v[134:135]
	s_mov_b32 m0, s52
	s_nop 0
	global_load_lds_dwordx4 v[146:147], off
	v_lshl_add_u64 v[146:147], s[22:23], 0, v[130:131]
	s_add_i32 m0, s52, 0x2000
	s_nop 0
	global_load_lds_dwordx4 v[146:147], off
	v_add_u32_e32 v145, 0x10000, v142
	ds_read_b128 v[146:149], v145
	ds_read_b128 v[150:153], v145 offset:1024
	ds_read_b128 v[154:157], v145 offset:2048
	ds_read_b128 v[158:161], v145 offset:3072
	s_add_i32 s51, s51, 2
	s_add_u32 s20, s20, 0x100
	s_addc_u32 s21, s21, 0
	s_add_u32 s49, s49, 0x100
	s_addc_u32 s50, s50, 0
	s_cmp_gt_u32 s51, 5
	s_waitcnt vmcnt(6)
	s_barrier
	v_mfma_f32_16x16x32_bf16 v[46:49], v[208:211], v[162:165], v[46:49]
	v_mfma_f32_16x16x32_bf16 v[42:45], v[228:231], v[162:165], v[42:45]
	v_mfma_f32_16x16x32_bf16 v[30:33], v[208:211], v[170:173], v[30:33]
	v_mfma_f32_16x16x32_bf16 v[26:29], v[228:231], v[170:173], v[26:29]
	v_mfma_f32_16x16x32_bf16 v[14:17], v[208:211], v[192:195], v[14:17]
	v_mfma_f32_16x16x32_bf16 v[10:13], v[228:231], v[192:195], v[10:13]
	v_mfma_f32_16x16x32_bf16 v[6:9], v[208:211], v[200:203], v[6:9]
	v_mfma_f32_16x16x32_bf16 v[2:5], v[228:231], v[200:203], v[2:5]
	v_mfma_f32_16x16x32_bf16 v[46:49], v[224:227], v[166:169], v[46:49]
	v_mfma_f32_16x16x32_bf16 v[42:45], v[232:235], v[166:169], v[42:45]
	v_mfma_f32_16x16x32_bf16 v[30:33], v[224:227], v[174:177], v[30:33]
	v_mfma_f32_16x16x32_bf16 v[26:29], v[232:235], v[174:177], v[26:29]
	v_mfma_f32_16x16x32_bf16 v[14:17], v[224:227], v[196:199], v[14:17]
	v_mfma_f32_16x16x32_bf16 v[10:13], v[232:235], v[196:199], v[10:13]
	v_mfma_f32_16x16x32_bf16 v[6:9], v[224:227], v[204:207], v[6:9]
	v_mfma_f32_16x16x32_bf16 v[2:5], v[232:235], v[204:207], v[2:5]
	s_barrier
	s_cbranch_scc0 .LBB0_357
	s_waitcnt lgkmcnt(0)
	v_lshl_add_u32 v146, s46, 8, v1
	v_lshl_or_b32 v148, s45, 8, v143
	v_ashrrev_i32_e32 v147, 31, v146
	v_readlane_b32 s48, v254, 40
	v_ashrrev_i32_e32 v149, 31, v148
	v_lshlrev_b64 v[150:151], 12, v[146:147]
	v_readlane_b32 s60, v254, 52
	v_readlane_b32 s61, v254, 53
	v_lshlrev_b64 v[148:149], 1, v[148:149]
	s_mov_b32 s19, 0x80000
	v_lshl_add_u64 v[150:151], s[60:61], 0, v[150:151]
	v_lshl_add_u64 v[150:151], v[150:151], 0, v[148:149]
	s_mov_b64 s[20:21], 0x80000
	v_cvt_pk_bf16_f32 v62, v62, v63
	v_cvt_pk_bf16_f32 v63, v64, v65
	v_cvt_pk_bf16_f32 v64, v58, v59
	v_add_co_u32_e32 v58, vcc, s19, v150
	v_cvt_pk_bf16_f32 v70, v70, v71
	v_cvt_pk_bf16_f32 v71, v72, v73
	v_cvt_pk_bf16_f32 v72, v66, v67
	v_lshl_add_u64 v[66:67], v[150:151], 0, s[20:21]
	v_addc_co_u32_e32 v59, vcc, 0, v151, vcc
	v_cvt_pk_bf16_f32 v46, v46, v47
	v_cvt_pk_bf16_f32 v47, v48, v49
	v_cvt_pk_bf16_f32 v48, v42, v43
	v_cvt_pk_bf16_f32 v49, v44, v45
	s_mov_b32 s19, 0x90000
	v_cvt_pk_bf16_f32 v110, v110, v111
	v_cvt_pk_bf16_f32 v111, v112, v113
	v_cvt_pk_bf16_f32 v112, v106, v107
	v_or_b32_e32 v106, 16, v146
	global_store_dwordx4 v[66:67], v[46:49], off offset:256
	s_mov_b64 s[20:21], 0x90000
	v_ashrrev_i32_e32 v107, 31, v106
	v_add_co_u32_e32 v48, vcc, s19, v150
	v_cvt_pk_bf16_f32 v94, v94, v95
	v_cvt_pk_bf16_f32 v95, v96, v97
	v_cvt_pk_bf16_f32 v96, v90, v91
	v_or_b32_e32 v90, 32, v146
	v_lshl_add_u64 v[46:47], v[150:151], 0, s[20:21]
	v_addc_co_u32_e32 v49, vcc, 0, v151, vcc
	v_cvt_pk_bf16_f32 v30, v30, v31
	v_cvt_pk_bf16_f32 v31, v32, v33
	v_cvt_pk_bf16_f32 v32, v26, v27
	v_cvt_pk_bf16_f32 v33, v28, v29
	s_mov_b32 s19, 0xa0000
	v_lshlrev_b64 v[106:107], 12, v[106:107]
	v_ashrrev_i32_e32 v91, 31, v90
	v_cvt_pk_bf16_f32 v78, v78, v79
	v_cvt_pk_bf16_f32 v79, v80, v81
	v_cvt_pk_bf16_f32 v80, v74, v75
	v_or_b32_e32 v74, 48, v146
	global_store_dwordx4 v[46:47], v[30:33], off offset:256
	s_mov_b64 s[20:21], 0xa0000
	v_cvt_pk_bf16_f32 v113, v108, v109
	v_add_co_u32_e32 v32, vcc, s19, v150
	v_lshl_add_u64 v[106:107], s[60:61], 0, v[106:107]
	v_lshlrev_b64 v[90:91], 12, v[90:91]
	v_ashrrev_i32_e32 v75, 31, v74
	v_lshl_add_u64 v[30:31], v[150:151], 0, s[20:21]
	v_addc_co_u32_e32 v33, vcc, 0, v151, vcc
	v_cvt_pk_bf16_f32 v14, v14, v15
	v_cvt_pk_bf16_f32 v15, v16, v17
	v_cvt_pk_bf16_f32 v16, v10, v11
	v_cvt_pk_bf16_f32 v17, v12, v13
	s_mov_b32 s19, 0xb0000
	global_store_dwordx4 v[150:151], v[110:113], off offset:256
	v_cvt_pk_bf16_f32 v97, v92, v93
	v_lshl_add_u64 v[90:91], s[60:61], 0, v[90:91]
	v_lshl_add_u64 v[110:111], v[106:107], 0, v[148:149]
	v_lshlrev_b64 v[74:75], 12, v[74:75]
	global_store_dwordx4 v[30:31], v[14:17], off offset:256
	global_store_dwordx4 v[110:111], v[94:97], off offset:256
	v_cvt_pk_bf16_f32 v81, v76, v77
	v_add_co_u32_e32 v16, vcc, s19, v150
	v_lshl_add_u64 v[94:95], v[90:91], 0, v[148:149]
	v_lshl_add_u64 v[74:75], s[60:61], 0, v[74:75]
	s_mov_b64 s[20:21], 0xb0000
	v_addc_co_u32_e32 v17, vcc, 0, v151, vcc
	v_cvt_pk_bf16_f32 v126, v126, v127
	v_cvt_pk_bf16_f32 v127, v128, v129
	v_cvt_pk_bf16_f32 v128, v122, v123
	v_cvt_pk_bf16_f32 v129, v124, v125
	v_cvt_pk_bf16_f32 v106, v118, v119
	v_cvt_pk_bf16_f32 v107, v120, v121
	v_cvt_pk_bf16_f32 v108, v114, v115
	v_cvt_pk_bf16_f32 v109, v116, v117
	v_cvt_pk_bf16_f32 v90, v102, v103
	v_cvt_pk_bf16_f32 v91, v104, v105
	v_cvt_pk_bf16_f32 v92, v98, v99
	v_cvt_pk_bf16_f32 v93, v100, v101
	global_store_dwordx4 v[94:95], v[78:81], off offset:256
	v_cvt_pk_bf16_f32 v76, v82, v83
	v_cvt_pk_bf16_f32 v77, v84, v85
	v_lshl_add_u64 v[78:79], v[74:75], 0, v[148:149]
	v_cvt_pk_bf16_f32 v74, v86, v87
	v_cvt_pk_bf16_f32 v75, v88, v89
	v_cvt_pk_bf16_f32 v73, v68, v69
	v_cvt_pk_bf16_f32 v65, v60, v61
	v_cvt_pk_bf16_f32 v42, v54, v55
	v_cvt_pk_bf16_f32 v43, v56, v57
	v_cvt_pk_bf16_f32 v44, v50, v51
	v_cvt_pk_bf16_f32 v45, v52, v53
	v_cvt_pk_bf16_f32 v26, v38, v39
	v_cvt_pk_bf16_f32 v27, v40, v41
	v_cvt_pk_bf16_f32 v28, v34, v35
	v_cvt_pk_bf16_f32 v29, v36, v37
	v_lshl_add_u64 v[14:15], v[150:151], 0, s[20:21]
	v_cvt_pk_bf16_f32 v10, v22, v23
	v_cvt_pk_bf16_f32 v11, v24, v25
	v_cvt_pk_bf16_f32 v12, v18, v19
	v_cvt_pk_bf16_f32 v13, v20, v21
	v_cvt_pk_bf16_f32 v6, v6, v7
	v_cvt_pk_bf16_f32 v7, v8, v9
	v_cvt_pk_bf16_f32 v8, v2, v3
	v_cvt_pk_bf16_f32 v9, v4, v5
	s_and_b64 vcc, exec, s[38:39]
	s_mov_b32 s45, s18
	s_mov_b32 s46, s30
	s_mov_b64 s[22:23], s[82:83]
	s_mov_b64 s[20:21], s[80:81]
	s_mov_b32 s64, 0x800000
	s_movk_i32 s65, 0x1fff
	v_readlane_b32 s49, v254, 41
	v_readlane_b32 s50, v254, 42
	v_readlane_b32 s51, v254, 43
	v_readlane_b32 s52, v254, 44
	v_readlane_b32 s53, v254, 45
	v_readlane_b32 s54, v254, 46
	v_readlane_b32 s55, v254, 47
	v_readlane_b32 s56, v254, 48
	v_readlane_b32 s57, v254, 49
	v_readlane_b32 s58, v254, 50
	v_readlane_b32 s59, v254, 51
	v_readlane_b32 s62, v254, 54
	v_readlane_b32 s63, v254, 55
	global_store_dwordx4 v[150:151], v[126:129], off
	global_store_dwordx4 v[110:111], v[106:109], off
	global_store_dwordx4 v[94:95], v[90:93], off
	global_store_dwordx4 v[78:79], v[74:77], off
	global_store_dwordx4 v[78:79], v[70:73], off offset:256
	global_store_dwordx4 v[58:59], v[62:65], off
	global_store_dwordx4 v[48:49], v[42:45], off
	global_store_dwordx4 v[32:33], v[26:29], off
	global_store_dwordx4 v[16:17], v[10:13], off
	global_store_dwordx4 v[14:15], v[6:9], off offset:256
	s_cbranch_vccz .LBB0_350
	s_waitcnt vmcnt(0)
	v_readlane_b32 s44, v255, 30
	s_mov_b32 s66, s90
	s_cmpk_gt_u32 s25, 0xff
	v_readlane_b32 s45, v255, 31
	v_readlane_b32 s42, v255, 32
	s_cbranch_scc1 .LBB0_361
	s_barrier

.LBB0_373:
	s_add_u32 s22, s20, 0xfffe0080
	s_addc_u32 s23, s21, -1
	s_add_i32 s52, 0, 0x10000
	s_cmp_eq_u32 s51, 4
	s_cselect_b32 s23, s31, s23
	s_cselect_b32 s22, s47, s22
	s_cselect_b32 s83, s19, s50
	s_cselect_b32 s82, s48, s49
	v_lshl_add_u64 v[178:179], s[20:21], 0, v[138:139]
	s_add_i32 m0, s27, 0xc000
	ds_read_b128 v[162:165], v144
	ds_read_b128 v[166:169], v144 offset:1024
	ds_read_b128 v[170:173], v144 offset:2048
	ds_read_b128 v[174:177], v144 offset:3072
	ds_read_b128 v[192:195], v144 offset:4096
	ds_read_b128 v[196:199], v144 offset:5120
	ds_read_b128 v[200:203], v144 offset:6144
	ds_read_b128 v[204:207], v144 offset:7168
	global_load_lds_dwordx4 v[178:179], off
	v_lshl_add_u64 v[178:179], s[20:21], 0, v[140:141]
	s_add_i32 m0, s27, 0xe000
	s_nop 0
	global_load_lds_dwordx4 v[178:179], off
	s_waitcnt lgkmcnt(8)
	s_barrier
	s_waitcnt lgkmcnt(0)
	v_mfma_f32_16x16x32_bf16 v[126:129], v[146:149], v[162:165], v[126:129]
	v_mfma_f32_16x16x32_bf16 v[122:125], v[154:157], v[162:165], v[122:125]
	v_mfma_f32_16x16x32_bf16 v[118:121], v[146:149], v[170:173], v[118:121]
	v_mfma_f32_16x16x32_bf16 v[114:117], v[154:157], v[170:173], v[114:117]
	v_mfma_f32_16x16x32_bf16 v[102:105], v[146:149], v[192:195], v[102:105]
	v_mfma_f32_16x16x32_bf16 v[98:101], v[154:157], v[192:195], v[98:101]
	v_mfma_f32_16x16x32_bf16 v[86:89], v[146:149], v[200:203], v[86:89]
	v_mfma_f32_16x16x32_bf16 v[82:85], v[154:157], v[200:203], v[82:85]
	v_mfma_f32_16x16x32_bf16 v[126:129], v[150:153], v[166:169], v[126:129]
	v_mfma_f32_16x16x32_bf16 v[122:125], v[158:161], v[166:169], v[122:125]
	v_mfma_f32_16x16x32_bf16 v[118:121], v[150:153], v[174:177], v[118:121]
	v_mfma_f32_16x16x32_bf16 v[114:117], v[158:161], v[174:177], v[114:117]
	v_mfma_f32_16x16x32_bf16 v[102:105], v[150:153], v[196:199], v[102:105]
	v_mfma_f32_16x16x32_bf16 v[98:101], v[158:161], v[196:199], v[98:101]
	v_mfma_f32_16x16x32_bf16 v[86:89], v[150:153], v[204:207], v[86:89]
	v_mfma_f32_16x16x32_bf16 v[82:85], v[158:161], v[204:207], v[82:85]
	s_barrier
	s_add_i32 s54, 0, 0x14000
	s_add_i32 s52, s52, s26
	v_add_u32_e32 v145, s54, v142
	v_lshl_add_u64 v[178:179], s[82:83], 0, v[134:135]
	s_mov_b32 m0, s52
	ds_read_b128 v[208:211], v145
	ds_read_b128 v[224:227], v145 offset:1024
	ds_read_b128 v[228:231], v145 offset:2048
	ds_read_b128 v[232:235], v145 offset:3072
	global_load_lds_dwordx4 v[178:179], off
	v_lshl_add_u64 v[212:213], s[82:83], 0, v[130:131]
	s_add_i32 m0, s52, 0x2000
	s_nop 0
	global_load_lds_dwordx4 v[212:213], off
	s_mov_b32 m0, s27
	v_lshl_add_u64 v[236:237], s[22:23], 0, v[136:137]
	s_waitcnt lgkmcnt(0)
	s_barrier
	v_mfma_f32_16x16x32_bf16 v[110:113], v[208:211], v[162:165], v[110:113]
	v_mfma_f32_16x16x32_bf16 v[106:109], v[228:231], v[162:165], v[106:109]
	v_mfma_f32_16x16x32_bf16 v[94:97], v[208:211], v[170:173], v[94:97]
	v_mfma_f32_16x16x32_bf16 v[90:93], v[228:231], v[170:173], v[90:93]
	v_mfma_f32_16x16x32_bf16 v[78:81], v[208:211], v[192:195], v[78:81]
	v_mfma_f32_16x16x32_bf16 v[74:77], v[228:231], v[192:195], v[74:77]
	v_mfma_f32_16x16x32_bf16 v[70:73], v[208:211], v[200:203], v[70:73]
	v_mfma_f32_16x16x32_bf16 v[66:69], v[228:231], v[200:203], v[66:69]
	v_mfma_f32_16x16x32_bf16 v[110:113], v[224:227], v[166:169], v[110:113]
	v_mfma_f32_16x16x32_bf16 v[106:109], v[232:235], v[166:169], v[106:109]
	v_mfma_f32_16x16x32_bf16 v[94:97], v[224:227], v[174:177], v[94:97]
	v_mfma_f32_16x16x32_bf16 v[90:93], v[232:235], v[174:177], v[90:93]
	v_mfma_f32_16x16x32_bf16 v[78:81], v[224:227], v[196:199], v[78:81]
	v_mfma_f32_16x16x32_bf16 v[74:77], v[232:235], v[196:199], v[74:77]
	v_mfma_f32_16x16x32_bf16 v[70:73], v[224:227], v[204:207], v[70:73]
	v_mfma_f32_16x16x32_bf16 v[66:69], v[232:235], v[204:207], v[66:69]
	s_barrier
	ds_read_b128 v[162:165], v144 offset:16384
	ds_read_b128 v[166:169], v144 offset:17408
	ds_read_b128 v[170:173], v144 offset:18432
	ds_read_b128 v[174:177], v144 offset:19456
	ds_read_b128 v[192:195], v144 offset:20480
	ds_read_b128 v[196:199], v144 offset:21504
	ds_read_b128 v[200:203], v144 offset:22528
	ds_read_b128 v[204:207], v144 offset:23552
	global_load_lds_dwordx4 v[236:237], off
	v_lshl_add_u64 v[238:239], s[22:23], 0, v[132:133]
	s_mov_b32 m0, s28
	s_nop 0
	global_load_lds_dwordx4 v[238:239], off
	s_waitcnt vmcnt(10)
	s_barrier
	s_waitcnt lgkmcnt(0)
	v_mfma_f32_16x16x32_bf16 v[62:65], v[146:149], v[162:165], v[62:65]
	v_mfma_f32_16x16x32_bf16 v[58:61], v[154:157], v[162:165], v[58:61]
	v_mfma_f32_16x16x32_bf16 v[54:57], v[146:149], v[170:173], v[54:57]
	v_mfma_f32_16x16x32_bf16 v[50:53], v[154:157], v[170:173], v[50:53]
	v_mfma_f32_16x16x32_bf16 v[38:41], v[146:149], v[192:195], v[38:41]
	v_mfma_f32_16x16x32_bf16 v[34:37], v[154:157], v[192:195], v[34:37]
	v_mfma_f32_16x16x32_bf16 v[22:25], v[146:149], v[200:203], v[22:25]
	v_mfma_f32_16x16x32_bf16 v[18:21], v[154:157], v[200:203], v[18:21]
	v_mfma_f32_16x16x32_bf16 v[62:65], v[150:153], v[166:169], v[62:65]
	v_mfma_f32_16x16x32_bf16 v[58:61], v[158:161], v[166:169], v[58:61]
	v_mfma_f32_16x16x32_bf16 v[54:57], v[150:153], v[174:177], v[54:57]
	v_mfma_f32_16x16x32_bf16 v[50:53], v[158:161], v[174:177], v[50:53]
	v_mfma_f32_16x16x32_bf16 v[38:41], v[150:153], v[196:199], v[38:41]
	v_mfma_f32_16x16x32_bf16 v[34:37], v[158:161], v[196:199], v[34:37]
	v_mfma_f32_16x16x32_bf16 v[22:25], v[150:153], v[204:207], v[22:25]
	v_mfma_f32_16x16x32_bf16 v[18:21], v[158:161], v[204:207], v[18:21]
	s_barrier
	s_add_u32 s52, s82, 0x20000
	s_addc_u32 s53, s83, 0
	s_add_i32 s54, s54, s26
	v_lshl_add_u64 v[146:147], s[52:53], 0, v[134:135]
	s_mov_b32 m0, s54
	s_nop 0
	global_load_lds_dwordx4 v[146:147], off
	v_lshl_add_u64 v[146:147], s[52:53], 0, v[130:131]
	s_add_i32 m0, s54, 0x2000
	s_nop 0
	global_load_lds_dwordx4 v[146:147], off
	v_add_u32_e32 v145, 0x18000, v142
	ds_read_b128 v[146:149], v145
	ds_read_b128 v[150:153], v145 offset:1024
	ds_read_b128 v[154:157], v145 offset:2048
	ds_read_b128 v[158:161], v145 offset:3072
	s_add_i32 s52, 0, 0x18000
	s_waitcnt vmcnt(6)
	s_barrier
	v_mfma_f32_16x16x32_bf16 v[46:49], v[208:211], v[162:165], v[46:49]
	v_mfma_f32_16x16x32_bf16 v[42:45], v[228:231], v[162:165], v[42:45]
	v_mfma_f32_16x16x32_bf16 v[30:33], v[208:211], v[170:173], v[30:33]
	v_mfma_f32_16x16x32_bf16 v[26:29], v[228:231], v[170:173], v[26:29]
	v_mfma_f32_16x16x32_bf16 v[14:17], v[208:211], v[192:195], v[14:17]
	v_mfma_f32_16x16x32_bf16 v[10:13], v[228:231], v[192:195], v[10:13]
	v_mfma_f32_16x16x32_bf16 v[6:9], v[208:211], v[200:203], v[6:9]
	v_mfma_f32_16x16x32_bf16 v[2:5], v[228:231], v[200:203], v[2:5]
	v_mfma_f32_16x16x32_bf16 v[46:49], v[224:227], v[166:169], v[46:49]
	v_mfma_f32_16x16x32_bf16 v[42:45], v[232:235], v[166:169], v[42:45]
	v_mfma_f32_16x16x32_bf16 v[30:33], v[224:227], v[174:177], v[30:33]
	v_mfma_f32_16x16x32_bf16 v[26:29], v[232:235], v[174:177], v[26:29]
	v_mfma_f32_16x16x32_bf16 v[14:17], v[224:227], v[196:199], v[14:17]
	v_mfma_f32_16x16x32_bf16 v[10:13], v[232:235], v[196:199], v[10:13]
	v_mfma_f32_16x16x32_bf16 v[6:9], v[224:227], v[204:207], v[6:9]
	v_mfma_f32_16x16x32_bf16 v[2:5], v[232:235], v[204:207], v[2:5]
	s_barrier
	s_add_u32 s22, s22, 0x20000
	s_addc_u32 s23, s23, 0
	s_mov_b32 m0, s29
	v_lshl_add_u64 v[208:209], s[22:23], 0, v[136:137]
	ds_read_b128 v[162:165], v144 offset:32768
	ds_read_b128 v[166:169], v144 offset:33792
	ds_read_b128 v[170:173], v144 offset:34816
	ds_read_b128 v[174:177], v144 offset:35840
	ds_read_b128 v[192:195], v144 offset:36864
	ds_read_b128 v[196:199], v144 offset:37888
	ds_read_b128 v[200:203], v144 offset:38912
	ds_read_b128 v[204:207], v144 offset:39936
	global_load_lds_dwordx4 v[208:209], off
	v_lshl_add_u64 v[208:209], s[22:23], 0, v[132:133]
	s_mov_b32 m0, s36
	s_nop 0
	global_load_lds_dwordx4 v[208:209], off
	s_waitcnt lgkmcnt(8)
	s_barrier
	s_waitcnt lgkmcnt(0)
	v_mfma_f32_16x16x32_bf16 v[126:129], v[146:149], v[162:165], v[126:129]
	v_mfma_f32_16x16x32_bf16 v[122:125], v[154:157], v[162:165], v[122:125]
	v_mfma_f32_16x16x32_bf16 v[118:121], v[146:149], v[170:173], v[118:121]
	v_mfma_f32_16x16x32_bf16 v[114:117], v[154:157], v[170:173], v[114:117]
	v_mfma_f32_16x16x32_bf16 v[102:105], v[146:149], v[192:195], v[102:105]
	v_mfma_f32_16x16x32_bf16 v[98:101], v[154:157], v[192:195], v[98:101]
	v_mfma_f32_16x16x32_bf16 v[86:89], v[146:149], v[200:203], v[86:89]
	v_mfma_f32_16x16x32_bf16 v[82:85], v[154:157], v[200:203], v[82:85]
	v_mfma_f32_16x16x32_bf16 v[126:129], v[150:153], v[166:169], v[126:129]
	v_mfma_f32_16x16x32_bf16 v[122:125], v[158:161], v[166:169], v[122:125]
	v_mfma_f32_16x16x32_bf16 v[118:121], v[150:153], v[174:177], v[118:121]
	v_mfma_f32_16x16x32_bf16 v[114:117], v[158:161], v[174:177], v[114:117]
	v_mfma_f32_16x16x32_bf16 v[102:105], v[150:153], v[196:199], v[102:105]
	v_mfma_f32_16x16x32_bf16 v[98:101], v[158:161], v[196:199], v[98:101]
	v_mfma_f32_16x16x32_bf16 v[86:89], v[150:153], v[204:207], v[86:89]
	v_mfma_f32_16x16x32_bf16 v[82:85], v[158:161], v[204:207], v[82:85]
	s_barrier
	s_add_i32 s53, 0, 0x1c000
	s_add_i32 s22, s52, s26
	v_add_u32_e32 v145, s53, v142
	v_lshl_add_u64 v[178:179], v[178:179], 0, s[78:79]
	s_mov_b32 m0, s22
	ds_read_b128 v[208:211], v145
	ds_read_b128 v[224:227], v145 offset:1024
	ds_read_b128 v[228:231], v145 offset:2048
	ds_read_b128 v[232:235], v145 offset:3072
	global_load_lds_dwordx4 v[178:179], off
	v_lshl_add_u64 v[178:179], v[212:213], 0, s[78:79]
	s_add_i32 m0, s22, 0x2000
	s_nop 0
	global_load_lds_dwordx4 v[178:179], off
	s_mov_b32 m0, s42
	v_lshl_add_u64 v[178:179], v[236:237], 0, s[78:79]
	s_waitcnt lgkmcnt(0)
	s_barrier
	v_mfma_f32_16x16x32_bf16 v[110:113], v[208:211], v[162:165], v[110:113]
	v_mfma_f32_16x16x32_bf16 v[106:109], v[228:231], v[162:165], v[106:109]
	v_mfma_f32_16x16x32_bf16 v[94:97], v[208:211], v[170:173], v[94:97]
	v_mfma_f32_16x16x32_bf16 v[90:93], v[228:231], v[170:173], v[90:93]
	v_mfma_f32_16x16x32_bf16 v[78:81], v[208:211], v[192:195], v[78:81]
	v_mfma_f32_16x16x32_bf16 v[74:77], v[228:231], v[192:195], v[74:77]
	v_mfma_f32_16x16x32_bf16 v[70:73], v[208:211], v[200:203], v[70:73]
	v_mfma_f32_16x16x32_bf16 v[66:69], v[228:231], v[200:203], v[66:69]
	v_mfma_f32_16x16x32_bf16 v[110:113], v[224:227], v[166:169], v[110:113]
	v_mfma_f32_16x16x32_bf16 v[106:109], v[232:235], v[166:169], v[106:109]
	v_mfma_f32_16x16x32_bf16 v[94:97], v[224:227], v[174:177], v[94:97]
	v_mfma_f32_16x16x32_bf16 v[90:93], v[232:235], v[174:177], v[90:93]
	v_mfma_f32_16x16x32_bf16 v[78:81], v[224:227], v[196:199], v[78:81]
	v_mfma_f32_16x16x32_bf16 v[74:77], v[232:235], v[196:199], v[74:77]
	v_mfma_f32_16x16x32_bf16 v[70:73], v[224:227], v[204:207], v[70:73]
	v_mfma_f32_16x16x32_bf16 v[66:69], v[232:235], v[204:207], v[66:69]
	s_barrier
	ds_read_b128 v[162:165], v144 offset:49152
	ds_read_b128 v[166:169], v144 offset:50176
	ds_read_b128 v[170:173], v144 offset:51200
	ds_read_b128 v[174:177], v144 offset:52224
	ds_read_b128 v[192:195], v144 offset:53248
	ds_read_b128 v[196:199], v144 offset:54272
	ds_read_b128 v[200:203], v144 offset:55296
	ds_read_b128 v[204:207], v144 offset:56320
	global_load_lds_dwordx4 v[178:179], off
	v_lshl_add_u64 v[178:179], v[238:239], 0, s[78:79]
	s_mov_b32 m0, s43
	s_nop 0
	global_load_lds_dwordx4 v[178:179], off
	s_waitcnt vmcnt(10)
	s_barrier
	s_waitcnt lgkmcnt(0)
	v_mfma_f32_16x16x32_bf16 v[62:65], v[146:149], v[162:165], v[62:65]
	v_mfma_f32_16x16x32_bf16 v[58:61], v[154:157], v[162:165], v[58:61]
	v_mfma_f32_16x16x32_bf16 v[54:57], v[146:149], v[170:173], v[54:57]
	v_mfma_f32_16x16x32_bf16 v[50:53], v[154:157], v[170:173], v[50:53]
	v_mfma_f32_16x16x32_bf16 v[38:41], v[146:149], v[192:195], v[38:41]
	v_mfma_f32_16x16x32_bf16 v[34:37], v[154:157], v[192:195], v[34:37]
	v_mfma_f32_16x16x32_bf16 v[22:25], v[146:149], v[200:203], v[22:25]
	v_mfma_f32_16x16x32_bf16 v[18:21], v[154:157], v[200:203], v[18:21]
	v_mfma_f32_16x16x32_bf16 v[62:65], v[150:153], v[166:169], v[62:65]
	v_mfma_f32_16x16x32_bf16 v[58:61], v[158:161], v[166:169], v[58:61]
	v_mfma_f32_16x16x32_bf16 v[54:57], v[150:153], v[174:177], v[54:57]
	v_mfma_f32_16x16x32_bf16 v[50:53], v[158:161], v[174:177], v[50:53]
	v_mfma_f32_16x16x32_bf16 v[38:41], v[150:153], v[196:199], v[38:41]
	v_mfma_f32_16x16x32_bf16 v[34:37], v[158:161], v[196:199], v[34:37]
	v_mfma_f32_16x16x32_bf16 v[22:25], v[150:153], v[204:207], v[22:25]
	v_mfma_f32_16x16x32_bf16 v[18:21], v[158:161], v[204:207], v[18:21]
	s_barrier
	s_add_u32 s22, s82, 0x20080
	s_addc_u32 s23, s83, 0
	s_add_i32 s52, s53, s26
	v_lshl_add_u64 v[146:147], s[22:23], 0, v[134:135]
	s_mov_b32 m0, s52
	s_nop 0
	global_load_lds_dwordx4 v[146:147], off
	v_lshl_add_u64 v[146:147], s[22:23], 0, v[130:131]
	s_add_i32 m0, s52, 0x2000
	s_nop 0
	global_load_lds_dwordx4 v[146:147], off
	v_add_u32_e32 v145, 0x10000, v142
	ds_read_b128 v[146:149], v145
	ds_read_b128 v[150:153], v145 offset:1024
	ds_read_b128 v[154:157], v145 offset:2048
	ds_read_b128 v[158:161], v145 offset:3072
	s_add_i32 s51, s51, 2
	s_add_u32 s20, s20, 0x100
	s_addc_u32 s21, s21, 0
	s_add_u32 s49, s49, 0x100
	s_addc_u32 s50, s50, 0
	s_cmp_gt_u32 s51, 5
	s_waitcnt vmcnt(6)
	s_barrier
	v_mfma_f32_16x16x32_bf16 v[46:49], v[208:211], v[162:165], v[46:49]
	v_mfma_f32_16x16x32_bf16 v[42:45], v[228:231], v[162:165], v[42:45]
	v_mfma_f32_16x16x32_bf16 v[30:33], v[208:211], v[170:173], v[30:33]
	v_mfma_f32_16x16x32_bf16 v[26:29], v[228:231], v[170:173], v[26:29]
	v_mfma_f32_16x16x32_bf16 v[14:17], v[208:211], v[192:195], v[14:17]
	v_mfma_f32_16x16x32_bf16 v[10:13], v[228:231], v[192:195], v[10:13]
	v_mfma_f32_16x16x32_bf16 v[6:9], v[208:211], v[200:203], v[6:9]
	v_mfma_f32_16x16x32_bf16 v[2:5], v[228:231], v[200:203], v[2:5]
	v_mfma_f32_16x16x32_bf16 v[46:49], v[224:227], v[166:169], v[46:49]
	v_mfma_f32_16x16x32_bf16 v[42:45], v[232:235], v[166:169], v[42:45]
	v_mfma_f32_16x16x32_bf16 v[30:33], v[224:227], v[174:177], v[30:33]
	v_mfma_f32_16x16x32_bf16 v[26:29], v[232:235], v[174:177], v[26:29]
	v_mfma_f32_16x16x32_bf16 v[14:17], v[224:227], v[196:199], v[14:17]
	v_mfma_f32_16x16x32_bf16 v[10:13], v[232:235], v[196:199], v[10:13]
	v_mfma_f32_16x16x32_bf16 v[6:9], v[224:227], v[204:207], v[6:9]
	v_mfma_f32_16x16x32_bf16 v[2:5], v[232:235], v[204:207], v[2:5]
	s_barrier
	s_cbranch_scc0 .LBB0_373
	s_waitcnt lgkmcnt(0)
	v_lshl_add_u32 v146, s46, 8, v1
	v_lshl_or_b32 v148, s45, 8, v143
	v_ashrrev_i32_e32 v147, 31, v146
	v_readlane_b32 s48, v254, 40
	v_ashrrev_i32_e32 v149, 31, v148
	v_lshlrev_b64 v[150:151], 14, v[146:147]
	v_readlane_b32 s62, v254, 54
	v_readlane_b32 s63, v254, 55
	v_lshlrev_b64 v[148:149], 1, v[148:149]
	s_mov_b32 s19, 0x200000
	v_lshl_add_u64 v[150:151], s[62:63], 0, v[150:151]
	v_lshl_add_u64 v[150:151], v[150:151], 0, v[148:149]
	s_mov_b64 s[20:21], 0x200000
	v_cvt_pk_bf16_f32 v62, v62, v63
	v_cvt_pk_bf16_f32 v63, v64, v65
	v_cvt_pk_bf16_f32 v64, v58, v59
	v_add_co_u32_e32 v58, vcc, s19, v150
	v_cvt_pk_bf16_f32 v70, v70, v71
	v_cvt_pk_bf16_f32 v71, v72, v73
	v_cvt_pk_bf16_f32 v72, v66, v67
	v_lshl_add_u64 v[66:67], v[150:151], 0, s[20:21]
	v_addc_co_u32_e32 v59, vcc, 0, v151, vcc
	v_cvt_pk_bf16_f32 v46, v46, v47
	v_cvt_pk_bf16_f32 v47, v48, v49
	v_cvt_pk_bf16_f32 v48, v42, v43
	v_cvt_pk_bf16_f32 v49, v44, v45
	s_mov_b32 s19, 0x240000
	v_cvt_pk_bf16_f32 v110, v110, v111
	v_cvt_pk_bf16_f32 v111, v112, v113
	v_cvt_pk_bf16_f32 v112, v106, v107
	v_or_b32_e32 v106, 16, v146
	global_store_dwordx4 v[66:67], v[46:49], off offset:256
	s_mov_b64 s[20:21], 0x240000
	v_ashrrev_i32_e32 v107, 31, v106
	v_add_co_u32_e32 v48, vcc, s19, v150
	v_cvt_pk_bf16_f32 v94, v94, v95
	v_cvt_pk_bf16_f32 v95, v96, v97
	v_cvt_pk_bf16_f32 v96, v90, v91
	v_or_b32_e32 v90, 32, v146
	v_lshl_add_u64 v[46:47], v[150:151], 0, s[20:21]
	v_addc_co_u32_e32 v49, vcc, 0, v151, vcc
	v_cvt_pk_bf16_f32 v30, v30, v31
	v_cvt_pk_bf16_f32 v31, v32, v33
	v_cvt_pk_bf16_f32 v32, v26, v27
	v_cvt_pk_bf16_f32 v33, v28, v29
	s_mov_b32 s19, 0x280000
	v_lshlrev_b64 v[106:107], 14, v[106:107]
	v_ashrrev_i32_e32 v91, 31, v90
	v_cvt_pk_bf16_f32 v78, v78, v79
	v_cvt_pk_bf16_f32 v79, v80, v81
	v_cvt_pk_bf16_f32 v80, v74, v75
	v_or_b32_e32 v74, 48, v146
	global_store_dwordx4 v[46:47], v[30:33], off offset:256
	s_mov_b64 s[20:21], 0x280000
	v_cvt_pk_bf16_f32 v113, v108, v109
	v_add_co_u32_e32 v32, vcc, s19, v150
	v_lshl_add_u64 v[106:107], s[62:63], 0, v[106:107]
	v_lshlrev_b64 v[90:91], 14, v[90:91]
	v_ashrrev_i32_e32 v75, 31, v74
	v_lshl_add_u64 v[30:31], v[150:151], 0, s[20:21]
	v_addc_co_u32_e32 v33, vcc, 0, v151, vcc
	v_cvt_pk_bf16_f32 v14, v14, v15
	v_cvt_pk_bf16_f32 v15, v16, v17
	v_cvt_pk_bf16_f32 v16, v10, v11
	v_cvt_pk_bf16_f32 v17, v12, v13
	s_mov_b32 s19, 0x2c0000
	global_store_dwordx4 v[150:151], v[110:113], off offset:256
	v_cvt_pk_bf16_f32 v97, v92, v93
	v_lshl_add_u64 v[90:91], s[62:63], 0, v[90:91]
	v_lshl_add_u64 v[110:111], v[106:107], 0, v[148:149]
	v_lshlrev_b64 v[74:75], 14, v[74:75]
	global_store_dwordx4 v[30:31], v[14:17], off offset:256
	global_store_dwordx4 v[110:111], v[94:97], off offset:256
	v_cvt_pk_bf16_f32 v81, v76, v77
	v_add_co_u32_e32 v16, vcc, s19, v150
	v_lshl_add_u64 v[94:95], v[90:91], 0, v[148:149]
	v_lshl_add_u64 v[74:75], s[62:63], 0, v[74:75]
	s_mov_b64 s[20:21], 0x2c0000
	v_addc_co_u32_e32 v17, vcc, 0, v151, vcc
	v_cvt_pk_bf16_f32 v126, v126, v127
	v_cvt_pk_bf16_f32 v127, v128, v129
	v_cvt_pk_bf16_f32 v128, v122, v123
	v_cvt_pk_bf16_f32 v129, v124, v125
	v_cvt_pk_bf16_f32 v106, v118, v119
	v_cvt_pk_bf16_f32 v107, v120, v121
	v_cvt_pk_bf16_f32 v108, v114, v115
	v_cvt_pk_bf16_f32 v109, v116, v117
	v_cvt_pk_bf16_f32 v90, v102, v103
	v_cvt_pk_bf16_f32 v91, v104, v105
	v_cvt_pk_bf16_f32 v92, v98, v99
	v_cvt_pk_bf16_f32 v93, v100, v101
	global_store_dwordx4 v[94:95], v[78:81], off offset:256
	v_cvt_pk_bf16_f32 v76, v82, v83
	v_cvt_pk_bf16_f32 v77, v84, v85
	v_lshl_add_u64 v[78:79], v[74:75], 0, v[148:149]
	v_cvt_pk_bf16_f32 v74, v86, v87
	v_cvt_pk_bf16_f32 v75, v88, v89
	v_cvt_pk_bf16_f32 v73, v68, v69
	v_cvt_pk_bf16_f32 v65, v60, v61
	v_cvt_pk_bf16_f32 v42, v54, v55
	v_cvt_pk_bf16_f32 v43, v56, v57
	v_cvt_pk_bf16_f32 v44, v50, v51
	v_cvt_pk_bf16_f32 v45, v52, v53
	v_cvt_pk_bf16_f32 v26, v38, v39
	v_cvt_pk_bf16_f32 v27, v40, v41
	v_cvt_pk_bf16_f32 v28, v34, v35
	v_cvt_pk_bf16_f32 v29, v36, v37
	v_lshl_add_u64 v[14:15], v[150:151], 0, s[20:21]
	v_cvt_pk_bf16_f32 v10, v22, v23
	v_cvt_pk_bf16_f32 v11, v24, v25
	v_cvt_pk_bf16_f32 v12, v18, v19
	v_cvt_pk_bf16_f32 v13, v20, v21
	v_cvt_pk_bf16_f32 v6, v6, v7
	v_cvt_pk_bf16_f32 v7, v8, v9
	v_cvt_pk_bf16_f32 v8, v2, v3
	v_cvt_pk_bf16_f32 v9, v4, v5
	s_and_b64 vcc, exec, s[0:1]
	s_mov_b32 s45, s18
	s_mov_b32 s46, s30
	s_mov_b64 s[22:23], s[80:81]
	s_mov_b64 s[20:21], s[38:39]
	s_mov_b32 s64, 0x800000
	s_movk_i32 s65, 0x1fff
	v_readlane_b32 s49, v254, 41
	v_readlane_b32 s50, v254, 42
	v_readlane_b32 s51, v254, 43
	v_readlane_b32 s52, v254, 44
	v_readlane_b32 s53, v254, 45
	v_readlane_b32 s54, v254, 46
	v_readlane_b32 s55, v254, 47
	v_readlane_b32 s56, v254, 48
	v_readlane_b32 s57, v254, 49
	v_readlane_b32 s58, v254, 50
	v_readlane_b32 s59, v254, 51
	v_readlane_b32 s60, v254, 52
	v_readlane_b32 s61, v254, 53
	global_store_dwordx4 v[150:151], v[126:129], off
	global_store_dwordx4 v[110:111], v[106:109], off
	global_store_dwordx4 v[94:95], v[90:93], off
	global_store_dwordx4 v[78:79], v[74:77], off
	global_store_dwordx4 v[78:79], v[70:73], off offset:256
	global_store_dwordx4 v[58:59], v[62:65], off
	global_store_dwordx4 v[48:49], v[42:45], off
	global_store_dwordx4 v[32:33], v[26:29], off
	global_store_dwordx4 v[16:17], v[10:13], off
	global_store_dwordx4 v[14:15], v[6:9], off offset:256
	s_cbranch_vccz .LBB0_366
	s_waitcnt vmcnt(0)
	v_readlane_b32 s44, v255, 30
	s_mov_b32 s66, s90
	s_cmpk_gt_u32 s25, 0xff
	v_readlane_b32 s45, v255, 31
	v_readlane_b32 s42, v255, 32
	s_cbranch_scc1 .LBB0_377
	s_barrier

.LBB0_386:
	s_add_u32 s20, s18, 0xfffe0080
	s_addc_u32 s21, s19, -1
	s_add_i32 s50, 0, 0x10000
	s_cmp_eq_u32 s49, 4
	s_cselect_b32 s23, s44, s21
	s_cselect_b32 s22, s45, s20
	s_cselect_b32 s21, s39, s48
	s_cselect_b32 s20, s46, s47
	v_lshl_add_u64 v[178:179], s[18:19], 0, v[146:147]
	s_add_i32 m0, s90, 0xc000
	ds_read_b128 v[162:165], v156
	ds_read_b128 v[166:169], v156 offset:1024
	ds_read_b128 v[170:173], v156 offset:2048
	ds_read_b128 v[174:177], v156 offset:3072
	ds_read_b128 v[192:195], v156 offset:4096
	ds_read_b128 v[196:199], v156 offset:5120
	ds_read_b128 v[200:203], v156 offset:6144
	ds_read_b128 v[204:207], v156 offset:7168
	global_load_lds_dwordx4 v[178:179], off
	v_lshl_add_u64 v[178:179], s[18:19], 0, v[148:149]
	s_add_i32 m0, s90, 0xe000
	s_nop 0
	global_load_lds_dwordx4 v[178:179], off
	s_waitcnt lgkmcnt(8)
	s_barrier
	s_waitcnt lgkmcnt(0)
	v_mfma_f32_16x16x32_bf16 v[126:129], v[130:133], v[162:165], v[126:129]
	v_mfma_f32_16x16x32_bf16 v[122:125], v[150:153], v[162:165], v[122:125]
	v_mfma_f32_16x16x32_bf16 v[118:121], v[130:133], v[170:173], v[118:121]
	v_mfma_f32_16x16x32_bf16 v[110:113], v[150:153], v[170:173], v[110:113]
	v_mfma_f32_16x16x32_bf16 v[102:105], v[130:133], v[192:195], v[102:105]
	v_mfma_f32_16x16x32_bf16 v[94:97], v[150:153], v[192:195], v[94:97]
	v_mfma_f32_16x16x32_bf16 v[86:89], v[130:133], v[200:203], v[86:89]
	v_mfma_f32_16x16x32_bf16 v[78:81], v[150:153], v[200:203], v[78:81]
	v_mfma_f32_16x16x32_bf16 v[126:129], v[134:137], v[166:169], v[126:129]
	v_mfma_f32_16x16x32_bf16 v[122:125], v[158:161], v[166:169], v[122:125]
	v_mfma_f32_16x16x32_bf16 v[118:121], v[134:137], v[174:177], v[118:121]
	v_mfma_f32_16x16x32_bf16 v[110:113], v[158:161], v[174:177], v[110:113]
	v_mfma_f32_16x16x32_bf16 v[102:105], v[134:137], v[196:199], v[102:105]
	v_mfma_f32_16x16x32_bf16 v[94:97], v[158:161], v[196:199], v[94:97]
	v_mfma_f32_16x16x32_bf16 v[86:89], v[134:137], v[204:207], v[86:89]
	v_mfma_f32_16x16x32_bf16 v[78:81], v[158:161], v[204:207], v[78:81]
	s_barrier
	s_add_i32 s52, 0, 0x14000
	s_add_i32 s50, s50, s36
	v_add_u32_e32 v157, s52, v154
	v_lshl_add_u64 v[178:179], s[20:21], 0, v[142:143]
	s_mov_b32 m0, s50
	ds_read_b128 v[208:211], v157
	ds_read_b128 v[224:227], v157 offset:1024
	ds_read_b128 v[228:231], v157 offset:2048
	ds_read_b128 v[232:235], v157 offset:3072
	global_load_lds_dwordx4 v[178:179], off
	v_lshl_add_u64 v[212:213], s[20:21], 0, v[138:139]
	s_add_i32 m0, s50, 0x2000
	s_nop 0
	global_load_lds_dwordx4 v[212:213], off
	s_mov_b32 m0, s90
	v_lshl_add_u64 v[236:237], s[22:23], 0, v[144:145]
	s_waitcnt lgkmcnt(0)
	s_barrier
	v_mfma_f32_16x16x32_bf16 v[114:117], v[208:211], v[162:165], v[114:117]
	v_mfma_f32_16x16x32_bf16 v[106:109], v[228:231], v[162:165], v[106:109]
	v_mfma_f32_16x16x32_bf16 v[98:101], v[208:211], v[170:173], v[98:101]
	v_mfma_f32_16x16x32_bf16 v[90:93], v[228:231], v[170:173], v[90:93]
	v_mfma_f32_16x16x32_bf16 v[82:85], v[208:211], v[192:195], v[82:85]
	v_mfma_f32_16x16x32_bf16 v[74:77], v[228:231], v[192:195], v[74:77]
	v_mfma_f32_16x16x32_bf16 v[70:73], v[208:211], v[200:203], v[70:73]
	v_mfma_f32_16x16x32_bf16 v[66:69], v[228:231], v[200:203], v[66:69]
	v_mfma_f32_16x16x32_bf16 v[114:117], v[224:227], v[166:169], v[114:117]
	v_mfma_f32_16x16x32_bf16 v[106:109], v[232:235], v[166:169], v[106:109]
	v_mfma_f32_16x16x32_bf16 v[98:101], v[224:227], v[174:177], v[98:101]
	v_mfma_f32_16x16x32_bf16 v[90:93], v[232:235], v[174:177], v[90:93]
	v_mfma_f32_16x16x32_bf16 v[82:85], v[224:227], v[196:199], v[82:85]
	v_mfma_f32_16x16x32_bf16 v[74:77], v[232:235], v[196:199], v[74:77]
	v_mfma_f32_16x16x32_bf16 v[70:73], v[224:227], v[204:207], v[70:73]
	v_mfma_f32_16x16x32_bf16 v[66:69], v[232:235], v[204:207], v[66:69]
	s_barrier
	ds_read_b128 v[162:165], v156 offset:16384
	ds_read_b128 v[166:169], v156 offset:17408
	ds_read_b128 v[170:173], v156 offset:18432
	ds_read_b128 v[174:177], v156 offset:19456
	ds_read_b128 v[192:195], v156 offset:20480
	ds_read_b128 v[196:199], v156 offset:21504
	ds_read_b128 v[200:203], v156 offset:22528
	ds_read_b128 v[204:207], v156 offset:23552
	global_load_lds_dwordx4 v[236:237], off
	v_lshl_add_u64 v[238:239], s[22:23], 0, v[140:141]
	s_mov_b32 m0, s91
	s_nop 0
	global_load_lds_dwordx4 v[238:239], off
	s_waitcnt vmcnt(10)
	s_barrier
	s_waitcnt lgkmcnt(0)
	v_mfma_f32_16x16x32_bf16 v[62:65], v[130:133], v[162:165], v[62:65]
	v_mfma_f32_16x16x32_bf16 v[58:61], v[150:153], v[162:165], v[58:61]
	v_mfma_f32_16x16x32_bf16 v[54:57], v[130:133], v[170:173], v[54:57]
	v_mfma_f32_16x16x32_bf16 v[46:49], v[150:153], v[170:173], v[46:49]
	v_mfma_f32_16x16x32_bf16 v[38:41], v[130:133], v[192:195], v[38:41]
	v_mfma_f32_16x16x32_bf16 v[30:33], v[150:153], v[192:195], v[30:33]
	v_mfma_f32_16x16x32_bf16 v[22:25], v[130:133], v[200:203], v[22:25]
	v_mfma_f32_16x16x32_bf16 v[14:17], v[150:153], v[200:203], v[14:17]
	v_mfma_f32_16x16x32_bf16 v[62:65], v[134:137], v[166:169], v[62:65]
	v_mfma_f32_16x16x32_bf16 v[58:61], v[158:161], v[166:169], v[58:61]
	v_mfma_f32_16x16x32_bf16 v[54:57], v[134:137], v[174:177], v[54:57]
	v_mfma_f32_16x16x32_bf16 v[46:49], v[158:161], v[174:177], v[46:49]
	v_mfma_f32_16x16x32_bf16 v[38:41], v[134:137], v[196:199], v[38:41]
	v_mfma_f32_16x16x32_bf16 v[30:33], v[158:161], v[196:199], v[30:33]
	v_mfma_f32_16x16x32_bf16 v[22:25], v[134:137], v[204:207], v[22:25]
	v_mfma_f32_16x16x32_bf16 v[14:17], v[158:161], v[204:207], v[14:17]
	s_barrier
	s_add_u32 s50, s20, 0x20000
	s_addc_u32 s51, s21, 0
	s_add_i32 s52, s52, s36
	v_lshl_add_u64 v[130:131], s[50:51], 0, v[142:143]
	s_mov_b32 m0, s52
	s_nop 0
	global_load_lds_dwordx4 v[130:131], off
	v_lshl_add_u64 v[130:131], s[50:51], 0, v[138:139]
	s_add_i32 m0, s52, 0x2000
	s_nop 0
	global_load_lds_dwordx4 v[130:131], off
	v_add_u32_e32 v157, 0x18000, v154
	ds_read_b128 v[130:133], v157
	ds_read_b128 v[134:137], v157 offset:1024
	ds_read_b128 v[150:153], v157 offset:2048
	ds_read_b128 v[158:161], v157 offset:3072
	s_add_i32 s50, 0, 0x18000
	s_waitcnt vmcnt(6)
	s_barrier
	v_mfma_f32_16x16x32_bf16 v[50:53], v[208:211], v[162:165], v[50:53]
	v_mfma_f32_16x16x32_bf16 v[42:45], v[228:231], v[162:165], v[42:45]
	v_mfma_f32_16x16x32_bf16 v[34:37], v[208:211], v[170:173], v[34:37]
	v_mfma_f32_16x16x32_bf16 v[26:29], v[228:231], v[170:173], v[26:29]
	v_mfma_f32_16x16x32_bf16 v[18:21], v[208:211], v[192:195], v[18:21]
	v_mfma_f32_16x16x32_bf16 v[10:13], v[228:231], v[192:195], v[10:13]
	v_mfma_f32_16x16x32_bf16 v[6:9], v[208:211], v[200:203], v[6:9]
	v_mfma_f32_16x16x32_bf16 v[2:5], v[228:231], v[200:203], v[2:5]
	v_mfma_f32_16x16x32_bf16 v[50:53], v[224:227], v[166:169], v[50:53]
	v_mfma_f32_16x16x32_bf16 v[42:45], v[232:235], v[166:169], v[42:45]
	v_mfma_f32_16x16x32_bf16 v[34:37], v[224:227], v[174:177], v[34:37]
	v_mfma_f32_16x16x32_bf16 v[26:29], v[232:235], v[174:177], v[26:29]
	v_mfma_f32_16x16x32_bf16 v[18:21], v[224:227], v[196:199], v[18:21]
	v_mfma_f32_16x16x32_bf16 v[10:13], v[232:235], v[196:199], v[10:13]
	v_mfma_f32_16x16x32_bf16 v[6:9], v[224:227], v[204:207], v[6:9]
	v_mfma_f32_16x16x32_bf16 v[2:5], v[232:235], v[204:207], v[2:5]
	s_barrier
	s_add_u32 s22, s22, 0x20000
	s_addc_u32 s23, s23, 0
	s_mov_b32 m0, s42
	v_lshl_add_u64 v[208:209], s[22:23], 0, v[144:145]
	ds_read_b128 v[162:165], v156 offset:32768
	ds_read_b128 v[166:169], v156 offset:33792
	ds_read_b128 v[170:173], v156 offset:34816
	ds_read_b128 v[174:177], v156 offset:35840
	ds_read_b128 v[192:195], v156 offset:36864
	ds_read_b128 v[196:199], v156 offset:37888
	ds_read_b128 v[200:203], v156 offset:38912
	ds_read_b128 v[204:207], v156 offset:39936
	global_load_lds_dwordx4 v[208:209], off
	v_lshl_add_u64 v[208:209], s[22:23], 0, v[140:141]
	s_mov_b32 m0, s43
	s_nop 0
	global_load_lds_dwordx4 v[208:209], off
	s_waitcnt lgkmcnt(8)
	s_barrier
	s_waitcnt lgkmcnt(0)
	v_mfma_f32_16x16x32_bf16 v[126:129], v[130:133], v[162:165], v[126:129]
	v_mfma_f32_16x16x32_bf16 v[122:125], v[150:153], v[162:165], v[122:125]
	v_mfma_f32_16x16x32_bf16 v[118:121], v[130:133], v[170:173], v[118:121]
	v_mfma_f32_16x16x32_bf16 v[110:113], v[150:153], v[170:173], v[110:113]
	v_mfma_f32_16x16x32_bf16 v[102:105], v[130:133], v[192:195], v[102:105]
	v_mfma_f32_16x16x32_bf16 v[94:97], v[150:153], v[192:195], v[94:97]
	v_mfma_f32_16x16x32_bf16 v[86:89], v[130:133], v[200:203], v[86:89]
	v_mfma_f32_16x16x32_bf16 v[78:81], v[150:153], v[200:203], v[78:81]
	v_mfma_f32_16x16x32_bf16 v[126:129], v[134:137], v[166:169], v[126:129]
	v_mfma_f32_16x16x32_bf16 v[122:125], v[158:161], v[166:169], v[122:125]
	v_mfma_f32_16x16x32_bf16 v[118:121], v[134:137], v[174:177], v[118:121]
	v_mfma_f32_16x16x32_bf16 v[110:113], v[158:161], v[174:177], v[110:113]
	v_mfma_f32_16x16x32_bf16 v[102:105], v[134:137], v[196:199], v[102:105]
	v_mfma_f32_16x16x32_bf16 v[94:97], v[158:161], v[196:199], v[94:97]
	v_mfma_f32_16x16x32_bf16 v[86:89], v[134:137], v[204:207], v[86:89]
	v_mfma_f32_16x16x32_bf16 v[78:81], v[158:161], v[204:207], v[78:81]
	s_barrier
	s_add_i32 s22, 0, 0x1c000
	s_add_i32 s23, s50, s36
	v_add_u32_e32 v157, s22, v154
	v_lshl_add_u64 v[178:179], v[178:179], 0, s[78:79]
	s_mov_b32 m0, s23
	ds_read_b128 v[208:211], v157
	ds_read_b128 v[224:227], v157 offset:1024
	ds_read_b128 v[228:231], v157 offset:2048
	ds_read_b128 v[232:235], v157 offset:3072
	global_load_lds_dwordx4 v[178:179], off
	v_lshl_add_u64 v[178:179], v[212:213], 0, s[78:79]
	s_add_i32 m0, s23, 0x2000
	s_nop 0
	global_load_lds_dwordx4 v[178:179], off
	s_mov_b32 m0, s25
	v_lshl_add_u64 v[178:179], v[236:237], 0, s[78:79]
	s_waitcnt lgkmcnt(0)
	s_barrier
	v_mfma_f32_16x16x32_bf16 v[114:117], v[208:211], v[162:165], v[114:117]
	v_mfma_f32_16x16x32_bf16 v[106:109], v[228:231], v[162:165], v[106:109]
	v_mfma_f32_16x16x32_bf16 v[98:101], v[208:211], v[170:173], v[98:101]
	v_mfma_f32_16x16x32_bf16 v[90:93], v[228:231], v[170:173], v[90:93]
	v_mfma_f32_16x16x32_bf16 v[82:85], v[208:211], v[192:195], v[82:85]
	v_mfma_f32_16x16x32_bf16 v[74:77], v[228:231], v[192:195], v[74:77]
	v_mfma_f32_16x16x32_bf16 v[70:73], v[208:211], v[200:203], v[70:73]
	v_mfma_f32_16x16x32_bf16 v[66:69], v[228:231], v[200:203], v[66:69]
	v_mfma_f32_16x16x32_bf16 v[114:117], v[224:227], v[166:169], v[114:117]
	v_mfma_f32_16x16x32_bf16 v[106:109], v[232:235], v[166:169], v[106:109]
	v_mfma_f32_16x16x32_bf16 v[98:101], v[224:227], v[174:177], v[98:101]
	v_mfma_f32_16x16x32_bf16 v[90:93], v[232:235], v[174:177], v[90:93]
	v_mfma_f32_16x16x32_bf16 v[82:85], v[224:227], v[196:199], v[82:85]
	v_mfma_f32_16x16x32_bf16 v[74:77], v[232:235], v[196:199], v[74:77]
	v_mfma_f32_16x16x32_bf16 v[70:73], v[224:227], v[204:207], v[70:73]
	v_mfma_f32_16x16x32_bf16 v[66:69], v[232:235], v[204:207], v[66:69]
	s_barrier
	ds_read_b128 v[162:165], v156 offset:49152
	ds_read_b128 v[166:169], v156 offset:50176
	ds_read_b128 v[170:173], v156 offset:51200
	ds_read_b128 v[174:177], v156 offset:52224
	ds_read_b128 v[192:195], v156 offset:53248
	ds_read_b128 v[196:199], v156 offset:54272
	ds_read_b128 v[200:203], v156 offset:55296
	ds_read_b128 v[204:207], v156 offset:56320
	global_load_lds_dwordx4 v[178:179], off
	v_lshl_add_u64 v[178:179], v[238:239], 0, s[78:79]
	s_mov_b32 m0, s26
	s_nop 0
	global_load_lds_dwordx4 v[178:179], off
	s_waitcnt vmcnt(10)
	s_barrier
	s_waitcnt lgkmcnt(0)
	v_mfma_f32_16x16x32_bf16 v[62:65], v[130:133], v[162:165], v[62:65]
	v_mfma_f32_16x16x32_bf16 v[58:61], v[150:153], v[162:165], v[58:61]
	v_mfma_f32_16x16x32_bf16 v[54:57], v[130:133], v[170:173], v[54:57]
	v_mfma_f32_16x16x32_bf16 v[46:49], v[150:153], v[170:173], v[46:49]
	v_mfma_f32_16x16x32_bf16 v[38:41], v[130:133], v[192:195], v[38:41]
	v_mfma_f32_16x16x32_bf16 v[30:33], v[150:153], v[192:195], v[30:33]
	v_mfma_f32_16x16x32_bf16 v[22:25], v[130:133], v[200:203], v[22:25]
	v_mfma_f32_16x16x32_bf16 v[14:17], v[150:153], v[200:203], v[14:17]
	v_mfma_f32_16x16x32_bf16 v[62:65], v[134:137], v[166:169], v[62:65]
	v_mfma_f32_16x16x32_bf16 v[58:61], v[158:161], v[166:169], v[58:61]
	v_mfma_f32_16x16x32_bf16 v[54:57], v[134:137], v[174:177], v[54:57]
	v_mfma_f32_16x16x32_bf16 v[46:49], v[158:161], v[174:177], v[46:49]
	v_mfma_f32_16x16x32_bf16 v[38:41], v[134:137], v[196:199], v[38:41]
	v_mfma_f32_16x16x32_bf16 v[30:33], v[158:161], v[196:199], v[30:33]
	v_mfma_f32_16x16x32_bf16 v[22:25], v[134:137], v[204:207], v[22:25]
	v_mfma_f32_16x16x32_bf16 v[14:17], v[158:161], v[204:207], v[14:17]
	s_barrier
	s_add_u32 s20, s20, 0x20080
	s_addc_u32 s21, s21, 0
	s_add_i32 s22, s22, s36
	v_lshl_add_u64 v[130:131], s[20:21], 0, v[142:143]
	s_mov_b32 m0, s22
	s_nop 0
	global_load_lds_dwordx4 v[130:131], off
	v_lshl_add_u64 v[130:131], s[20:21], 0, v[138:139]
	s_add_i32 m0, s22, 0x2000
	s_nop 0
	global_load_lds_dwordx4 v[130:131], off
	v_add_u32_e32 v157, 0x10000, v154
	ds_read_b128 v[130:133], v157
	ds_read_b128 v[134:137], v157 offset:1024
	ds_read_b128 v[150:153], v157 offset:2048
	ds_read_b128 v[158:161], v157 offset:3072
	s_add_i32 s49, s49, 2
	s_add_u32 s18, s18, 0x100
	s_addc_u32 s19, s19, 0
	s_add_u32 s47, s47, 0x100
	s_addc_u32 s48, s48, 0
	s_cmp_gt_u32 s49, 5
	s_waitcnt vmcnt(6)
	s_barrier
	v_mfma_f32_16x16x32_bf16 v[50:53], v[208:211], v[162:165], v[50:53]
	v_mfma_f32_16x16x32_bf16 v[42:45], v[228:231], v[162:165], v[42:45]
	v_mfma_f32_16x16x32_bf16 v[34:37], v[208:211], v[170:173], v[34:37]
	v_mfma_f32_16x16x32_bf16 v[26:29], v[228:231], v[170:173], v[26:29]
	v_mfma_f32_16x16x32_bf16 v[18:21], v[208:211], v[192:195], v[18:21]
	v_mfma_f32_16x16x32_bf16 v[10:13], v[228:231], v[192:195], v[10:13]
	v_mfma_f32_16x16x32_bf16 v[6:9], v[208:211], v[200:203], v[6:9]
	v_mfma_f32_16x16x32_bf16 v[2:5], v[228:231], v[200:203], v[2:5]
	v_mfma_f32_16x16x32_bf16 v[50:53], v[224:227], v[166:169], v[50:53]
	v_mfma_f32_16x16x32_bf16 v[42:45], v[232:235], v[166:169], v[42:45]
	v_mfma_f32_16x16x32_bf16 v[34:37], v[224:227], v[174:177], v[34:37]
	v_mfma_f32_16x16x32_bf16 v[26:29], v[232:235], v[174:177], v[26:29]
	v_mfma_f32_16x16x32_bf16 v[18:21], v[224:227], v[196:199], v[18:21]
	v_mfma_f32_16x16x32_bf16 v[10:13], v[232:235], v[196:199], v[10:13]
	v_mfma_f32_16x16x32_bf16 v[6:9], v[224:227], v[204:207], v[6:9]
	v_mfma_f32_16x16x32_bf16 v[2:5], v[232:235], v[204:207], v[2:5]
	s_barrier
	s_cbranch_scc0 .LBB0_386
	s_waitcnt lgkmcnt(0)
	v_lshl_add_u32 v164, s29, 8, v1
	v_lshl_or_b32 v150, s28, 8, v155
	s_mov_b64 s[18:19], -1
	s_cmp_lt_i32 s28, 8
	v_or_b32_e32 v163, 16, v164
	v_or_b32_e32 v162, 32, v164
	v_or_b32_e32 v161, 48, v164
	v_add_u32_e32 v160, 0x80, v164
	v_add_u32_e32 v159, 0x90, v164
	v_add_u32_e32 v158, 0xa0, v164
	v_add_u32_e32 v157, 0xb0, v164
	s_cbranch_scc1 .LBB0_389
	v_lshlrev_b32_e32 v130, 7, v164
	v_readlane_b32 s4, v255, 4
	v_and_b32_e32 v132, 0x3e780, v130
	v_mov_b32_e32 v133, v0
	v_readlane_b32 s5, v255, 5
	v_readlane_b32 s6, v255, 6
	v_readlane_b32 s7, v255, 7
	v_lshlrev_b32_e32 v130, 1, v150
	v_lshl_add_u64 v[134:135], s[4:5], 0, v[132:133]
	v_and_b32_e32 v130, 0x70, v130
	v_mov_b32_e32 v131, v0
	v_lshl_add_u64 v[132:133], s[6:7], 0, v[132:133]
	v_lshl_add_u64 v[152:153], v[132:133], 0, v[130:131]
	v_lshl_add_u64 v[136:137], v[134:135], 0, v[130:131]
	global_load_dwordx4 v[170:173], v[152:153], off
	global_load_dwordx4 v[166:169], v[136:137], off
	v_readlane_b32 s8, v255, 8
	v_readlane_b32 s9, v255, 9
	v_mov_b32_e32 v151, v0
	v_lshlrev_b64 v[134:135], 1, v[150:151]
	v_mov_b64_e32 v[132:133], s[8:9]
	v_mad_i64_i32 v[174:175], s[18:19], v164, s24, v[132:133]
	v_lshl_add_u64 v[174:175], v[174:175], 0, v[134:135]
	v_readlane_b32 s10, v255, 10
	v_readlane_b32 s11, v255, 11
	s_waitcnt vmcnt(0)
	v_pk_mul_f32 v[172:173], v[172:173], s[86:87] op_sel_hi:[1,0]
	v_pk_mul_f32 v[170:171], v[170:171], s[86:87] op_sel_hi:[1,0]
	v_pk_mul_f32 v[168:169], v[168:169], s[86:87] op_sel_hi:[1,0]
	v_pk_mul_f32 v[166:167], v[166:167], s[86:87] op_sel_hi:[1,0]
	v_pk_mul_f32 v[176:177], v[124:125], v[172:173]
	v_pk_mul_f32 v[178:179], v[122:123], v[170:171]
	v_pk_mul_f32 v[172:173], v[128:129], v[172:173]
	v_pk_mul_f32 v[170:171], v[126:127], v[170:171]
	v_pk_fma_f32 v[176:177], v[128:129], v[168:169], v[176:177] neg_lo:[0,0,1] neg_hi:[0,0,1]
	v_pk_fma_f32 v[178:179], v[126:127], v[166:167], v[178:179] neg_lo:[0,0,1] neg_hi:[0,0,1]
	v_pk_fma_f32 v[172:173], v[124:125], v[168:169], v[172:173]
	v_pk_fma_f32 v[168:169], v[122:123], v[166:167], v[170:171]
	v_cvt_pk_bf16_f32 v166, v178, v179
	v_cvt_pk_bf16_f32 v167, v176, v177
	v_cvt_pk_bf16_f32 v168, v168, v169
	v_cvt_pk_bf16_f32 v169, v172, v173
	global_store_dwordx4 v[174:175], v[166:169], off
	global_load_dwordx4 v[166:169], v[136:137], off
	s_nop 0
	global_load_dwordx4 v[170:173], v[152:153], off
	v_lshlrev_b32_e32 v136, 7, v163
	v_mov_b32_e32 v137, v0
	v_and_b32_e32 v136, 0x3ef80, v136
	v_lshl_add_u64 v[152:153], s[4:5], 0, v[136:137]
	v_lshl_add_u64 v[136:137], s[6:7], 0, v[136:137]
	v_lshl_add_u64 v[136:137], v[136:137], 0, v[130:131]
	v_lshl_add_u64 v[152:153], v[152:153], 0, v[130:131]
	s_waitcnt vmcnt(0)
	v_pk_mul_f32 v[168:169], v[168:169], s[86:87] op_sel_hi:[1,0]
	v_pk_mul_f32 v[172:173], v[172:173], s[86:87] op_sel_hi:[1,0]
	v_pk_mul_f32 v[170:171], v[170:171], s[86:87] op_sel_hi:[1,0]
	v_pk_mul_f32 v[166:167], v[166:167], s[86:87] op_sel_hi:[1,0]
	v_pk_mul_f32 v[176:177], v[108:109], v[172:173]
	v_pk_mul_f32 v[178:179], v[106:107], v[170:171]
	v_pk_mul_f32 v[172:173], v[116:117], v[172:173]
	v_pk_mul_f32 v[170:171], v[114:115], v[170:171]
	v_pk_fma_f32 v[176:177], v[116:117], v[168:169], v[176:177] neg_lo:[0,0,1] neg_hi:[0,0,1]
	v_pk_fma_f32 v[178:179], v[114:115], v[166:167], v[178:179] neg_lo:[0,0,1] neg_hi:[0,0,1]
	v_pk_fma_f32 v[172:173], v[108:109], v[168:169], v[172:173]
	v_pk_fma_f32 v[168:169], v[106:107], v[166:167], v[170:171]
	v_cvt_pk_bf16_f32 v166, v178, v179
	v_cvt_pk_bf16_f32 v167, v176, v177
	v_cvt_pk_bf16_f32 v168, v168, v169
	v_cvt_pk_bf16_f32 v169, v172, v173
	global_store_dwordx4 v[174:175], v[166:169], off offset:256
	global_load_dwordx4 v[170:173], v[136:137], off
	v_mad_i64_i32 v[174:175], s[18:19], v163, s24, v[132:133]
	global_load_dwordx4 v[166:169], v[152:153], off
	v_lshl_add_u64 v[174:175], v[174:175], 0, v[134:135]
	s_waitcnt vmcnt(0)
	v_pk_mul_f32 v[172:173], v[172:173], s[86:87] op_sel_hi:[1,0]
	v_pk_mul_f32 v[170:171], v[170:171], s[86:87] op_sel_hi:[1,0]
	v_pk_mul_f32 v[176:177], v[112:113], v[172:173]
	v_pk_mul_f32 v[168:169], v[168:169], s[86:87] op_sel_hi:[1,0]
	v_pk_mul_f32 v[166:167], v[166:167], s[86:87] op_sel_hi:[1,0]
	v_pk_mul_f32 v[178:179], v[110:111], v[170:171]
	v_pk_mul_f32 v[172:173], v[120:121], v[172:173]
	v_pk_mul_f32 v[170:171], v[118:119], v[170:171]
	v_pk_fma_f32 v[176:177], v[120:121], v[168:169], v[176:177] neg_lo:[0,0,1] neg_hi:[0,0,1]
	v_pk_fma_f32 v[178:179], v[118:119], v[166:167], v[178:179] neg_lo:[0,0,1] neg_hi:[0,0,1]
	v_pk_fma_f32 v[172:173], v[112:113], v[168:169], v[172:173]
	v_pk_fma_f32 v[168:169], v[110:111], v[166:167], v[170:171]
	v_cvt_pk_bf16_f32 v166, v178, v179
	v_cvt_pk_bf16_f32 v167, v176, v177
	v_cvt_pk_bf16_f32 v168, v168, v169
	v_cvt_pk_bf16_f32 v169, v172, v173
	global_store_dwordx4 v[174:175], v[166:169], off
	global_load_dwordx4 v[166:169], v[152:153], off
	s_nop 0
	global_load_dwordx4 v[170:173], v[136:137], off
	v_lshlrev_b32_e32 v136, 7, v162
	v_mov_b32_e32 v137, v0
	v_and_b32_e32 v136, 0x3f780, v136
	v_lshl_add_u64 v[152:153], s[4:5], 0, v[136:137]
	v_lshl_add_u64 v[136:137], s[6:7], 0, v[136:137]
	v_lshl_add_u64 v[136:137], v[136:137], 0, v[130:131]
	v_lshl_add_u64 v[152:153], v[152:153], 0, v[130:131]
	s_waitcnt vmcnt(0)
	v_pk_mul_f32 v[168:169], v[168:169], s[86:87] op_sel_hi:[1,0]
	v_pk_mul_f32 v[172:173], v[172:173], s[86:87] op_sel_hi:[1,0]
	v_pk_mul_f32 v[170:171], v[170:171], s[86:87] op_sel_hi:[1,0]
	v_pk_mul_f32 v[166:167], v[166:167], s[86:87] op_sel_hi:[1,0]
	v_pk_mul_f32 v[176:177], v[92:93], v[172:173]
	v_pk_mul_f32 v[178:179], v[90:91], v[170:171]
	v_pk_mul_f32 v[172:173], v[100:101], v[172:173]
	v_pk_mul_f32 v[170:171], v[98:99], v[170:171]
	v_pk_fma_f32 v[176:177], v[100:101], v[168:169], v[176:177] neg_lo:[0,0,1] neg_hi:[0,0,1]
	v_pk_fma_f32 v[178:179], v[98:99], v[166:167], v[178:179] neg_lo:[0,0,1] neg_hi:[0,0,1]
	v_pk_fma_f32 v[172:173], v[92:93], v[168:169], v[172:173]
	v_pk_fma_f32 v[168:169], v[90:91], v[166:167], v[170:171]
	v_cvt_pk_bf16_f32 v166, v178, v179
	v_cvt_pk_bf16_f32 v167, v176, v177
	v_cvt_pk_bf16_f32 v168, v168, v169
	v_cvt_pk_bf16_f32 v169, v172, v173
	global_store_dwordx4 v[174:175], v[166:169], off offset:256
	global_load_dwordx4 v[170:173], v[136:137], off
	v_mad_i64_i32 v[174:175], s[18:19], v162, s24, v[132:133]
	global_load_dwordx4 v[166:169], v[152:153], off
	v_lshl_add_u64 v[174:175], v[174:175], 0, v[134:135]
	s_waitcnt vmcnt(0)
	v_pk_mul_f32 v[172:173], v[172:173], s[86:87] op_sel_hi:[1,0]
	v_pk_mul_f32 v[170:171], v[170:171], s[86:87] op_sel_hi:[1,0]
	v_pk_mul_f32 v[176:177], v[96:97], v[172:173]
	v_pk_mul_f32 v[168:169], v[168:169], s[86:87] op_sel_hi:[1,0]
	v_pk_mul_f32 v[166:167], v[166:167], s[86:87] op_sel_hi:[1,0]
	v_pk_mul_f32 v[178:179], v[94:95], v[170:171]
	v_pk_mul_f32 v[172:173], v[104:105], v[172:173]
	v_pk_mul_f32 v[170:171], v[102:103], v[170:171]
	v_pk_fma_f32 v[176:177], v[104:105], v[168:169], v[176:177] neg_lo:[0,0,1] neg_hi:[0,0,1]
	v_pk_fma_f32 v[178:179], v[102:103], v[166:167], v[178:179] neg_lo:[0,0,1] neg_hi:[0,0,1]
	v_pk_fma_f32 v[172:173], v[96:97], v[168:169], v[172:173]
	v_pk_fma_f32 v[168:169], v[94:95], v[166:167], v[170:171]
	v_cvt_pk_bf16_f32 v166, v178, v179
	v_cvt_pk_bf16_f32 v167, v176, v177
	v_cvt_pk_bf16_f32 v168, v168, v169
	v_cvt_pk_bf16_f32 v169, v172, v173
	global_store_dwordx4 v[174:175], v[166:169], off
	global_load_dwordx4 v[166:169], v[152:153], off
	s_nop 0
	global_load_dwordx4 v[170:173], v[136:137], off
	v_lshlrev_b32_e32 v136, 7, v161
	v_mov_b32_e32 v137, v0
	v_and_b32_e32 v136, 0x3ff80, v136
	v_lshl_add_u64 v[152:153], s[4:5], 0, v[136:137]
	v_lshl_add_u64 v[136:137], s[6:7], 0, v[136:137]
	v_lshl_add_u64 v[136:137], v[136:137], 0, v[130:131]
	v_lshl_add_u64 v[152:153], v[152:153], 0, v[130:131]
	s_waitcnt vmcnt(0)
	v_pk_mul_f32 v[168:169], v[168:169], s[86:87] op_sel_hi:[1,0]
	v_pk_mul_f32 v[172:173], v[172:173], s[86:87] op_sel_hi:[1,0]
	v_pk_mul_f32 v[170:171], v[170:171], s[86:87] op_sel_hi:[1,0]
	v_pk_mul_f32 v[166:167], v[166:167], s[86:87] op_sel_hi:[1,0]
	v_pk_mul_f32 v[176:177], v[76:77], v[172:173]
	v_pk_mul_f32 v[178:179], v[74:75], v[170:171]
	v_pk_mul_f32 v[172:173], v[84:85], v[172:173]
	v_pk_mul_f32 v[170:171], v[82:83], v[170:171]
	v_pk_fma_f32 v[176:177], v[84:85], v[168:169], v[176:177] neg_lo:[0,0,1] neg_hi:[0,0,1]
	v_pk_fma_f32 v[178:179], v[82:83], v[166:167], v[178:179] neg_lo:[0,0,1] neg_hi:[0,0,1]
	v_pk_fma_f32 v[172:173], v[76:77], v[168:169], v[172:173]
	v_pk_fma_f32 v[168:169], v[74:75], v[166:167], v[170:171]
	v_cvt_pk_bf16_f32 v166, v178, v179
	v_cvt_pk_bf16_f32 v167, v176, v177
	v_cvt_pk_bf16_f32 v168, v168, v169
	v_cvt_pk_bf16_f32 v169, v172, v173
	global_store_dwordx4 v[174:175], v[166:169], off offset:256
	global_load_dwordx4 v[170:173], v[136:137], off
	v_mad_i64_i32 v[174:175], s[18:19], v161, s24, v[132:133]
	global_load_dwordx4 v[166:169], v[152:153], off
	v_lshl_add_u64 v[174:175], v[174:175], 0, v[134:135]
	s_waitcnt vmcnt(0)
	v_pk_mul_f32 v[172:173], v[172:173], s[86:87] op_sel_hi:[1,0]
	v_pk_mul_f32 v[170:171], v[170:171], s[86:87] op_sel_hi:[1,0]
	v_pk_mul_f32 v[176:177], v[80:81], v[172:173]
	v_pk_mul_f32 v[168:169], v[168:169], s[86:87] op_sel_hi:[1,0]
	v_pk_mul_f32 v[166:167], v[166:167], s[86:87] op_sel_hi:[1,0]
	v_pk_mul_f32 v[178:179], v[78:79], v[170:171]
	v_pk_mul_f32 v[172:173], v[88:89], v[172:173]
	v_pk_mul_f32 v[170:171], v[86:87], v[170:171]
	v_pk_fma_f32 v[176:177], v[88:89], v[168:169], v[176:177] neg_lo:[0,0,1] neg_hi:[0,0,1]
	v_pk_fma_f32 v[178:179], v[86:87], v[166:167], v[178:179] neg_lo:[0,0,1] neg_hi:[0,0,1]
	v_pk_fma_f32 v[172:173], v[80:81], v[168:169], v[172:173]
	v_pk_fma_f32 v[168:169], v[78:79], v[166:167], v[170:171]
	v_cvt_pk_bf16_f32 v166, v178, v179
	v_cvt_pk_bf16_f32 v167, v176, v177
	v_cvt_pk_bf16_f32 v168, v168, v169
	v_cvt_pk_bf16_f32 v169, v172, v173
	global_store_dwordx4 v[174:175], v[166:169], off
	global_load_dwordx4 v[166:169], v[152:153], off
	s_nop 0
	global_load_dwordx4 v[170:173], v[136:137], off
	v_lshlrev_b32_e32 v136, 7, v160
	v_mov_b32_e32 v137, v0
	v_and_b32_e32 v136, 0x3e780, v136
	v_lshl_add_u64 v[152:153], s[4:5], 0, v[136:137]
	v_lshl_add_u64 v[136:137], s[6:7], 0, v[136:137]
	v_lshl_add_u64 v[136:137], v[136:137], 0, v[130:131]
	v_lshl_add_u64 v[152:153], v[152:153], 0, v[130:131]
	s_waitcnt vmcnt(0)
	v_pk_mul_f32 v[168:169], v[168:169], s[86:87] op_sel_hi:[1,0]
	v_pk_mul_f32 v[172:173], v[172:173], s[86:87] op_sel_hi:[1,0]
	v_pk_mul_f32 v[170:171], v[170:171], s[86:87] op_sel_hi:[1,0]
	v_pk_mul_f32 v[166:167], v[166:167], s[86:87] op_sel_hi:[1,0]
	v_pk_mul_f32 v[176:177], v[68:69], v[172:173]
	v_pk_mul_f32 v[178:179], v[66:67], v[170:171]
	v_pk_mul_f32 v[172:173], v[72:73], v[172:173]
	v_pk_mul_f32 v[170:171], v[70:71], v[170:171]
	v_pk_fma_f32 v[176:177], v[72:73], v[168:169], v[176:177] neg_lo:[0,0,1] neg_hi:[0,0,1]
	v_pk_fma_f32 v[178:179], v[70:71], v[166:167], v[178:179] neg_lo:[0,0,1] neg_hi:[0,0,1]
	v_pk_fma_f32 v[172:173], v[68:69], v[168:169], v[172:173]
	v_pk_fma_f32 v[168:169], v[66:67], v[166:167], v[170:171]
	v_cvt_pk_bf16_f32 v166, v178, v179
	v_cvt_pk_bf16_f32 v167, v176, v177
	v_cvt_pk_bf16_f32 v168, v168, v169
	v_cvt_pk_bf16_f32 v169, v172, v173
	global_store_dwordx4 v[174:175], v[166:169], off offset:256
	global_load_dwordx4 v[170:173], v[136:137], off
	v_mad_i64_i32 v[174:175], s[18:19], v160, s24, v[132:133]
	global_load_dwordx4 v[166:169], v[152:153], off
	v_lshl_add_u64 v[174:175], v[174:175], 0, v[134:135]
	s_waitcnt vmcnt(0)
	v_pk_mul_f32 v[172:173], v[172:173], s[86:87] op_sel_hi:[1,0]
	v_pk_mul_f32 v[170:171], v[170:171], s[86:87] op_sel_hi:[1,0]
	v_pk_mul_f32 v[176:177], v[60:61], v[172:173]
	v_pk_mul_f32 v[168:169], v[168:169], s[86:87] op_sel_hi:[1,0]
	v_pk_mul_f32 v[166:167], v[166:167], s[86:87] op_sel_hi:[1,0]
	v_pk_mul_f32 v[178:179], v[58:59], v[170:171]
	v_pk_mul_f32 v[172:173], v[64:65], v[172:173]
	v_pk_mul_f32 v[170:171], v[62:63], v[170:171]
	v_pk_fma_f32 v[176:177], v[64:65], v[168:169], v[176:177] neg_lo:[0,0,1] neg_hi:[0,0,1]
	v_pk_fma_f32 v[178:179], v[62:63], v[166:167], v[178:179] neg_lo:[0,0,1] neg_hi:[0,0,1]
	v_pk_fma_f32 v[172:173], v[60:61], v[168:169], v[172:173]
	v_pk_fma_f32 v[168:169], v[58:59], v[166:167], v[170:171]
	v_cvt_pk_bf16_f32 v166, v178, v179
	v_cvt_pk_bf16_f32 v167, v176, v177
	v_cvt_pk_bf16_f32 v168, v168, v169
	v_cvt_pk_bf16_f32 v169, v172, v173
	global_store_dwordx4 v[174:175], v[166:169], off
	global_load_dwordx4 v[166:169], v[152:153], off
	s_nop 0
	global_load_dwordx4 v[170:173], v[136:137], off
	v_lshlrev_b32_e32 v136, 7, v159
	v_mov_b32_e32 v137, v0
	v_and_b32_e32 v136, 0x3ef80, v136
	v_lshl_add_u64 v[152:153], s[4:5], 0, v[136:137]
	v_lshl_add_u64 v[136:137], s[6:7], 0, v[136:137]
	v_lshl_add_u64 v[136:137], v[136:137], 0, v[130:131]
	v_lshl_add_u64 v[152:153], v[152:153], 0, v[130:131]
	s_waitcnt vmcnt(0)
	v_pk_mul_f32 v[168:169], v[168:169], s[86:87] op_sel_hi:[1,0]
	v_pk_mul_f32 v[172:173], v[172:173], s[86:87] op_sel_hi:[1,0]
	v_pk_mul_f32 v[170:171], v[170:171], s[86:87] op_sel_hi:[1,0]
	v_pk_mul_f32 v[166:167], v[166:167], s[86:87] op_sel_hi:[1,0]
	v_pk_mul_f32 v[176:177], v[44:45], v[172:173]
	v_pk_mul_f32 v[178:179], v[42:43], v[170:171]
	v_pk_mul_f32 v[172:173], v[52:53], v[172:173]
	v_pk_mul_f32 v[170:171], v[50:51], v[170:171]
	v_pk_fma_f32 v[176:177], v[52:53], v[168:169], v[176:177] neg_lo:[0,0,1] neg_hi:[0,0,1]
	v_pk_fma_f32 v[178:179], v[50:51], v[166:167], v[178:179] neg_lo:[0,0,1] neg_hi:[0,0,1]
	v_pk_fma_f32 v[172:173], v[44:45], v[168:169], v[172:173]
	v_pk_fma_f32 v[168:169], v[42:43], v[166:167], v[170:171]
	v_cvt_pk_bf16_f32 v166, v178, v179
	v_cvt_pk_bf16_f32 v167, v176, v177
	v_cvt_pk_bf16_f32 v168, v168, v169
	v_cvt_pk_bf16_f32 v169, v172, v173
	global_store_dwordx4 v[174:175], v[166:169], off offset:256
	global_load_dwordx4 v[170:173], v[136:137], off
	v_mad_i64_i32 v[174:175], s[18:19], v159, s24, v[132:133]
	global_load_dwordx4 v[166:169], v[152:153], off
	v_lshl_add_u64 v[174:175], v[174:175], 0, v[134:135]
	s_waitcnt vmcnt(0)
	v_pk_mul_f32 v[172:173], v[172:173], s[86:87] op_sel_hi:[1,0]
	v_pk_mul_f32 v[170:171], v[170:171], s[86:87] op_sel_hi:[1,0]
	v_pk_mul_f32 v[176:177], v[48:49], v[172:173]
	v_pk_mul_f32 v[168:169], v[168:169], s[86:87] op_sel_hi:[1,0]
	v_pk_mul_f32 v[166:167], v[166:167], s[86:87] op_sel_hi:[1,0]
	v_pk_mul_f32 v[178:179], v[46:47], v[170:171]
	v_pk_mul_f32 v[172:173], v[56:57], v[172:173]
	v_pk_mul_f32 v[170:171], v[54:55], v[170:171]
	v_pk_fma_f32 v[176:177], v[56:57], v[168:169], v[176:177] neg_lo:[0,0,1] neg_hi:[0,0,1]
	v_pk_fma_f32 v[178:179], v[54:55], v[166:167], v[178:179] neg_lo:[0,0,1] neg_hi:[0,0,1]
	v_pk_fma_f32 v[172:173], v[48:49], v[168:169], v[172:173]
	v_pk_fma_f32 v[168:169], v[46:47], v[166:167], v[170:171]
	v_cvt_pk_bf16_f32 v166, v178, v179
	v_cvt_pk_bf16_f32 v167, v176, v177
	v_cvt_pk_bf16_f32 v168, v168, v169
	v_cvt_pk_bf16_f32 v169, v172, v173
	global_store_dwordx4 v[174:175], v[166:169], off
	global_load_dwordx4 v[166:169], v[152:153], off
	s_nop 0
	global_load_dwordx4 v[170:173], v[136:137], off
	v_lshlrev_b32_e32 v136, 7, v158
	v_mov_b32_e32 v137, v0
	v_and_b32_e32 v136, 0x3f780, v136
	v_lshl_add_u64 v[152:153], s[4:5], 0, v[136:137]
	v_lshl_add_u64 v[136:137], s[6:7], 0, v[136:137]
	v_lshl_add_u64 v[136:137], v[136:137], 0, v[130:131]
	v_lshl_add_u64 v[152:153], v[152:153], 0, v[130:131]
	s_waitcnt vmcnt(0)
	v_pk_mul_f32 v[168:169], v[168:169], s[86:87] op_sel_hi:[1,0]
	v_pk_mul_f32 v[172:173], v[172:173], s[86:87] op_sel_hi:[1,0]
	v_pk_mul_f32 v[170:171], v[170:171], s[86:87] op_sel_hi:[1,0]
	v_pk_mul_f32 v[166:167], v[166:167], s[86:87] op_sel_hi:[1,0]
	v_pk_mul_f32 v[176:177], v[28:29], v[172:173]
	v_pk_mul_f32 v[178:179], v[26:27], v[170:171]
	v_pk_mul_f32 v[172:173], v[36:37], v[172:173]
	v_pk_mul_f32 v[170:171], v[34:35], v[170:171]
	v_pk_fma_f32 v[176:177], v[36:37], v[168:169], v[176:177] neg_lo:[0,0,1] neg_hi:[0,0,1]
	v_pk_fma_f32 v[178:179], v[34:35], v[166:167], v[178:179] neg_lo:[0,0,1] neg_hi:[0,0,1]
	v_pk_fma_f32 v[172:173], v[28:29], v[168:169], v[172:173]
	v_pk_fma_f32 v[168:169], v[26:27], v[166:167], v[170:171]
	v_cvt_pk_bf16_f32 v166, v178, v179
	v_cvt_pk_bf16_f32 v167, v176, v177
	v_cvt_pk_bf16_f32 v168, v168, v169
	v_cvt_pk_bf16_f32 v169, v172, v173
	global_store_dwordx4 v[174:175], v[166:169], off offset:256
	global_load_dwordx4 v[170:173], v[136:137], off
	v_mad_i64_i32 v[174:175], s[18:19], v158, s24, v[132:133]
	global_load_dwordx4 v[166:169], v[152:153], off
	v_lshl_add_u64 v[174:175], v[174:175], 0, v[134:135]
	s_waitcnt vmcnt(0)
	v_pk_mul_f32 v[172:173], v[172:173], s[86:87] op_sel_hi:[1,0]
	v_pk_mul_f32 v[170:171], v[170:171], s[86:87] op_sel_hi:[1,0]
	v_pk_mul_f32 v[176:177], v[32:33], v[172:173]
	v_pk_mul_f32 v[168:169], v[168:169], s[86:87] op_sel_hi:[1,0]
	v_pk_mul_f32 v[166:167], v[166:167], s[86:87] op_sel_hi:[1,0]
	v_pk_mul_f32 v[178:179], v[30:31], v[170:171]
	v_pk_mul_f32 v[172:173], v[40:41], v[172:173]
	v_pk_mul_f32 v[170:171], v[38:39], v[170:171]
	v_pk_fma_f32 v[176:177], v[40:41], v[168:169], v[176:177] neg_lo:[0,0,1] neg_hi:[0,0,1]
	v_pk_fma_f32 v[178:179], v[38:39], v[166:167], v[178:179] neg_lo:[0,0,1] neg_hi:[0,0,1]
	v_pk_fma_f32 v[172:173], v[32:33], v[168:169], v[172:173]
	v_pk_fma_f32 v[168:169], v[30:31], v[166:167], v[170:171]
	v_cvt_pk_bf16_f32 v166, v178, v179
	v_cvt_pk_bf16_f32 v167, v176, v177
	v_cvt_pk_bf16_f32 v168, v168, v169
	v_cvt_pk_bf16_f32 v169, v172, v173
	global_store_dwordx4 v[174:175], v[166:169], off
	global_load_dwordx4 v[166:169], v[152:153], off
	s_nop 0
	global_load_dwordx4 v[170:173], v[136:137], off
	v_lshlrev_b32_e32 v136, 7, v157
	v_mov_b32_e32 v137, v0
	v_and_b32_e32 v136, 0x3ff80, v136
	v_lshl_add_u64 v[152:153], s[4:5], 0, v[136:137]
	v_lshl_add_u64 v[176:177], v[152:153], 0, v[130:131]
	v_lshl_add_u64 v[136:137], s[6:7], 0, v[136:137]
	v_lshl_add_u64 v[136:137], v[136:137], 0, v[130:131]
	v_mad_i64_i32 v[130:131], s[18:19], v157, s24, v[132:133]
	s_mov_b64 s[18:19], 0
	s_waitcnt vmcnt(0)
	v_pk_mul_f32 v[152:153], v[168:169], s[86:87] op_sel_hi:[1,0]
	v_pk_mul_f32 v[168:169], v[172:173], s[86:87] op_sel_hi:[1,0]
	v_pk_mul_f32 v[170:171], v[170:171], s[86:87] op_sel_hi:[1,0]
	v_pk_mul_f32 v[166:167], v[166:167], s[86:87] op_sel_hi:[1,0]
	v_pk_mul_f32 v[172:173], v[12:13], v[168:169]
	v_pk_mul_f32 v[178:179], v[10:11], v[170:171]
	v_pk_mul_f32 v[168:169], v[20:21], v[168:169]
	v_pk_mul_f32 v[170:171], v[18:19], v[170:171]
	v_pk_fma_f32 v[172:173], v[20:21], v[152:153], v[172:173] neg_lo:[0,0,1] neg_hi:[0,0,1]
	v_pk_fma_f32 v[178:179], v[18:19], v[166:167], v[178:179] neg_lo:[0,0,1] neg_hi:[0,0,1]
	v_pk_fma_f32 v[152:153], v[12:13], v[152:153], v[168:169]
	v_pk_fma_f32 v[168:169], v[10:11], v[166:167], v[170:171]
	v_cvt_pk_bf16_f32 v166, v178, v179
	v_cvt_pk_bf16_f32 v167, v172, v173
	v_cvt_pk_bf16_f32 v168, v168, v169
	v_cvt_pk_bf16_f32 v169, v152, v153
	global_store_dwordx4 v[174:175], v[166:169], off offset:256
	global_load_dwordx4 v[166:169], v[176:177], off
	v_lshl_add_u64 v[152:153], v[130:131], 0, v[134:135]
	global_load_dwordx4 v[170:173], v[136:137], off
	s_waitcnt vmcnt(0)
	v_pk_mul_f32 v[132:133], v[166:167], s[86:87] op_sel_hi:[1,0]
	v_pk_mul_f32 v[130:131], v[168:169], s[86:87] op_sel_hi:[1,0]
	v_pk_mul_f32 v[134:135], v[172:173], s[86:87] op_sel_hi:[1,0]
	v_pk_mul_f32 v[166:167], v[170:171], s[86:87] op_sel_hi:[1,0]
	v_pk_mul_f32 v[168:169], v[16:17], v[134:135]
	v_pk_mul_f32 v[170:171], v[14:15], v[166:167]
	v_pk_mul_f32 v[134:135], v[24:25], v[134:135]
	v_pk_mul_f32 v[166:167], v[22:23], v[166:167]
	v_pk_fma_f32 v[168:169], v[24:25], v[130:131], v[168:169] neg_lo:[0,0,1] neg_hi:[0,0,1]
	v_pk_fma_f32 v[170:171], v[22:23], v[132:133], v[170:171] neg_lo:[0,0,1] neg_hi:[0,0,1]
	v_pk_fma_f32 v[134:135], v[16:17], v[130:131], v[134:135]
	v_pk_fma_f32 v[132:133], v[14:15], v[132:133], v[166:167]
	v_cvt_pk_bf16_f32 v130, v170, v171
	v_cvt_pk_bf16_f32 v131, v168, v169
	v_cvt_pk_bf16_f32 v132, v132, v133
	v_cvt_pk_bf16_f32 v133, v134, v135
	global_store_dwordx4 v[152:153], v[130:133], off
	global_load_dwordx4 v[130:133], v[176:177], off
	s_nop 0
	global_load_dwordx4 v[134:137], v[136:137], off
	s_waitcnt vmcnt(0)
	v_pk_mul_f32 v[166:167], v[132:133], s[86:87] op_sel_hi:[1,0]
	v_pk_mul_f32 v[168:169], v[130:131], s[86:87] op_sel_hi:[1,0]
	v_pk_mul_f32 v[130:131], v[136:137], s[86:87] op_sel_hi:[1,0]
	v_pk_mul_f32 v[132:133], v[134:135], s[86:87] op_sel_hi:[1,0]
	v_pk_mul_f32 v[134:135], v[4:5], v[130:131]
	v_pk_mul_f32 v[136:137], v[2:3], v[132:133]
	v_pk_mul_f32 v[170:171], v[8:9], v[130:131]
	v_pk_mul_f32 v[172:173], v[6:7], v[132:133]
	v_pk_fma_f32 v[132:133], v[8:9], v[166:167], v[134:135] neg_lo:[0,0,1] neg_hi:[0,0,1]
	v_pk_fma_f32 v[130:131], v[6:7], v[168:169], v[136:137] neg_lo:[0,0,1] neg_hi:[0,0,1]
	v_pk_fma_f32 v[136:137], v[4:5], v[166:167], v[170:171]
	v_pk_fma_f32 v[134:135], v[2:3], v[168:169], v[172:173]

.LBB0_526:
	s_add_u32 s20, s18, 0xfff80080
	s_addc_u32 s21, s19, -1
	s_add_i32 s56, 0, 0x10000
	s_cmp_eq_u32 s55, 28
	s_cselect_b32 s23, s39, s21
	s_cselect_b32 s22, s51, s20
	s_cselect_b32 s21, s31, s54
	s_cselect_b32 s20, s52, s53
	v_lshl_add_u64 v[152:153], s[18:19], 0, v[140:141]
	s_add_i32 m0, s29, 0xc000
	ds_read_b128 v[164:167], v154
	ds_read_b128 v[168:171], v154 offset:1024
	ds_read_b128 v[172:175], v154 offset:2048
	ds_read_b128 v[176:179], v154 offset:3072
	ds_read_b128 v[192:195], v154 offset:4096
	ds_read_b128 v[196:199], v154 offset:5120
	ds_read_b128 v[200:203], v154 offset:6144
	ds_read_b128 v[204:207], v154 offset:7168
	global_load_lds_dwordx4 v[152:153], off
	v_lshl_add_u64 v[152:153], s[18:19], 0, v[142:143]
	s_add_i32 m0, s29, 0xe000
	s_nop 0
	global_load_lds_dwordx4 v[152:153], off
	s_waitcnt lgkmcnt(8)
	s_barrier
	s_waitcnt lgkmcnt(0)
	v_mfma_f32_16x16x32_bf16 v[126:129], v[144:147], v[164:167], v[126:129]
	v_mfma_f32_16x16x32_bf16 v[122:125], v[156:159], v[164:167], v[122:125]
	v_mfma_f32_16x16x32_bf16 v[118:121], v[144:147], v[172:175], v[118:121]
	v_mfma_f32_16x16x32_bf16 v[114:117], v[156:159], v[172:175], v[114:117]
	v_mfma_f32_16x16x32_bf16 v[102:105], v[144:147], v[192:195], v[102:105]
	v_mfma_f32_16x16x32_bf16 v[98:101], v[156:159], v[192:195], v[98:101]
	v_mfma_f32_16x16x32_bf16 v[86:89], v[144:147], v[200:203], v[86:89]
	v_mfma_f32_16x16x32_bf16 v[82:85], v[156:159], v[200:203], v[82:85]
	v_mfma_f32_16x16x32_bf16 v[126:129], v[148:151], v[168:171], v[126:129]
	v_mfma_f32_16x16x32_bf16 v[122:125], v[160:163], v[168:171], v[122:125]
	v_mfma_f32_16x16x32_bf16 v[118:121], v[148:151], v[176:179], v[118:121]
	v_mfma_f32_16x16x32_bf16 v[114:117], v[160:163], v[176:179], v[114:117]
	v_mfma_f32_16x16x32_bf16 v[102:105], v[148:151], v[196:199], v[102:105]
	v_mfma_f32_16x16x32_bf16 v[98:101], v[160:163], v[196:199], v[98:101]
	v_mfma_f32_16x16x32_bf16 v[86:89], v[148:151], v[204:207], v[86:89]
	v_mfma_f32_16x16x32_bf16 v[82:85], v[160:163], v[204:207], v[82:85]
	s_barrier
	s_add_i32 s58, 0, 0x14000
	v_add_u32_e32 v152, s58, v139
	s_add_i32 s56, s56, s28
	ds_read_b128 v[208:211], v152
	ds_read_b128 v[224:227], v152 offset:1024
	ds_read_b128 v[228:231], v152 offset:2048
	ds_read_b128 v[232:235], v152 offset:3072
	v_lshl_add_u64 v[152:153], s[20:21], 0, v[134:135]
	s_mov_b32 m0, s56
	v_lshl_add_u64 v[212:213], s[20:21], 0, v[130:131]
	global_load_lds_dwordx4 v[152:153], off
	s_add_i32 m0, s56, 0x2000
	s_nop 0
	global_load_lds_dwordx4 v[212:213], off
	s_mov_b32 m0, s29
	v_lshl_add_u64 v[236:237], s[22:23], 0, v[136:137]
	s_waitcnt lgkmcnt(0)
	s_barrier
	v_mfma_f32_16x16x32_bf16 v[110:113], v[208:211], v[164:167], v[110:113]
	v_mfma_f32_16x16x32_bf16 v[106:109], v[228:231], v[164:167], v[106:109]
	v_mfma_f32_16x16x32_bf16 v[94:97], v[208:211], v[172:175], v[94:97]
	v_mfma_f32_16x16x32_bf16 v[90:93], v[228:231], v[172:175], v[90:93]
	v_mfma_f32_16x16x32_bf16 v[78:81], v[208:211], v[192:195], v[78:81]
	v_mfma_f32_16x16x32_bf16 v[74:77], v[228:231], v[192:195], v[74:77]
	v_mfma_f32_16x16x32_bf16 v[70:73], v[208:211], v[200:203], v[70:73]
	v_mfma_f32_16x16x32_bf16 v[66:69], v[228:231], v[200:203], v[66:69]
	v_mfma_f32_16x16x32_bf16 v[110:113], v[224:227], v[168:171], v[110:113]
	v_mfma_f32_16x16x32_bf16 v[106:109], v[232:235], v[168:171], v[106:109]
	v_mfma_f32_16x16x32_bf16 v[94:97], v[224:227], v[176:179], v[94:97]
	v_mfma_f32_16x16x32_bf16 v[90:93], v[232:235], v[176:179], v[90:93]
	v_mfma_f32_16x16x32_bf16 v[78:81], v[224:227], v[196:199], v[78:81]
	v_mfma_f32_16x16x32_bf16 v[74:77], v[232:235], v[196:199], v[74:77]
	v_mfma_f32_16x16x32_bf16 v[70:73], v[224:227], v[204:207], v[70:73]
	v_mfma_f32_16x16x32_bf16 v[66:69], v[232:235], v[204:207], v[66:69]
	s_barrier
	ds_read_b128 v[164:167], v154 offset:16384
	ds_read_b128 v[168:171], v154 offset:17408
	ds_read_b128 v[172:175], v154 offset:18432
	ds_read_b128 v[176:179], v154 offset:19456
	ds_read_b128 v[192:195], v154 offset:20480
	ds_read_b128 v[196:199], v154 offset:21504
	ds_read_b128 v[200:203], v154 offset:22528
	ds_read_b128 v[204:207], v154 offset:23552
	global_load_lds_dwordx4 v[236:237], off
	v_lshl_add_u64 v[238:239], s[22:23], 0, v[132:133]
	s_mov_b32 m0, s44
	s_nop 0
	global_load_lds_dwordx4 v[238:239], off
	s_waitcnt vmcnt(10)
	s_barrier
	s_waitcnt lgkmcnt(0)
	v_mfma_f32_16x16x32_bf16 v[62:65], v[144:147], v[164:167], v[62:65]
	v_mfma_f32_16x16x32_bf16 v[58:61], v[156:159], v[164:167], v[58:61]
	v_mfma_f32_16x16x32_bf16 v[54:57], v[144:147], v[172:175], v[54:57]
	v_mfma_f32_16x16x32_bf16 v[50:53], v[156:159], v[172:175], v[50:53]
	v_mfma_f32_16x16x32_bf16 v[38:41], v[144:147], v[192:195], v[38:41]
	v_mfma_f32_16x16x32_bf16 v[34:37], v[156:159], v[192:195], v[34:37]
	v_mfma_f32_16x16x32_bf16 v[22:25], v[144:147], v[200:203], v[22:25]
	v_mfma_f32_16x16x32_bf16 v[18:21], v[156:159], v[200:203], v[18:21]
	v_mfma_f32_16x16x32_bf16 v[62:65], v[148:151], v[168:171], v[62:65]
	v_mfma_f32_16x16x32_bf16 v[58:61], v[160:163], v[168:171], v[58:61]
	v_mfma_f32_16x16x32_bf16 v[54:57], v[148:151], v[176:179], v[54:57]
	v_mfma_f32_16x16x32_bf16 v[50:53], v[160:163], v[176:179], v[50:53]
	v_mfma_f32_16x16x32_bf16 v[38:41], v[148:151], v[196:199], v[38:41]
	v_mfma_f32_16x16x32_bf16 v[34:37], v[160:163], v[196:199], v[34:37]
	v_mfma_f32_16x16x32_bf16 v[22:25], v[148:151], v[204:207], v[22:25]
	v_mfma_f32_16x16x32_bf16 v[18:21], v[160:163], v[204:207], v[18:21]
	s_barrier
	s_add_u32 s56, s20, 0x80000
	s_addc_u32 s57, s21, 0
	s_add_i32 s58, s58, s28
	v_lshl_add_u64 v[144:145], s[56:57], 0, v[134:135]
	s_mov_b32 m0, s58
	s_nop 0
	global_load_lds_dwordx4 v[144:145], off
	v_lshl_add_u64 v[144:145], s[56:57], 0, v[130:131]
	s_add_i32 m0, s58, 0x2000
	s_nop 0
	global_load_lds_dwordx4 v[144:145], off
	v_add_u32_e32 v155, 0x18000, v139
	ds_read_b128 v[144:147], v155
	ds_read_b128 v[148:151], v155 offset:1024
	ds_read_b128 v[156:159], v155 offset:2048
	ds_read_b128 v[160:163], v155 offset:3072
	s_add_i32 s56, 0, 0x18000
	s_waitcnt vmcnt(6)
	s_barrier
	v_mfma_f32_16x16x32_bf16 v[46:49], v[208:211], v[164:167], v[46:49]
	v_mfma_f32_16x16x32_bf16 v[42:45], v[228:231], v[164:167], v[42:45]
	v_mfma_f32_16x16x32_bf16 v[30:33], v[208:211], v[172:175], v[30:33]
	v_mfma_f32_16x16x32_bf16 v[26:29], v[228:231], v[172:175], v[26:29]
	v_mfma_f32_16x16x32_bf16 v[14:17], v[208:211], v[192:195], v[14:17]
	v_mfma_f32_16x16x32_bf16 v[10:13], v[228:231], v[192:195], v[10:13]
	v_mfma_f32_16x16x32_bf16 v[6:9], v[208:211], v[200:203], v[6:9]
	v_mfma_f32_16x16x32_bf16 v[2:5], v[228:231], v[200:203], v[2:5]
	v_mfma_f32_16x16x32_bf16 v[46:49], v[224:227], v[168:171], v[46:49]
	v_mfma_f32_16x16x32_bf16 v[42:45], v[232:235], v[168:171], v[42:45]
	v_mfma_f32_16x16x32_bf16 v[30:33], v[224:227], v[176:179], v[30:33]
	v_mfma_f32_16x16x32_bf16 v[26:29], v[232:235], v[176:179], v[26:29]
	v_mfma_f32_16x16x32_bf16 v[14:17], v[224:227], v[196:199], v[14:17]
	v_mfma_f32_16x16x32_bf16 v[10:13], v[232:235], v[196:199], v[10:13]
	v_mfma_f32_16x16x32_bf16 v[6:9], v[224:227], v[204:207], v[6:9]
	v_mfma_f32_16x16x32_bf16 v[2:5], v[232:235], v[204:207], v[2:5]
	s_barrier
	s_add_u32 s22, s22, 0x80000
	s_addc_u32 s23, s23, 0
	s_mov_b32 m0, s45
	v_lshl_add_u64 v[208:209], s[22:23], 0, v[136:137]
	ds_read_b128 v[164:167], v154 offset:32768
	ds_read_b128 v[168:171], v154 offset:33792
	ds_read_b128 v[172:175], v154 offset:34816
	ds_read_b128 v[176:179], v154 offset:35840
	ds_read_b128 v[192:195], v154 offset:36864
	ds_read_b128 v[196:199], v154 offset:37888
	ds_read_b128 v[200:203], v154 offset:38912
	ds_read_b128 v[204:207], v154 offset:39936
	global_load_lds_dwordx4 v[208:209], off
	v_lshl_add_u64 v[208:209], s[22:23], 0, v[132:133]
	s_mov_b32 m0, s46
	s_nop 0
	global_load_lds_dwordx4 v[208:209], off
	s_waitcnt lgkmcnt(8)
	s_barrier
	s_waitcnt lgkmcnt(0)
	v_mfma_f32_16x16x32_bf16 v[126:129], v[144:147], v[164:167], v[126:129]
	v_mfma_f32_16x16x32_bf16 v[122:125], v[156:159], v[164:167], v[122:125]
	v_mfma_f32_16x16x32_bf16 v[118:121], v[144:147], v[172:175], v[118:121]
	v_mfma_f32_16x16x32_bf16 v[114:117], v[156:159], v[172:175], v[114:117]
	v_mfma_f32_16x16x32_bf16 v[102:105], v[144:147], v[192:195], v[102:105]
	v_mfma_f32_16x16x32_bf16 v[98:101], v[156:159], v[192:195], v[98:101]
	v_mfma_f32_16x16x32_bf16 v[86:89], v[144:147], v[200:203], v[86:89]
	v_mfma_f32_16x16x32_bf16 v[82:85], v[156:159], v[200:203], v[82:85]
	v_mfma_f32_16x16x32_bf16 v[126:129], v[148:151], v[168:171], v[126:129]
	v_mfma_f32_16x16x32_bf16 v[122:125], v[160:163], v[168:171], v[122:125]
	v_mfma_f32_16x16x32_bf16 v[118:121], v[148:151], v[176:179], v[118:121]
	v_mfma_f32_16x16x32_bf16 v[114:117], v[160:163], v[176:179], v[114:117]
	v_mfma_f32_16x16x32_bf16 v[102:105], v[148:151], v[196:199], v[102:105]
	v_mfma_f32_16x16x32_bf16 v[98:101], v[160:163], v[196:199], v[98:101]
	v_mfma_f32_16x16x32_bf16 v[86:89], v[148:151], v[204:207], v[86:89]
	v_mfma_f32_16x16x32_bf16 v[82:85], v[160:163], v[204:207], v[82:85]
	s_barrier
	s_add_i32 s22, 0, 0x1c000
	s_add_i32 s23, s56, s28
	v_add_u32_e32 v155, s22, v139
	v_lshl_add_u64 v[152:153], v[152:153], 0, s[78:79]
	s_mov_b32 m0, s23
	ds_read_b128 v[208:211], v155
	ds_read_b128 v[224:227], v155 offset:1024
	ds_read_b128 v[228:231], v155 offset:2048
	ds_read_b128 v[232:235], v155 offset:3072
	global_load_lds_dwordx4 v[152:153], off
	v_lshl_add_u64 v[152:153], v[212:213], 0, s[78:79]
	s_add_i32 m0, s23, 0x2000
	s_nop 0
	global_load_lds_dwordx4 v[152:153], off
	s_mov_b32 m0, s47
	v_lshl_add_u64 v[152:153], v[236:237], 0, s[78:79]
	s_waitcnt lgkmcnt(0)
	s_barrier
	v_mfma_f32_16x16x32_bf16 v[110:113], v[208:211], v[164:167], v[110:113]
	v_mfma_f32_16x16x32_bf16 v[106:109], v[228:231], v[164:167], v[106:109]
	v_mfma_f32_16x16x32_bf16 v[94:97], v[208:211], v[172:175], v[94:97]
	v_mfma_f32_16x16x32_bf16 v[90:93], v[228:231], v[172:175], v[90:93]
	v_mfma_f32_16x16x32_bf16 v[78:81], v[208:211], v[192:195], v[78:81]
	v_mfma_f32_16x16x32_bf16 v[74:77], v[228:231], v[192:195], v[74:77]
	v_mfma_f32_16x16x32_bf16 v[70:73], v[208:211], v[200:203], v[70:73]
	v_mfma_f32_16x16x32_bf16 v[66:69], v[228:231], v[200:203], v[66:69]
	v_mfma_f32_16x16x32_bf16 v[110:113], v[224:227], v[168:171], v[110:113]
	v_mfma_f32_16x16x32_bf16 v[106:109], v[232:235], v[168:171], v[106:109]
	v_mfma_f32_16x16x32_bf16 v[94:97], v[224:227], v[176:179], v[94:97]
	v_mfma_f32_16x16x32_bf16 v[90:93], v[232:235], v[176:179], v[90:93]
	v_mfma_f32_16x16x32_bf16 v[78:81], v[224:227], v[196:199], v[78:81]
	v_mfma_f32_16x16x32_bf16 v[74:77], v[232:235], v[196:199], v[74:77]
	v_mfma_f32_16x16x32_bf16 v[70:73], v[224:227], v[204:207], v[70:73]
	v_mfma_f32_16x16x32_bf16 v[66:69], v[232:235], v[204:207], v[66:69]
	s_barrier
	ds_read_b128 v[164:167], v154 offset:49152
	ds_read_b128 v[168:171], v154 offset:50176
	ds_read_b128 v[172:175], v154 offset:51200
	ds_read_b128 v[176:179], v154 offset:52224
	ds_read_b128 v[192:195], v154 offset:53248
	ds_read_b128 v[196:199], v154 offset:54272
	ds_read_b128 v[200:203], v154 offset:55296
	ds_read_b128 v[204:207], v154 offset:56320
	global_load_lds_dwordx4 v[152:153], off
	v_lshl_add_u64 v[152:153], v[238:239], 0, s[78:79]
	s_mov_b32 m0, s48
	s_nop 0
	global_load_lds_dwordx4 v[152:153], off
	s_waitcnt vmcnt(10)
	s_barrier
	s_waitcnt lgkmcnt(0)
	v_mfma_f32_16x16x32_bf16 v[62:65], v[144:147], v[164:167], v[62:65]
	v_mfma_f32_16x16x32_bf16 v[58:61], v[156:159], v[164:167], v[58:61]
	v_mfma_f32_16x16x32_bf16 v[54:57], v[144:147], v[172:175], v[54:57]
	v_mfma_f32_16x16x32_bf16 v[50:53], v[156:159], v[172:175], v[50:53]
	v_mfma_f32_16x16x32_bf16 v[38:41], v[144:147], v[192:195], v[38:41]
	v_mfma_f32_16x16x32_bf16 v[34:37], v[156:159], v[192:195], v[34:37]
	v_mfma_f32_16x16x32_bf16 v[22:25], v[144:147], v[200:203], v[22:25]
	v_mfma_f32_16x16x32_bf16 v[18:21], v[156:159], v[200:203], v[18:21]
	v_mfma_f32_16x16x32_bf16 v[62:65], v[148:151], v[168:171], v[62:65]
	v_mfma_f32_16x16x32_bf16 v[58:61], v[160:163], v[168:171], v[58:61]
	v_mfma_f32_16x16x32_bf16 v[54:57], v[148:151], v[176:179], v[54:57]
	v_mfma_f32_16x16x32_bf16 v[50:53], v[160:163], v[176:179], v[50:53]
	v_mfma_f32_16x16x32_bf16 v[38:41], v[148:151], v[196:199], v[38:41]
	v_mfma_f32_16x16x32_bf16 v[34:37], v[160:163], v[196:199], v[34:37]
	v_mfma_f32_16x16x32_bf16 v[22:25], v[148:151], v[204:207], v[22:25]
	v_mfma_f32_16x16x32_bf16 v[18:21], v[160:163], v[204:207], v[18:21]
	s_barrier
	s_add_u32 s20, s20, 0x80080
	s_addc_u32 s21, s21, 0
	s_add_i32 s22, s22, s28
	v_lshl_add_u64 v[144:145], s[20:21], 0, v[134:135]
	s_mov_b32 m0, s22
	s_nop 0
	global_load_lds_dwordx4 v[144:145], off
	v_lshl_add_u64 v[144:145], s[20:21], 0, v[130:131]
	s_add_i32 m0, s22, 0x2000
	s_nop 0
	global_load_lds_dwordx4 v[144:145], off
	v_add_u32_e32 v152, 0x10000, v139
	ds_read_b128 v[144:147], v152
	ds_read_b128 v[148:151], v152 offset:1024
	ds_read_b128 v[156:159], v152 offset:2048
	ds_read_b128 v[160:163], v152 offset:3072
	s_add_i32 s55, s55, 2
	s_add_u32 s18, s18, 0x100
	s_addc_u32 s19, s19, 0
	s_add_u32 s53, s53, 0x100
	s_addc_u32 s54, s54, 0
	s_cmp_gt_u32 s55, 29
	s_waitcnt vmcnt(6)
	s_barrier
	v_mfma_f32_16x16x32_bf16 v[46:49], v[208:211], v[164:167], v[46:49]
	v_mfma_f32_16x16x32_bf16 v[42:45], v[228:231], v[164:167], v[42:45]
	v_mfma_f32_16x16x32_bf16 v[30:33], v[208:211], v[172:175], v[30:33]
	v_mfma_f32_16x16x32_bf16 v[26:29], v[228:231], v[172:175], v[26:29]
	v_mfma_f32_16x16x32_bf16 v[14:17], v[208:211], v[192:195], v[14:17]
	v_mfma_f32_16x16x32_bf16 v[10:13], v[228:231], v[192:195], v[10:13]
	v_mfma_f32_16x16x32_bf16 v[6:9], v[208:211], v[200:203], v[6:9]
	v_mfma_f32_16x16x32_bf16 v[2:5], v[228:231], v[200:203], v[2:5]
	v_mfma_f32_16x16x32_bf16 v[46:49], v[224:227], v[168:171], v[46:49]
	v_mfma_f32_16x16x32_bf16 v[42:45], v[232:235], v[168:171], v[42:45]
	v_mfma_f32_16x16x32_bf16 v[30:33], v[224:227], v[176:179], v[30:33]
	v_mfma_f32_16x16x32_bf16 v[26:29], v[232:235], v[176:179], v[26:29]
	v_mfma_f32_16x16x32_bf16 v[14:17], v[224:227], v[196:199], v[14:17]
	v_mfma_f32_16x16x32_bf16 v[10:13], v[232:235], v[196:199], v[10:13]
	v_mfma_f32_16x16x32_bf16 v[6:9], v[224:227], v[204:207], v[6:9]
	v_mfma_f32_16x16x32_bf16 v[2:5], v[232:235], v[204:207], v[2:5]
	s_barrier
	s_cbranch_scc0 .LBB0_526
	s_waitcnt lgkmcnt(0)
	v_lshl_add_u32 v152, s36, 8, v1
	v_or_b32_e32 v150, 16, v152
	v_or_b32_e32 v148, 32, v152
	v_or_b32_e32 v146, 48, v152
	s_mov_b64 s[18:19], -1
	s_cmp_lt_i32 s50, 8
	v_ashrrev_i32_e32 v153, 31, v152
	v_lshlrev_b32_e32 v144, 1, v138
	v_ashrrev_i32_e32 v151, 31, v150
	v_ashrrev_i32_e32 v149, 31, v148
	v_ashrrev_i32_e32 v147, 31, v146
	s_cbranch_scc1 .LBB0_529
	s_lshl_b32 s18, s50, 7
	s_add_i32 s36, s18, 0xfffffc00
	v_lshlrev_b64 v[156:157], 12, v[152:153]
	v_lshl_add_u64 v[156:157], s[72:73], 0, v[156:157]
	s_lshl_b64 s[18:19], s[36:37], 1
	v_lshl_add_u64 v[156:157], v[156:157], 0, s[18:19]
	v_mov_b32_e32 v145, v0
	v_lshl_add_u64 v[160:161], v[156:157], 0, v[144:145]
	v_pk_mul_f32 v[158:159], v[128:129], v[112:113]
	v_pk_mul_f32 v[156:157], v[126:127], v[110:111]
	v_pk_mul_f32 v[162:163], v[124:125], v[108:109]
	v_pk_mul_f32 v[164:165], v[122:123], v[106:107]
	v_cvt_pk_bf16_f32 v156, v156, v157
	v_cvt_pk_bf16_f32 v157, v158, v159
	v_cvt_pk_bf16_f32 v158, v164, v165
	v_cvt_pk_bf16_f32 v159, v162, v163
	global_store_dwordx4 v[160:161], v[156:159], off
	v_pk_mul_f32 v[164:165], v[116:117], v[92:93]
	v_pk_mul_f32 v[166:167], v[114:115], v[90:91]
	v_lshlrev_b64 v[156:157], 12, v[150:151]
	v_lshl_add_u64 v[156:157], s[72:73], 0, v[156:157]
	v_lshl_add_u64 v[156:157], v[156:157], 0, s[18:19]
	v_lshl_add_u64 v[162:163], v[156:157], 0, v[144:145]
	v_pk_mul_f32 v[158:159], v[120:121], v[96:97]
	v_pk_mul_f32 v[156:157], v[118:119], v[94:95]
	s_nop 0
	v_cvt_pk_bf16_f32 v156, v156, v157
	v_cvt_pk_bf16_f32 v157, v158, v159
	v_cvt_pk_bf16_f32 v158, v166, v167
	v_cvt_pk_bf16_f32 v159, v164, v165
	global_store_dwordx4 v[162:163], v[156:159], off
	v_pk_mul_f32 v[164:165], v[100:101], v[76:77]
	v_pk_mul_f32 v[166:167], v[98:99], v[74:75]
	v_lshlrev_b64 v[156:157], 12, v[148:149]
	v_lshl_add_u64 v[156:157], s[72:73], 0, v[156:157]
	v_lshl_add_u64 v[156:157], v[156:157], 0, s[18:19]
	v_lshl_add_u64 v[162:163], v[156:157], 0, v[144:145]
	v_pk_mul_f32 v[158:159], v[104:105], v[80:81]
	v_pk_mul_f32 v[156:157], v[102:103], v[78:79]
	s_nop 0
	v_cvt_pk_bf16_f32 v156, v156, v157
	v_cvt_pk_bf16_f32 v157, v158, v159
	v_cvt_pk_bf16_f32 v158, v166, v167
	v_cvt_pk_bf16_f32 v159, v164, v165
	global_store_dwordx4 v[162:163], v[156:159], off
	v_pk_mul_f32 v[164:165], v[84:85], v[68:69]
	v_pk_mul_f32 v[166:167], v[82:83], v[66:67]
	v_lshlrev_b64 v[156:157], 12, v[146:147]
	v_lshl_add_u64 v[156:157], s[72:73], 0, v[156:157]
	v_lshl_add_u64 v[156:157], v[156:157], 0, s[18:19]
	v_lshl_add_u64 v[162:163], v[156:157], 0, v[144:145]
	v_pk_mul_f32 v[158:159], v[88:89], v[72:73]
	v_pk_mul_f32 v[156:157], v[86:87], v[70:71]
	s_mov_b32 s18, 0x80000
	v_cvt_pk_bf16_f32 v156, v156, v157
	v_cvt_pk_bf16_f32 v157, v158, v159
	v_cvt_pk_bf16_f32 v158, v166, v167
	v_cvt_pk_bf16_f32 v159, v164, v165
	global_store_dwordx4 v[162:163], v[156:159], off
	v_pk_mul_f32 v[162:163], v[60:61], v[44:45]
	v_pk_mul_f32 v[164:165], v[58:59], v[42:43]
	v_pk_mul_f32 v[158:159], v[64:65], v[48:49]
	v_pk_mul_f32 v[156:157], v[62:63], v[46:47]
	s_nop 0
	v_cvt_pk_bf16_f32 v156, v156, v157
	v_cvt_pk_bf16_f32 v157, v158, v159
	v_cvt_pk_bf16_f32 v159, v162, v163
	v_add_co_u32_e32 v162, vcc, s18, v160
	v_cvt_pk_bf16_f32 v158, v164, v165
	s_nop 0
	v_addc_co_u32_e32 v163, vcc, 0, v161, vcc
	global_store_dwordx4 v[162:163], v[156:159], off
	v_pk_mul_f32 v[162:163], v[52:53], v[28:29]
	s_mov_b32 s18, 0x90000
	v_pk_mul_f32 v[158:159], v[56:57], v[32:33]
	v_pk_mul_f32 v[156:157], v[54:55], v[30:31]
	v_pk_mul_f32 v[164:165], v[50:51], v[26:27]
	v_cvt_pk_bf16_f32 v156, v156, v157
	v_cvt_pk_bf16_f32 v157, v158, v159
	v_cvt_pk_bf16_f32 v159, v162, v163
	v_add_co_u32_e32 v162, vcc, s18, v160
	v_cvt_pk_bf16_f32 v158, v164, v165
	s_nop 0
	v_addc_co_u32_e32 v163, vcc, 0, v161, vcc
	global_store_dwordx4 v[162:163], v[156:159], off
	v_pk_mul_f32 v[162:163], v[36:37], v[12:13]
	s_mov_b32 s18, 0xa0000
	v_pk_mul_f32 v[158:159], v[40:41], v[16:17]
	v_pk_mul_f32 v[156:157], v[38:39], v[14:15]
	v_pk_mul_f32 v[164:165], v[34:35], v[10:11]
	v_cvt_pk_bf16_f32 v156, v156, v157
	v_cvt_pk_bf16_f32 v157, v158, v159
	v_cvt_pk_bf16_f32 v159, v162, v163
	v_add_co_u32_e32 v162, vcc, s18, v160
	v_cvt_pk_bf16_f32 v158, v164, v165
	s_nop 0
	v_addc_co_u32_e32 v163, vcc, 0, v161, vcc
	global_store_dwordx4 v[162:163], v[156:159], off
	v_pk_mul_f32 v[162:163], v[20:21], v[4:5]
	v_pk_mul_f32 v[164:165], v[18:19], v[2:3]
	v_pk_mul_f32 v[158:159], v[24:25], v[8:9]
	v_pk_mul_f32 v[156:157], v[22:23], v[6:7]
	v_add_co_u32_e32 v160, vcc, 0xb0000, v160
	v_cvt_pk_bf16_f32 v156, v156, v157
	v_cvt_pk_bf16_f32 v157, v158, v159
	v_cvt_pk_bf16_f32 v158, v164, v165
	v_cvt_pk_bf16_f32 v159, v162, v163
	v_addc_co_u32_e32 v161, vcc, 0, v161, vcc
	s_mov_b64 s[18:19], 0
	global_store_dwordx4 v[160:161], v[156:159], off

.LBB0_649:
	s_add_u32 s18, s38, vcc_lo
	s_addc_u32 s19, s39, vcc_hi
	s_add_u32 s18, s18, 0x100
	s_addc_u32 s19, s19, 0
	s_add_u32 s57, s50, vcc_lo
	s_addc_u32 s58, s51, vcc_hi
	s_add_i32 s59, 0, 0x10000
	s_cmpk_eq_i32 vcc_lo, 0xf00
	s_cselect_b32 s23, s52, s19
	s_cselect_b32 s22, s53, s18
	s_cselect_b32 s19, s54, s58
	s_cselect_b32 s18, s55, s57
	v_lshl_add_u64 v[162:163], v[142:143], 0, vcc
	s_add_i32 m0, s28, 0xc000
	ds_read_b128 v[170:173], v148
	ds_read_b128 v[174:177], v148 offset:1024
	ds_read_b128 v[192:195], v148 offset:2048
	ds_read_b128 v[196:199], v148 offset:3072
	ds_read_b128 v[200:203], v148 offset:4096
	ds_read_b128 v[204:207], v148 offset:5120
	ds_read_b128 v[208:211], v148 offset:6144
	ds_read_b128 v[224:227], v148 offset:7168
	global_load_lds_dwordx4 v[162:163], off
	v_lshl_add_u64 v[162:163], v[144:145], 0, vcc
	s_add_i32 m0, s28, 0xe000
	s_nop 0
	global_load_lds_dwordx4 v[162:163], off
	s_waitcnt lgkmcnt(8)
	s_barrier
	s_waitcnt lgkmcnt(0)
	v_mfma_f32_16x16x32_bf16 v[90:93], v[150:153], v[170:173], v[90:93]
	v_mfma_f32_16x16x32_bf16 v[94:97], v[158:161], v[170:173], v[94:97]
	v_mfma_f32_16x16x32_bf16 v[102:105], v[150:153], v[192:195], v[102:105]
	v_mfma_f32_16x16x32_bf16 v[106:109], v[158:161], v[192:195], v[106:109]
	v_mfma_f32_16x16x32_bf16 v[114:117], v[150:153], v[200:203], v[114:117]
	v_mfma_f32_16x16x32_bf16 v[118:121], v[158:161], v[200:203], v[118:121]
	v_mfma_f32_16x16x32_bf16 v[122:125], v[150:153], v[208:211], v[122:125]
	v_mfma_f32_16x16x32_bf16 v[126:129], v[158:161], v[208:211], v[126:129]
	v_mfma_f32_16x16x32_bf16 v[90:93], v[154:157], v[174:177], v[90:93]
	v_mfma_f32_16x16x32_bf16 v[94:97], v[166:169], v[174:177], v[94:97]
	v_mfma_f32_16x16x32_bf16 v[102:105], v[154:157], v[196:199], v[102:105]
	v_mfma_f32_16x16x32_bf16 v[106:109], v[166:169], v[196:199], v[106:109]
	v_mfma_f32_16x16x32_bf16 v[114:117], v[154:157], v[204:207], v[114:117]
	v_mfma_f32_16x16x32_bf16 v[118:121], v[166:169], v[204:207], v[118:121]
	v_mfma_f32_16x16x32_bf16 v[122:125], v[154:157], v[224:227], v[122:125]
	v_mfma_f32_16x16x32_bf16 v[126:129], v[166:169], v[224:227], v[126:129]
	s_barrier
	s_add_i32 s57, 0, 0x14000
	s_add_i32 s58, s59, s85
	v_add_u32_e32 v149, s57, v147
	v_lshl_add_u64 v[162:163], s[18:19], 0, v[134:135]
	s_mov_b32 m0, s58
	ds_read_b128 v[228:231], v149
	ds_read_b128 v[232:235], v149 offset:1024
	ds_read_b128 v[236:239], v149 offset:2048
	ds_read_b128 v[240:243], v149 offset:3072
	global_load_lds_dwordx4 v[162:163], off
	v_lshl_add_u64 v[178:179], s[18:19], 0, v[130:131]
	s_add_i32 m0, s58, 0x2000
	s_nop 0
	global_load_lds_dwordx4 v[178:179], off
	s_mov_b32 m0, s28
	v_lshl_add_u64 v[212:213], s[22:23], 0, v[136:137]
	s_waitcnt lgkmcnt(0)
	s_barrier
	v_mfma_f32_16x16x32_bf16 v[10:13], v[228:231], v[170:173], v[10:13]
	v_mfma_f32_16x16x32_bf16 v[14:17], v[236:239], v[170:173], v[14:17]
	v_mfma_f32_16x16x32_bf16 v[26:29], v[228:231], v[192:195], v[26:29]
	v_mfma_f32_16x16x32_bf16 v[38:41], v[236:239], v[192:195], v[38:41]
	v_mfma_f32_16x16x32_bf16 v[58:61], v[228:231], v[200:203], v[58:61]
	v_mfma_f32_16x16x32_bf16 v[62:65], v[236:239], v[200:203], v[62:65]
	v_mfma_f32_16x16x32_bf16 v[74:77], v[228:231], v[208:211], v[74:77]
	v_mfma_f32_16x16x32_bf16 v[78:81], v[236:239], v[208:211], v[78:81]
	v_mfma_f32_16x16x32_bf16 v[10:13], v[232:235], v[174:177], v[10:13]
	v_mfma_f32_16x16x32_bf16 v[14:17], v[240:243], v[174:177], v[14:17]
	v_mfma_f32_16x16x32_bf16 v[26:29], v[232:235], v[196:199], v[26:29]
	v_mfma_f32_16x16x32_bf16 v[38:41], v[240:243], v[196:199], v[38:41]
	v_mfma_f32_16x16x32_bf16 v[58:61], v[232:235], v[204:207], v[58:61]
	v_mfma_f32_16x16x32_bf16 v[62:65], v[240:243], v[204:207], v[62:65]
	v_mfma_f32_16x16x32_bf16 v[74:77], v[232:235], v[224:227], v[74:77]
	v_mfma_f32_16x16x32_bf16 v[78:81], v[240:243], v[224:227], v[78:81]
	s_barrier
	ds_read_b128 v[170:173], v148 offset:16384
	ds_read_b128 v[174:177], v148 offset:17408
	ds_read_b128 v[192:195], v148 offset:18432
	ds_read_b128 v[196:199], v148 offset:19456
	ds_read_b128 v[200:203], v148 offset:20480
	ds_read_b128 v[204:207], v148 offset:21504
	ds_read_b128 v[208:211], v148 offset:22528
	ds_read_b128 v[224:227], v148 offset:23552
	global_load_lds_dwordx4 v[212:213], off
	v_lshl_add_u64 v[244:245], s[22:23], 0, v[132:133]
	s_mov_b32 m0, s29
	s_nop 0
	global_load_lds_dwordx4 v[244:245], off
	s_waitcnt vmcnt(10)
	s_barrier
	s_waitcnt lgkmcnt(0)
	v_mfma_f32_16x16x32_bf16 v[110:113], v[150:153], v[170:173], v[110:113]
	v_mfma_f32_16x16x32_bf16 v[98:101], v[158:161], v[170:173], v[98:101]
	v_mfma_f32_16x16x32_bf16 v[82:85], v[150:153], v[192:195], v[82:85]
	v_mfma_f32_16x16x32_bf16 v[66:69], v[158:161], v[192:195], v[66:69]
	v_mfma_f32_16x16x32_bf16 v[50:53], v[150:153], v[200:203], v[50:53]
	v_mfma_f32_16x16x32_bf16 v[42:45], v[158:161], v[200:203], v[42:45]
	v_mfma_f32_16x16x32_bf16 v[30:33], v[150:153], v[208:211], v[30:33]
	v_mfma_f32_16x16x32_bf16 v[18:21], v[158:161], v[208:211], v[18:21]
	v_mfma_f32_16x16x32_bf16 v[110:113], v[154:157], v[174:177], v[110:113]
	v_mfma_f32_16x16x32_bf16 v[98:101], v[166:169], v[174:177], v[98:101]
	v_mfma_f32_16x16x32_bf16 v[82:85], v[154:157], v[196:199], v[82:85]
	v_mfma_f32_16x16x32_bf16 v[66:69], v[166:169], v[196:199], v[66:69]
	v_mfma_f32_16x16x32_bf16 v[50:53], v[154:157], v[204:207], v[50:53]
	v_mfma_f32_16x16x32_bf16 v[42:45], v[166:169], v[204:207], v[42:45]
	v_mfma_f32_16x16x32_bf16 v[30:33], v[154:157], v[224:227], v[30:33]
	v_mfma_f32_16x16x32_bf16 v[18:21], v[166:169], v[224:227], v[18:21]
	s_barrier
	s_add_u32 s58, s18, 0x80000
	s_addc_u32 s59, s19, 0
	s_add_i32 s57, s57, s85
	v_lshl_add_u64 v[150:151], s[58:59], 0, v[134:135]
	s_mov_b32 m0, s57
	s_nop 0
	global_load_lds_dwordx4 v[150:151], off
	v_lshl_add_u64 v[150:151], s[58:59], 0, v[130:131]
	s_add_i32 m0, s57, 0x2000
	s_nop 0
	global_load_lds_dwordx4 v[150:151], off
	v_add_u32_e32 v149, 0x18000, v147
	ds_read_b128 v[150:153], v149
	ds_read_b128 v[154:157], v149 offset:1024
	ds_read_b128 v[158:161], v149 offset:2048
	ds_read_b128 v[166:169], v149 offset:3072
	s_add_i32 s57, 0, 0x18000
	s_waitcnt vmcnt(6)
	s_barrier
	v_mfma_f32_16x16x32_bf16 v[86:89], v[228:231], v[170:173], v[86:89]
	v_mfma_f32_16x16x32_bf16 v[70:73], v[236:239], v[170:173], v[70:73]
	v_mfma_f32_16x16x32_bf16 v[54:57], v[228:231], v[192:195], v[54:57]
	v_mfma_f32_16x16x32_bf16 v[46:49], v[236:239], v[192:195], v[46:49]
	v_mfma_f32_16x16x32_bf16 v[34:37], v[228:231], v[200:203], v[34:37]
	v_mfma_f32_16x16x32_bf16 v[22:25], v[236:239], v[200:203], v[22:25]
	v_mfma_f32_16x16x32_bf16 v[6:9], v[228:231], v[208:211], v[6:9]
	v_mfma_f32_16x16x32_bf16 v[2:5], v[236:239], v[208:211], v[2:5]
	v_mfma_f32_16x16x32_bf16 v[86:89], v[232:235], v[174:177], v[86:89]
	v_mfma_f32_16x16x32_bf16 v[70:73], v[240:243], v[174:177], v[70:73]
	v_mfma_f32_16x16x32_bf16 v[54:57], v[232:235], v[196:199], v[54:57]
	v_mfma_f32_16x16x32_bf16 v[46:49], v[240:243], v[196:199], v[46:49]
	v_mfma_f32_16x16x32_bf16 v[34:37], v[232:235], v[204:207], v[34:37]
	v_mfma_f32_16x16x32_bf16 v[22:25], v[240:243], v[204:207], v[22:25]
	v_mfma_f32_16x16x32_bf16 v[6:9], v[232:235], v[224:227], v[6:9]
	v_mfma_f32_16x16x32_bf16 v[2:5], v[240:243], v[224:227], v[2:5]
	s_barrier
	s_add_u32 s22, s22, 0x80000
	s_addc_u32 s23, s23, 0
	s_mov_b32 m0, s97
	v_lshl_add_u64 v[228:229], s[22:23], 0, v[136:137]
	ds_read_b128 v[170:173], v148 offset:32768
	ds_read_b128 v[174:177], v148 offset:33792
	ds_read_b128 v[192:195], v148 offset:34816
	ds_read_b128 v[196:199], v148 offset:35840
	ds_read_b128 v[200:203], v148 offset:36864
	ds_read_b128 v[204:207], v148 offset:37888
	ds_read_b128 v[208:211], v148 offset:38912
	ds_read_b128 v[224:227], v148 offset:39936
	global_load_lds_dwordx4 v[228:229], off
	v_lshl_add_u64 v[228:229], s[22:23], 0, v[132:133]
	s_mov_b32 m0, s44
	s_nop 0
	global_load_lds_dwordx4 v[228:229], off
	s_waitcnt lgkmcnt(8)
	s_barrier
	s_waitcnt lgkmcnt(0)
	v_mfma_f32_16x16x32_bf16 v[90:93], v[150:153], v[170:173], v[90:93]
	v_mfma_f32_16x16x32_bf16 v[94:97], v[158:161], v[170:173], v[94:97]
	v_mfma_f32_16x16x32_bf16 v[102:105], v[150:153], v[192:195], v[102:105]
	v_mfma_f32_16x16x32_bf16 v[106:109], v[158:161], v[192:195], v[106:109]
	v_mfma_f32_16x16x32_bf16 v[114:117], v[150:153], v[200:203], v[114:117]
	v_mfma_f32_16x16x32_bf16 v[118:121], v[158:161], v[200:203], v[118:121]
	v_mfma_f32_16x16x32_bf16 v[122:125], v[150:153], v[208:211], v[122:125]
	v_mfma_f32_16x16x32_bf16 v[126:129], v[158:161], v[208:211], v[126:129]
	v_mfma_f32_16x16x32_bf16 v[90:93], v[154:157], v[174:177], v[90:93]
	v_mfma_f32_16x16x32_bf16 v[94:97], v[166:169], v[174:177], v[94:97]
	v_mfma_f32_16x16x32_bf16 v[102:105], v[154:157], v[196:199], v[102:105]
	v_mfma_f32_16x16x32_bf16 v[106:109], v[166:169], v[196:199], v[106:109]
	v_mfma_f32_16x16x32_bf16 v[114:117], v[154:157], v[204:207], v[114:117]
	v_mfma_f32_16x16x32_bf16 v[118:121], v[166:169], v[204:207], v[118:121]
	v_mfma_f32_16x16x32_bf16 v[122:125], v[154:157], v[224:227], v[122:125]
	v_mfma_f32_16x16x32_bf16 v[126:129], v[166:169], v[224:227], v[126:129]
	s_barrier
	s_add_i32 s22, 0, 0x1c000
	s_add_i32 s23, s57, s85
	v_add_u32_e32 v149, s22, v147
	v_lshl_add_u64 v[162:163], v[162:163], 0, s[78:79]
	s_mov_b32 m0, s23
	ds_read_b128 v[228:231], v149
	ds_read_b128 v[232:235], v149 offset:1024
	ds_read_b128 v[236:239], v149 offset:2048
	ds_read_b128 v[240:243], v149 offset:3072
	global_load_lds_dwordx4 v[162:163], off
	v_lshl_add_u64 v[162:163], v[178:179], 0, s[78:79]
	s_add_i32 m0, s23, 0x2000
	s_nop 0
	global_load_lds_dwordx4 v[162:163], off
	s_mov_b32 m0, s46
	v_lshl_add_u64 v[162:163], v[212:213], 0, s[78:79]
	s_waitcnt lgkmcnt(0)
	s_barrier
	v_mfma_f32_16x16x32_bf16 v[10:13], v[228:231], v[170:173], v[10:13]
	v_mfma_f32_16x16x32_bf16 v[14:17], v[236:239], v[170:173], v[14:17]
	v_mfma_f32_16x16x32_bf16 v[26:29], v[228:231], v[192:195], v[26:29]
	v_mfma_f32_16x16x32_bf16 v[38:41], v[236:239], v[192:195], v[38:41]
	v_mfma_f32_16x16x32_bf16 v[58:61], v[228:231], v[200:203], v[58:61]
	v_mfma_f32_16x16x32_bf16 v[62:65], v[236:239], v[200:203], v[62:65]
	v_mfma_f32_16x16x32_bf16 v[74:77], v[228:231], v[208:211], v[74:77]
	v_mfma_f32_16x16x32_bf16 v[78:81], v[236:239], v[208:211], v[78:81]
	v_mfma_f32_16x16x32_bf16 v[10:13], v[232:235], v[174:177], v[10:13]
	v_mfma_f32_16x16x32_bf16 v[14:17], v[240:243], v[174:177], v[14:17]
	v_mfma_f32_16x16x32_bf16 v[26:29], v[232:235], v[196:199], v[26:29]
	v_mfma_f32_16x16x32_bf16 v[38:41], v[240:243], v[196:199], v[38:41]
	v_mfma_f32_16x16x32_bf16 v[58:61], v[232:235], v[204:207], v[58:61]
	v_mfma_f32_16x16x32_bf16 v[62:65], v[240:243], v[204:207], v[62:65]
	v_mfma_f32_16x16x32_bf16 v[74:77], v[232:235], v[224:227], v[74:77]
	v_mfma_f32_16x16x32_bf16 v[78:81], v[240:243], v[224:227], v[78:81]
	s_barrier
	ds_read_b128 v[170:173], v148 offset:49152
	ds_read_b128 v[174:177], v148 offset:50176
	ds_read_b128 v[192:195], v148 offset:51200
	ds_read_b128 v[196:199], v148 offset:52224
	ds_read_b128 v[200:203], v148 offset:53248
	ds_read_b128 v[204:207], v148 offset:54272
	ds_read_b128 v[208:211], v148 offset:55296
	ds_read_b128 v[224:227], v148 offset:56320
	global_load_lds_dwordx4 v[162:163], off
	v_lshl_add_u64 v[162:163], v[244:245], 0, s[78:79]
	s_mov_b32 m0, s47
	s_nop 0
	global_load_lds_dwordx4 v[162:163], off
	s_waitcnt vmcnt(10)
	s_barrier
	s_waitcnt lgkmcnt(0)
	v_mfma_f32_16x16x32_bf16 v[110:113], v[150:153], v[170:173], v[110:113]
	v_mfma_f32_16x16x32_bf16 v[98:101], v[158:161], v[170:173], v[98:101]
	v_mfma_f32_16x16x32_bf16 v[82:85], v[150:153], v[192:195], v[82:85]
	v_mfma_f32_16x16x32_bf16 v[66:69], v[158:161], v[192:195], v[66:69]
	v_mfma_f32_16x16x32_bf16 v[50:53], v[150:153], v[200:203], v[50:53]
	v_mfma_f32_16x16x32_bf16 v[42:45], v[158:161], v[200:203], v[42:45]
	v_mfma_f32_16x16x32_bf16 v[30:33], v[150:153], v[208:211], v[30:33]
	v_mfma_f32_16x16x32_bf16 v[18:21], v[158:161], v[208:211], v[18:21]
	v_mfma_f32_16x16x32_bf16 v[110:113], v[154:157], v[174:177], v[110:113]
	v_mfma_f32_16x16x32_bf16 v[98:101], v[166:169], v[174:177], v[98:101]
	v_mfma_f32_16x16x32_bf16 v[82:85], v[154:157], v[196:199], v[82:85]
	v_mfma_f32_16x16x32_bf16 v[66:69], v[166:169], v[196:199], v[66:69]
	v_mfma_f32_16x16x32_bf16 v[50:53], v[154:157], v[204:207], v[50:53]
	v_mfma_f32_16x16x32_bf16 v[42:45], v[166:169], v[204:207], v[42:45]
	v_mfma_f32_16x16x32_bf16 v[30:33], v[154:157], v[224:227], v[30:33]
	v_mfma_f32_16x16x32_bf16 v[18:21], v[166:169], v[224:227], v[18:21]
	s_barrier
	s_add_u32 s18, s18, 0x80080
	s_addc_u32 s19, s19, 0
	s_add_i32 s22, s22, s85
	v_lshl_add_u64 v[150:151], s[18:19], 0, v[134:135]
	s_mov_b32 m0, s22
	s_nop 0
	global_load_lds_dwordx4 v[150:151], off
	v_lshl_add_u64 v[150:151], s[18:19], 0, v[130:131]
	s_add_i32 m0, s22, 0x2000
	s_nop 0
	global_load_lds_dwordx4 v[150:151], off
	v_add_u32_e32 v149, 0x10000, v147
	ds_read_b128 v[150:153], v149
	ds_read_b128 v[154:157], v149 offset:1024
	ds_read_b128 v[158:161], v149 offset:2048
	ds_read_b128 v[166:169], v149 offset:3072
	s_add_i32 s56, s56, 2
	s_add_u32 vcc_lo, vcc_lo, 0x100
	s_addc_u32 vcc_hi, vcc_hi, 0
	s_cmp_gt_u32 s56, 29
	s_waitcnt vmcnt(6)
	s_barrier
	v_mfma_f32_16x16x32_bf16 v[86:89], v[228:231], v[170:173], v[86:89]
	v_mfma_f32_16x16x32_bf16 v[70:73], v[236:239], v[170:173], v[70:73]
	v_mfma_f32_16x16x32_bf16 v[54:57], v[228:231], v[192:195], v[54:57]
	v_mfma_f32_16x16x32_bf16 v[46:49], v[236:239], v[192:195], v[46:49]
	v_mfma_f32_16x16x32_bf16 v[34:37], v[228:231], v[200:203], v[34:37]
	v_mfma_f32_16x16x32_bf16 v[22:25], v[236:239], v[200:203], v[22:25]
	v_mfma_f32_16x16x32_bf16 v[6:9], v[228:231], v[208:211], v[6:9]
	v_mfma_f32_16x16x32_bf16 v[2:5], v[236:239], v[208:211], v[2:5]
	v_mfma_f32_16x16x32_bf16 v[86:89], v[232:235], v[174:177], v[86:89]
	v_mfma_f32_16x16x32_bf16 v[70:73], v[240:243], v[174:177], v[70:73]
	v_mfma_f32_16x16x32_bf16 v[54:57], v[232:235], v[196:199], v[54:57]
	v_mfma_f32_16x16x32_bf16 v[46:49], v[240:243], v[196:199], v[46:49]
	v_mfma_f32_16x16x32_bf16 v[34:37], v[232:235], v[204:207], v[34:37]
	v_mfma_f32_16x16x32_bf16 v[22:25], v[240:243], v[204:207], v[22:25]
	v_mfma_f32_16x16x32_bf16 v[6:9], v[232:235], v[224:227], v[6:9]
	v_mfma_f32_16x16x32_bf16 v[2:5], v[240:243], v[224:227], v[2:5]
	s_barrier
	s_cbranch_scc0 .LBB0_649
	s_waitcnt lgkmcnt(0)
	s_add_u32 s18, s50, 0xffffff00
	s_addc_u32 s19, s51, -1
	s_andn2_b64 vcc, exec, s[42:43]
	s_cbranch_vccnz .LBB0_652
	v_mov_b32_e32 v2, 0
	s_mov_b32 s84, s80
	s_mov_b32 s25, s82
	s_mov_b64 s[38:39], s[20:21]
	s_mov_b32 s48, s49
	v_mov_b32_e32 v3, v2
	v_mov_b32_e32 v4, v2
	v_mov_b32_e32 v5, v2
	v_mov_b32_e32 v6, v2
	v_mov_b32_e32 v7, v2
	v_mov_b32_e32 v8, v2
	v_mov_b32_e32 v9, v2
	v_mov_b32_e32 v22, v2
	v_mov_b32_e32 v23, v2
	v_mov_b32_e32 v24, v2
	v_mov_b32_e32 v25, v2
	v_mov_b32_e32 v34, v2
	v_mov_b32_e32 v35, v2
	v_mov_b32_e32 v36, v2
	v_mov_b32_e32 v37, v2
	v_mov_b32_e32 v46, v2
	v_mov_b32_e32 v47, v2
	v_mov_b32_e32 v48, v2
	v_mov_b32_e32 v49, v2
	v_mov_b32_e32 v54, v2
	v_mov_b32_e32 v55, v2
	v_mov_b32_e32 v56, v2
	v_mov_b32_e32 v57, v2
	v_mov_b32_e32 v70, v2
	v_mov_b32_e32 v71, v2
	v_mov_b32_e32 v72, v2
	v_mov_b32_e32 v73, v2
	v_mov_b32_e32 v86, v2
	v_mov_b32_e32 v87, v2
	v_mov_b32_e32 v88, v2
	v_mov_b32_e32 v89, v2
	v_mov_b32_e32 v18, v2
	v_mov_b32_e32 v19, v2
	v_mov_b32_e32 v20, v2
	v_mov_b32_e32 v21, v2
	v_mov_b32_e32 v30, v2
	v_mov_b32_e32 v31, v2
	v_mov_b32_e32 v32, v2
	v_mov_b32_e32 v33, v2
	v_mov_b32_e32 v42, v2
	v_mov_b32_e32 v43, v2
	v_mov_b32_e32 v44, v2
	v_mov_b32_e32 v45, v2
	v_mov_b32_e32 v50, v2
	v_mov_b32_e32 v51, v2
	v_mov_b32_e32 v52, v2
	v_mov_b32_e32 v53, v2
	v_mov_b32_e32 v66, v2
	v_mov_b32_e32 v67, v2
	v_mov_b32_e32 v68, v2
	v_mov_b32_e32 v69, v2
	v_mov_b32_e32 v82, v2
	v_mov_b32_e32 v83, v2
	v_mov_b32_e32 v84, v2
	v_mov_b32_e32 v85, v2
	v_mov_b32_e32 v98, v2
	v_mov_b32_e32 v99, v2
	v_mov_b32_e32 v100, v2
	v_mov_b32_e32 v101, v2
	v_mov_b32_e32 v110, v2
	v_mov_b32_e32 v111, v2
	v_mov_b32_e32 v112, v2
	v_mov_b32_e32 v113, v2
	v_mov_b32_e32 v78, v2
	v_mov_b32_e32 v79, v2
	v_mov_b32_e32 v80, v2
	v_mov_b32_e32 v81, v2
	v_mov_b32_e32 v74, v2
	v_mov_b32_e32 v75, v2
	v_mov_b32_e32 v76, v2
	v_mov_b32_e32 v77, v2
	v_mov_b32_e32 v62, v2
	v_mov_b32_e32 v63, v2
	v_mov_b32_e32 v64, v2
	v_mov_b32_e32 v65, v2
	v_mov_b32_e32 v58, v2
	v_mov_b32_e32 v59, v2
	v_mov_b32_e32 v60, v2
	v_mov_b32_e32 v61, v2
	v_mov_b32_e32 v38, v2
	v_mov_b32_e32 v39, v2
	v_mov_b32_e32 v40, v2
	v_mov_b32_e32 v41, v2
	v_mov_b32_e32 v26, v2
	v_mov_b32_e32 v27, v2
	v_mov_b32_e32 v28, v2
	v_mov_b32_e32 v29, v2
	v_mov_b32_e32 v14, v2
	v_mov_b32_e32 v15, v2
	v_mov_b32_e32 v16, v2
	v_mov_b32_e32 v17, v2
	v_mov_b32_e32 v10, v2
	v_mov_b32_e32 v11, v2
	v_mov_b32_e32 v12, v2
	v_mov_b32_e32 v13, v2
	v_mov_b32_e32 v126, v2
	v_mov_b32_e32 v127, v2
	v_mov_b32_e32 v128, v2
	v_mov_b32_e32 v129, v2
	v_mov_b32_e32 v122, v2
	v_mov_b32_e32 v123, v2
	v_mov_b32_e32 v124, v2
	v_mov_b32_e32 v125, v2
	v_mov_b32_e32 v118, v2
	v_mov_b32_e32 v119, v2
	v_mov_b32_e32 v120, v2
	v_mov_b32_e32 v121, v2
	v_mov_b32_e32 v114, v2
	v_mov_b32_e32 v115, v2
	v_mov_b32_e32 v116, v2
	v_mov_b32_e32 v117, v2
	v_mov_b32_e32 v106, v2
	v_mov_b32_e32 v107, v2
	v_mov_b32_e32 v108, v2
	v_mov_b32_e32 v109, v2
	v_mov_b32_e32 v102, v2
	v_mov_b32_e32 v103, v2
	v_mov_b32_e32 v104, v2
	v_mov_b32_e32 v105, v2
	v_mov_b32_e32 v94, v2
	v_mov_b32_e32 v95, v2
	v_mov_b32_e32 v96, v2
	v_mov_b32_e32 v97, v2
	v_mov_b32_e32 v90, v2
	v_mov_b32_e32 v91, v2
	v_mov_b32_e32 v92, v2
	v_mov_b32_e32 v93, v2
	s_andn2_b64 vcc, exec, s[0:1]
	s_cbranch_vccnz .LBB0_653
	s_branch .LBB0_654

.LBB0_749:
	s_add_u32 s20, s18, 0xfff80080
	s_addc_u32 s21, s19, -1
	s_add_i32 s58, 0, 0x10000
	s_cmp_eq_u32 s57, 28
	s_cselect_b32 s23, s39, s21
	s_cselect_b32 s22, s53, s20
	s_cselect_b32 s21, s31, s56
	s_cselect_b32 s20, s54, s55
	v_lshl_add_u64 v[212:213], s[18:19], 0, v[154:155]
	s_add_i32 m0, s44, 0xc000
	ds_read_b128 v[176:179], v158
	ds_read_b128 v[192:195], v158 offset:1024
	ds_read_b128 v[196:199], v158 offset:2048
	ds_read_b128 v[200:203], v158 offset:3072
	ds_read_b128 v[204:207], v158 offset:4096
	ds_read_b128 v[208:211], v158 offset:5120
	ds_read_b128 v[224:227], v158 offset:6144
	ds_read_b128 v[228:231], v158 offset:7168
	global_load_lds_dwordx4 v[212:213], off
	v_lshl_add_u64 v[212:213], s[18:19], 0, v[156:157]
	s_add_i32 m0, s44, 0xe000
	s_nop 0
	global_load_lds_dwordx4 v[212:213], off
	s_waitcnt lgkmcnt(8)
	s_barrier
	s_waitcnt lgkmcnt(0)
	v_mfma_f32_16x16x32_bf16 v[126:129], v[160:163], v[176:179], v[126:129]
	v_mfma_f32_16x16x32_bf16 v[122:125], v[168:171], v[176:179], v[122:125]
	v_mfma_f32_16x16x32_bf16 v[110:113], v[160:163], v[196:199], v[110:113]
	v_mfma_f32_16x16x32_bf16 v[106:109], v[168:171], v[196:199], v[106:109]
	v_mfma_f32_16x16x32_bf16 v[94:97], v[160:163], v[204:207], v[94:97]
	v_mfma_f32_16x16x32_bf16 v[90:93], v[168:171], v[204:207], v[90:93]
	v_mfma_f32_16x16x32_bf16 v[78:81], v[160:163], v[224:227], v[78:81]
	v_mfma_f32_16x16x32_bf16 v[74:77], v[168:171], v[224:227], v[74:77]
	v_mfma_f32_16x16x32_bf16 v[126:129], v[164:167], v[192:195], v[126:129]
	v_mfma_f32_16x16x32_bf16 v[122:125], v[172:175], v[192:195], v[122:125]
	v_mfma_f32_16x16x32_bf16 v[110:113], v[164:167], v[200:203], v[110:113]
	v_mfma_f32_16x16x32_bf16 v[106:109], v[172:175], v[200:203], v[106:109]
	v_mfma_f32_16x16x32_bf16 v[94:97], v[164:167], v[208:211], v[94:97]
	v_mfma_f32_16x16x32_bf16 v[90:93], v[172:175], v[208:211], v[90:93]
	v_mfma_f32_16x16x32_bf16 v[78:81], v[164:167], v[228:231], v[78:81]
	v_mfma_f32_16x16x32_bf16 v[74:77], v[172:175], v[228:231], v[74:77]
	s_barrier
	s_add_i32 s82, 0, 0x14000
	s_add_i32 s58, s58, s29
	v_add_u32_e32 v159, s82, v1
	v_lshl_add_u64 v[212:213], s[20:21], 0, v[134:135]
	s_mov_b32 m0, s58
	ds_read_b128 v[232:235], v159
	ds_read_b128 v[236:239], v159 offset:1024
	ds_read_b128 v[240:243], v159 offset:2048
	ds_read_b128 v[244:247], v159 offset:3072
	global_load_lds_dwordx4 v[212:213], off
	v_lshl_add_u64 v[248:249], s[20:21], 0, v[130:131]
	s_add_i32 m0, s58, 0x2000
	s_nop 0
	global_load_lds_dwordx4 v[248:249], off
	s_mov_b32 m0, s44
	v_lshl_add_u64 v[250:251], s[22:23], 0, v[136:137]
	s_waitcnt lgkmcnt(0)
	s_barrier
	v_mfma_f32_16x16x32_bf16 v[118:121], v[232:235], v[176:179], v[118:121]
	v_mfma_f32_16x16x32_bf16 v[114:117], v[240:243], v[176:179], v[114:117]
	v_mfma_f32_16x16x32_bf16 v[102:105], v[232:235], v[196:199], v[102:105]
	v_mfma_f32_16x16x32_bf16 v[98:101], v[240:243], v[196:199], v[98:101]
	v_mfma_f32_16x16x32_bf16 v[86:89], v[232:235], v[204:207], v[86:89]
	v_mfma_f32_16x16x32_bf16 v[82:85], v[240:243], v[204:207], v[82:85]
	v_mfma_f32_16x16x32_bf16 v[70:73], v[232:235], v[224:227], v[70:73]
	v_mfma_f32_16x16x32_bf16 v[66:69], v[240:243], v[224:227], v[66:69]
	v_mfma_f32_16x16x32_bf16 v[118:121], v[236:239], v[192:195], v[118:121]
	v_mfma_f32_16x16x32_bf16 v[114:117], v[244:247], v[192:195], v[114:117]
	v_mfma_f32_16x16x32_bf16 v[102:105], v[236:239], v[200:203], v[102:105]
	v_mfma_f32_16x16x32_bf16 v[98:101], v[244:247], v[200:203], v[98:101]
	v_mfma_f32_16x16x32_bf16 v[86:89], v[236:239], v[208:211], v[86:89]
	v_mfma_f32_16x16x32_bf16 v[82:85], v[244:247], v[208:211], v[82:85]
	v_mfma_f32_16x16x32_bf16 v[70:73], v[236:239], v[228:231], v[70:73]
	v_mfma_f32_16x16x32_bf16 v[66:69], v[244:247], v[228:231], v[66:69]
	s_barrier
	ds_read_b128 v[176:179], v158 offset:16384
	ds_read_b128 v[192:195], v158 offset:17408
	ds_read_b128 v[196:199], v158 offset:18432
	ds_read_b128 v[200:203], v158 offset:19456
	ds_read_b128 v[204:207], v158 offset:20480
	ds_read_b128 v[208:211], v158 offset:21504
	ds_read_b128 v[224:227], v158 offset:22528
	ds_read_b128 v[228:231], v158 offset:23552
	global_load_lds_dwordx4 v[250:251], off
	v_lshl_add_u64 v[222:223], s[22:23], 0, v[132:133]
	s_mov_b32 m0, s45
	s_nop 0
	global_load_lds_dwordx4 v[222:223], off
	s_waitcnt vmcnt(10)
	s_barrier
	s_waitcnt lgkmcnt(0)
	v_mfma_f32_16x16x32_bf16 v[62:65], v[160:163], v[176:179], v[62:65]
	v_mfma_f32_16x16x32_bf16 v[58:61], v[168:171], v[176:179], v[58:61]
	v_mfma_f32_16x16x32_bf16 v[46:49], v[160:163], v[196:199], v[46:49]
	v_mfma_f32_16x16x32_bf16 v[42:45], v[168:171], v[196:199], v[42:45]
	v_mfma_f32_16x16x32_bf16 v[30:33], v[160:163], v[204:207], v[30:33]
	v_mfma_f32_16x16x32_bf16 v[26:29], v[168:171], v[204:207], v[26:29]
	v_mfma_f32_16x16x32_bf16 v[14:17], v[160:163], v[224:227], v[14:17]
	v_mfma_f32_16x16x32_bf16 v[10:13], v[168:171], v[224:227], v[10:13]
	v_mfma_f32_16x16x32_bf16 v[62:65], v[164:167], v[192:195], v[62:65]
	v_mfma_f32_16x16x32_bf16 v[58:61], v[172:175], v[192:195], v[58:61]
	v_mfma_f32_16x16x32_bf16 v[46:49], v[164:167], v[200:203], v[46:49]
	v_mfma_f32_16x16x32_bf16 v[42:45], v[172:175], v[200:203], v[42:45]
	v_mfma_f32_16x16x32_bf16 v[30:33], v[164:167], v[208:211], v[30:33]
	v_mfma_f32_16x16x32_bf16 v[26:29], v[172:175], v[208:211], v[26:29]
	v_mfma_f32_16x16x32_bf16 v[14:17], v[164:167], v[228:231], v[14:17]
	v_mfma_f32_16x16x32_bf16 v[10:13], v[172:175], v[228:231], v[10:13]
	s_barrier
	s_add_u32 s58, s20, 0x80000
	s_addc_u32 s59, s21, 0
	s_add_i32 s82, s82, s29
	v_lshl_add_u64 v[160:161], s[58:59], 0, v[134:135]
	s_mov_b32 m0, s82
	s_nop 0
	global_load_lds_dwordx4 v[160:161], off
	v_lshl_add_u64 v[160:161], s[58:59], 0, v[130:131]
	s_add_i32 m0, s82, 0x2000
	s_nop 0
	global_load_lds_dwordx4 v[160:161], off
	v_add_u32_e32 v159, 0x18000, v1
	ds_read_b128 v[160:163], v159
	ds_read_b128 v[164:167], v159 offset:1024
	ds_read_b128 v[168:171], v159 offset:2048
	ds_read_b128 v[172:175], v159 offset:3072
	s_add_i32 s58, 0, 0x18000
	s_waitcnt vmcnt(6)
	s_barrier
	v_mfma_f32_16x16x32_bf16 v[54:57], v[232:235], v[176:179], v[54:57]
	v_mfma_f32_16x16x32_bf16 v[50:53], v[240:243], v[176:179], v[50:53]
	v_mfma_f32_16x16x32_bf16 v[38:41], v[232:235], v[196:199], v[38:41]
	v_mfma_f32_16x16x32_bf16 v[34:37], v[240:243], v[196:199], v[34:37]
	v_mfma_f32_16x16x32_bf16 v[22:25], v[232:235], v[204:207], v[22:25]
	v_mfma_f32_16x16x32_bf16 v[18:21], v[240:243], v[204:207], v[18:21]
	v_mfma_f32_16x16x32_bf16 v[6:9], v[232:235], v[224:227], v[6:9]
	v_mfma_f32_16x16x32_bf16 v[2:5], v[240:243], v[224:227], v[2:5]
	v_mfma_f32_16x16x32_bf16 v[54:57], v[236:239], v[192:195], v[54:57]
	v_mfma_f32_16x16x32_bf16 v[50:53], v[244:247], v[192:195], v[50:53]
	v_mfma_f32_16x16x32_bf16 v[38:41], v[236:239], v[200:203], v[38:41]
	v_mfma_f32_16x16x32_bf16 v[34:37], v[244:247], v[200:203], v[34:37]
	v_mfma_f32_16x16x32_bf16 v[22:25], v[236:239], v[208:211], v[22:25]
	v_mfma_f32_16x16x32_bf16 v[18:21], v[244:247], v[208:211], v[18:21]
	v_mfma_f32_16x16x32_bf16 v[6:9], v[236:239], v[228:231], v[6:9]
	v_mfma_f32_16x16x32_bf16 v[2:5], v[244:247], v[228:231], v[2:5]
	s_barrier
	s_add_u32 s22, s22, 0x80000
	s_addc_u32 s23, s23, 0
	s_mov_b32 m0, s46
	v_lshl_add_u64 v[232:233], s[22:23], 0, v[136:137]
	ds_read_b128 v[176:179], v158 offset:32768
	ds_read_b128 v[192:195], v158 offset:33792
	ds_read_b128 v[196:199], v158 offset:34816
	ds_read_b128 v[200:203], v158 offset:35840
	ds_read_b128 v[204:207], v158 offset:36864
	ds_read_b128 v[208:211], v158 offset:37888
	ds_read_b128 v[224:227], v158 offset:38912
	ds_read_b128 v[228:231], v158 offset:39936
	global_load_lds_dwordx4 v[232:233], off
	v_lshl_add_u64 v[232:233], s[22:23], 0, v[132:133]
	s_mov_b32 m0, s47
	s_nop 0
	global_load_lds_dwordx4 v[232:233], off
	s_waitcnt lgkmcnt(8)
	s_barrier
	s_waitcnt lgkmcnt(0)
	v_mfma_f32_16x16x32_bf16 v[126:129], v[160:163], v[176:179], v[126:129]
	v_mfma_f32_16x16x32_bf16 v[122:125], v[168:171], v[176:179], v[122:125]
	v_mfma_f32_16x16x32_bf16 v[110:113], v[160:163], v[196:199], v[110:113]
	v_mfma_f32_16x16x32_bf16 v[106:109], v[168:171], v[196:199], v[106:109]
	v_mfma_f32_16x16x32_bf16 v[94:97], v[160:163], v[204:207], v[94:97]
	v_mfma_f32_16x16x32_bf16 v[90:93], v[168:171], v[204:207], v[90:93]
	v_mfma_f32_16x16x32_bf16 v[78:81], v[160:163], v[224:227], v[78:81]
	v_mfma_f32_16x16x32_bf16 v[74:77], v[168:171], v[224:227], v[74:77]
	v_mfma_f32_16x16x32_bf16 v[126:129], v[164:167], v[192:195], v[126:129]
	v_mfma_f32_16x16x32_bf16 v[122:125], v[172:175], v[192:195], v[122:125]
	v_mfma_f32_16x16x32_bf16 v[110:113], v[164:167], v[200:203], v[110:113]
	v_mfma_f32_16x16x32_bf16 v[106:109], v[172:175], v[200:203], v[106:109]
	v_mfma_f32_16x16x32_bf16 v[94:97], v[164:167], v[208:211], v[94:97]
	v_mfma_f32_16x16x32_bf16 v[90:93], v[172:175], v[208:211], v[90:93]
	v_mfma_f32_16x16x32_bf16 v[78:81], v[164:167], v[228:231], v[78:81]
	v_mfma_f32_16x16x32_bf16 v[74:77], v[172:175], v[228:231], v[74:77]
	s_barrier
	s_add_i32 s22, 0, 0x1c000
	s_add_i32 s23, s58, s29
	v_add_u32_e32 v159, s22, v1
	v_lshl_add_u64 v[212:213], v[212:213], 0, s[78:79]
	s_mov_b32 m0, s23
	ds_read_b128 v[232:235], v159
	ds_read_b128 v[236:239], v159 offset:1024
	ds_read_b128 v[240:243], v159 offset:2048
	ds_read_b128 v[244:247], v159 offset:3072
	global_load_lds_dwordx4 v[212:213], off
	v_lshl_add_u64 v[212:213], v[248:249], 0, s[78:79]
	s_add_i32 m0, s23, 0x2000
	s_nop 0
	global_load_lds_dwordx4 v[212:213], off
	s_mov_b32 m0, s48
	v_lshl_add_u64 v[212:213], v[250:251], 0, s[78:79]
	s_waitcnt lgkmcnt(0)
	s_barrier
	v_mfma_f32_16x16x32_bf16 v[118:121], v[232:235], v[176:179], v[118:121]
	v_mfma_f32_16x16x32_bf16 v[114:117], v[240:243], v[176:179], v[114:117]
	v_mfma_f32_16x16x32_bf16 v[102:105], v[232:235], v[196:199], v[102:105]
	v_mfma_f32_16x16x32_bf16 v[98:101], v[240:243], v[196:199], v[98:101]
	v_mfma_f32_16x16x32_bf16 v[86:89], v[232:235], v[204:207], v[86:89]
	v_mfma_f32_16x16x32_bf16 v[82:85], v[240:243], v[204:207], v[82:85]
	v_mfma_f32_16x16x32_bf16 v[70:73], v[232:235], v[224:227], v[70:73]
	v_mfma_f32_16x16x32_bf16 v[66:69], v[240:243], v[224:227], v[66:69]
	v_mfma_f32_16x16x32_bf16 v[118:121], v[236:239], v[192:195], v[118:121]
	v_mfma_f32_16x16x32_bf16 v[114:117], v[244:247], v[192:195], v[114:117]
	v_mfma_f32_16x16x32_bf16 v[102:105], v[236:239], v[200:203], v[102:105]
	v_mfma_f32_16x16x32_bf16 v[98:101], v[244:247], v[200:203], v[98:101]
	v_mfma_f32_16x16x32_bf16 v[86:89], v[236:239], v[208:211], v[86:89]
	v_mfma_f32_16x16x32_bf16 v[82:85], v[244:247], v[208:211], v[82:85]
	v_mfma_f32_16x16x32_bf16 v[70:73], v[236:239], v[228:231], v[70:73]
	v_mfma_f32_16x16x32_bf16 v[66:69], v[244:247], v[228:231], v[66:69]
	s_barrier
	ds_read_b128 v[176:179], v158 offset:49152
	ds_read_b128 v[192:195], v158 offset:50176
	ds_read_b128 v[196:199], v158 offset:51200
	ds_read_b128 v[200:203], v158 offset:52224
	ds_read_b128 v[204:207], v158 offset:53248
	ds_read_b128 v[208:211], v158 offset:54272
	ds_read_b128 v[224:227], v158 offset:55296
	ds_read_b128 v[228:231], v158 offset:56320
	global_load_lds_dwordx4 v[212:213], off
	v_lshl_add_u64 v[212:213], v[222:223], 0, s[78:79]
	s_mov_b32 m0, s49
	s_nop 0
	global_load_lds_dwordx4 v[212:213], off
	s_waitcnt vmcnt(10)
	s_barrier
	s_waitcnt lgkmcnt(0)
	v_mfma_f32_16x16x32_bf16 v[62:65], v[160:163], v[176:179], v[62:65]
	v_mfma_f32_16x16x32_bf16 v[58:61], v[168:171], v[176:179], v[58:61]
	v_mfma_f32_16x16x32_bf16 v[46:49], v[160:163], v[196:199], v[46:49]
	v_mfma_f32_16x16x32_bf16 v[42:45], v[168:171], v[196:199], v[42:45]
	v_mfma_f32_16x16x32_bf16 v[30:33], v[160:163], v[204:207], v[30:33]
	v_mfma_f32_16x16x32_bf16 v[26:29], v[168:171], v[204:207], v[26:29]
	v_mfma_f32_16x16x32_bf16 v[14:17], v[160:163], v[224:227], v[14:17]
	v_mfma_f32_16x16x32_bf16 v[10:13], v[168:171], v[224:227], v[10:13]
	v_mfma_f32_16x16x32_bf16 v[62:65], v[164:167], v[192:195], v[62:65]
	v_mfma_f32_16x16x32_bf16 v[58:61], v[172:175], v[192:195], v[58:61]
	v_mfma_f32_16x16x32_bf16 v[46:49], v[164:167], v[200:203], v[46:49]
	v_mfma_f32_16x16x32_bf16 v[42:45], v[172:175], v[200:203], v[42:45]
	v_mfma_f32_16x16x32_bf16 v[30:33], v[164:167], v[208:211], v[30:33]
	v_mfma_f32_16x16x32_bf16 v[26:29], v[172:175], v[208:211], v[26:29]
	v_mfma_f32_16x16x32_bf16 v[14:17], v[164:167], v[228:231], v[14:17]
	v_mfma_f32_16x16x32_bf16 v[10:13], v[172:175], v[228:231], v[10:13]
	s_barrier
	s_add_u32 s20, s20, 0x80080
	s_addc_u32 s21, s21, 0
	s_add_i32 s22, s22, s29
	v_lshl_add_u64 v[160:161], s[20:21], 0, v[134:135]
	s_mov_b32 m0, s22
	s_nop 0
	global_load_lds_dwordx4 v[160:161], off
	v_lshl_add_u64 v[160:161], s[20:21], 0, v[130:131]
	s_add_i32 m0, s22, 0x2000
	s_nop 0
	global_load_lds_dwordx4 v[160:161], off
	v_add_u32_e32 v159, 0x10000, v1
	ds_read_b128 v[160:163], v159
	ds_read_b128 v[164:167], v159 offset:1024
	ds_read_b128 v[168:171], v159 offset:2048
	ds_read_b128 v[172:175], v159 offset:3072
	s_add_i32 s57, s57, 2
	s_add_u32 s18, s18, 0x100
	s_addc_u32 s19, s19, 0
	s_add_u32 s55, s55, 0x100
	s_addc_u32 s56, s56, 0
	s_cmp_gt_u32 s57, 29
	s_waitcnt vmcnt(6)
	s_barrier
	v_mfma_f32_16x16x32_bf16 v[54:57], v[232:235], v[176:179], v[54:57]
	v_mfma_f32_16x16x32_bf16 v[50:53], v[240:243], v[176:179], v[50:53]
	v_mfma_f32_16x16x32_bf16 v[38:41], v[232:235], v[196:199], v[38:41]
	v_mfma_f32_16x16x32_bf16 v[34:37], v[240:243], v[196:199], v[34:37]
	v_mfma_f32_16x16x32_bf16 v[22:25], v[232:235], v[204:207], v[22:25]
	v_mfma_f32_16x16x32_bf16 v[18:21], v[240:243], v[204:207], v[18:21]
	v_mfma_f32_16x16x32_bf16 v[6:9], v[232:235], v[224:227], v[6:9]
	v_mfma_f32_16x16x32_bf16 v[2:5], v[240:243], v[224:227], v[2:5]
	v_mfma_f32_16x16x32_bf16 v[54:57], v[236:239], v[192:195], v[54:57]
	v_mfma_f32_16x16x32_bf16 v[50:53], v[244:247], v[192:195], v[50:53]
	v_mfma_f32_16x16x32_bf16 v[38:41], v[236:239], v[200:203], v[38:41]
	v_mfma_f32_16x16x32_bf16 v[34:37], v[244:247], v[200:203], v[34:37]
	v_mfma_f32_16x16x32_bf16 v[22:25], v[236:239], v[208:211], v[22:25]
	v_mfma_f32_16x16x32_bf16 v[18:21], v[244:247], v[208:211], v[18:21]
	v_mfma_f32_16x16x32_bf16 v[6:9], v[236:239], v[228:231], v[6:9]
	v_mfma_f32_16x16x32_bf16 v[2:5], v[244:247], v[228:231], v[2:5]
	s_barrier
	s_cbranch_scc0 .LBB0_749
	s_waitcnt lgkmcnt(0)
	s_lshl_b32 s18, s52, 5
	s_add_i32 s18, s18, s51
	v_max_f32_e32 v122, 0, v122
	v_max_f32_e32 v123, 0, v123
	s_ashr_i32 s19, s18, 31
	v_pk_mul_f32 v[162:163], v[122:123], v[122:123]
	v_max_f32_e32 v123, v124, v124
	s_lshl_b64 s[18:19], s[18:19], 17
	v_max_f32_e32 v122, v128, v128
	v_max_f32_e32 v124, 0, v123
	v_max_f32_e32 v123, v129, v129
	s_add_u32 s18, s68, s18
	v_max_f32_e32 v126, 0, v126
	v_max_f32_e32 v127, 0, v127
	v_max_f32_e32 v122, 0, v122
	v_max_f32_e32 v123, 0, v123
	v_max_f32_e32 v125, 0, v125
	s_addc_u32 s19, s69, s19
	v_pk_mul_f32 v[126:127], v[126:127], v[126:127]
	v_pk_mul_f32 v[128:129], v[122:123], v[122:123]
	v_pk_mul_f32 v[164:165], v[124:125], v[124:125]
	v_lshl_add_u64 v[160:161], v[138:139], 1, s[18:19]
	v_cvt_pk_bf16_f32 v122, v126, v127
	v_cvt_pk_bf16_f32 v123, v128, v129
	v_cvt_pk_bf16_f32 v124, v162, v163
	v_cvt_pk_bf16_f32 v125, v164, v165
	v_max_f32_e32 v114, 0, v114
	v_max_f32_e32 v115, 0, v115
	global_store_dwordx4 v[160:161], v[122:125], off
	v_max_f32_e32 v118, v118, v118
	v_max_f32_e32 v119, v119, v119
	v_pk_mul_f32 v[122:123], v[114:115], v[114:115]
	v_max_f32_e32 v115, v116, v116
	v_max_f32_e32 v114, v120, v120
	v_max_f32_e32 v116, 0, v115
	v_max_f32_e32 v115, v121, v121
	v_max_f32_e32 v118, 0, v118
	v_max_f32_e32 v119, 0, v119
	v_max_f32_e32 v114, 0, v114
	v_max_f32_e32 v115, 0, v115
	v_max_f32_e32 v117, 0, v117
	v_pk_mul_f32 v[118:119], v[118:119], v[118:119]
	v_pk_mul_f32 v[120:121], v[114:115], v[114:115]
	v_pk_mul_f32 v[124:125], v[116:117], v[116:117]
	v_cvt_pk_bf16_f32 v114, v118, v119
	v_cvt_pk_bf16_f32 v115, v120, v121
	v_cvt_pk_bf16_f32 v116, v122, v123
	v_cvt_pk_bf16_f32 v117, v124, v125
	v_max_f32_e32 v106, 0, v106
	v_max_f32_e32 v107, 0, v107
	global_store_dwordx4 v[160:161], v[114:117], off offset:256
	v_max_f32_e32 v110, v110, v110
	v_max_f32_e32 v111, v111, v111
	v_pk_mul_f32 v[116:117], v[106:107], v[106:107]
	v_max_f32_e32 v107, v108, v108
	v_max_f32_e32 v106, v112, v112
	v_max_f32_e32 v108, 0, v107
	v_max_f32_e32 v107, v113, v113
	v_max_f32_e32 v110, 0, v110
	v_max_f32_e32 v111, 0, v111
	v_max_f32_e32 v106, 0, v106
	v_max_f32_e32 v107, 0, v107
	v_max_f32_e32 v109, 0, v109
	v_pk_mul_f32 v[110:111], v[110:111], v[110:111]
	v_pk_mul_f32 v[112:113], v[106:107], v[106:107]
	v_pk_mul_f32 v[118:119], v[108:109], v[108:109]
	v_lshl_add_u64 v[114:115], v[140:141], 1, s[18:19]
	v_cvt_pk_bf16_f32 v106, v110, v111
	v_cvt_pk_bf16_f32 v107, v112, v113
	v_cvt_pk_bf16_f32 v108, v116, v117
	v_cvt_pk_bf16_f32 v109, v118, v119
	v_max_f32_e32 v98, 0, v98
	v_max_f32_e32 v99, 0, v99
	global_store_dwordx4 v[114:115], v[106:109], off
	v_max_f32_e32 v102, v102, v102
	v_max_f32_e32 v103, v103, v103
	v_pk_mul_f32 v[106:107], v[98:99], v[98:99]
	v_max_f32_e32 v99, v100, v100
	v_max_f32_e32 v98, v104, v104
	v_max_f32_e32 v100, 0, v99
	v_max_f32_e32 v99, v105, v105
	v_max_f32_e32 v102, 0, v102
	v_max_f32_e32 v103, 0, v103
	v_max_f32_e32 v98, 0, v98
	v_max_f32_e32 v99, 0, v99
	v_max_f32_e32 v101, 0, v101
	v_pk_mul_f32 v[102:103], v[102:103], v[102:103]
	v_pk_mul_f32 v[104:105], v[98:99], v[98:99]
	v_pk_mul_f32 v[108:109], v[100:101], v[100:101]
	v_cvt_pk_bf16_f32 v98, v102, v103
	v_cvt_pk_bf16_f32 v99, v104, v105
	v_cvt_pk_bf16_f32 v100, v106, v107
	v_cvt_pk_bf16_f32 v101, v108, v109
	v_max_f32_e32 v90, 0, v90
	v_max_f32_e32 v91, 0, v91
	global_store_dwordx4 v[114:115], v[98:101], off offset:256
	v_max_f32_e32 v94, v94, v94
	v_max_f32_e32 v95, v95, v95
	v_pk_mul_f32 v[100:101], v[90:91], v[90:91]
	v_max_f32_e32 v91, v92, v92
	v_max_f32_e32 v90, v96, v96
	v_max_f32_e32 v92, 0, v91
	v_max_f32_e32 v91, v97, v97
	v_max_f32_e32 v94, 0, v94
	v_max_f32_e32 v95, 0, v95
	v_max_f32_e32 v90, 0, v90
	v_max_f32_e32 v91, 0, v91
	v_max_f32_e32 v93, 0, v93
	v_pk_mul_f32 v[94:95], v[94:95], v[94:95]
	v_pk_mul_f32 v[96:97], v[90:91], v[90:91]
	v_pk_mul_f32 v[102:103], v[92:93], v[92:93]
	v_lshl_add_u64 v[98:99], v[142:143], 1, s[18:19]
	v_cvt_pk_bf16_f32 v90, v94, v95
	v_cvt_pk_bf16_f32 v91, v96, v97
	v_cvt_pk_bf16_f32 v92, v100, v101
	v_cvt_pk_bf16_f32 v93, v102, v103
	v_max_f32_e32 v82, 0, v82
	v_max_f32_e32 v83, 0, v83
	global_store_dwordx4 v[98:99], v[90:93], off
	v_max_f32_e32 v86, v86, v86
	v_max_f32_e32 v87, v87, v87
	v_pk_mul_f32 v[90:91], v[82:83], v[82:83]
	v_max_f32_e32 v83, v84, v84
	v_max_f32_e32 v82, v88, v88
	v_max_f32_e32 v84, 0, v83
	v_max_f32_e32 v83, v89, v89
	v_max_f32_e32 v86, 0, v86
	v_max_f32_e32 v87, 0, v87
	v_max_f32_e32 v82, 0, v82
	v_max_f32_e32 v83, 0, v83
	v_max_f32_e32 v85, 0, v85
	v_pk_mul_f32 v[86:87], v[86:87], v[86:87]
	v_pk_mul_f32 v[88:89], v[82:83], v[82:83]
	v_pk_mul_f32 v[92:93], v[84:85], v[84:85]
	v_cvt_pk_bf16_f32 v82, v86, v87
	v_cvt_pk_bf16_f32 v83, v88, v89
	v_cvt_pk_bf16_f32 v84, v90, v91
	v_cvt_pk_bf16_f32 v85, v92, v93
	v_max_f32_e32 v74, 0, v74
	v_max_f32_e32 v75, 0, v75
	global_store_dwordx4 v[98:99], v[82:85], off offset:256
	v_max_f32_e32 v78, v78, v78
	v_max_f32_e32 v79, v79, v79
	v_pk_mul_f32 v[84:85], v[74:75], v[74:75]
	v_max_f32_e32 v75, v76, v76
	v_max_f32_e32 v74, v80, v80
	v_max_f32_e32 v76, 0, v75
	v_max_f32_e32 v75, v81, v81
	v_max_f32_e32 v78, 0, v78
	v_max_f32_e32 v79, 0, v79
	v_max_f32_e32 v74, 0, v74
	v_max_f32_e32 v75, 0, v75
	v_max_f32_e32 v77, 0, v77
	v_pk_mul_f32 v[78:79], v[78:79], v[78:79]
	v_pk_mul_f32 v[80:81], v[74:75], v[74:75]
	v_pk_mul_f32 v[86:87], v[76:77], v[76:77]
	v_lshl_add_u64 v[82:83], v[144:145], 1, s[18:19]
	v_cvt_pk_bf16_f32 v74, v78, v79
	v_cvt_pk_bf16_f32 v75, v80, v81
	v_cvt_pk_bf16_f32 v76, v84, v85
	v_cvt_pk_bf16_f32 v77, v86, v87
	v_max_f32_e32 v66, 0, v66
	v_max_f32_e32 v67, 0, v67
	global_store_dwordx4 v[82:83], v[74:77], off
	v_max_f32_e32 v70, v70, v70
	v_max_f32_e32 v71, v71, v71
	v_pk_mul_f32 v[74:75], v[66:67], v[66:67]
	v_max_f32_e32 v67, v68, v68
	v_max_f32_e32 v66, v72, v72
	v_max_f32_e32 v68, 0, v67
	v_max_f32_e32 v67, v73, v73
	v_max_f32_e32 v70, 0, v70
	v_max_f32_e32 v71, 0, v71
	v_max_f32_e32 v66, 0, v66
	v_max_f32_e32 v67, 0, v67
	v_max_f32_e32 v69, 0, v69
	v_pk_mul_f32 v[70:71], v[70:71], v[70:71]
	v_pk_mul_f32 v[72:73], v[66:67], v[66:67]
	v_pk_mul_f32 v[76:77], v[68:69], v[68:69]
	v_cvt_pk_bf16_f32 v66, v70, v71
	v_cvt_pk_bf16_f32 v67, v72, v73
	v_cvt_pk_bf16_f32 v68, v74, v75
	v_cvt_pk_bf16_f32 v69, v76, v77
	v_max_f32_e32 v58, 0, v58
	v_max_f32_e32 v59, 0, v59
	global_store_dwordx4 v[82:83], v[66:69], off offset:256
	v_max_f32_e32 v62, v62, v62
	v_max_f32_e32 v63, v63, v63
	v_pk_mul_f32 v[68:69], v[58:59], v[58:59]
	v_max_f32_e32 v59, v60, v60
	v_max_f32_e32 v58, v64, v64
	v_max_f32_e32 v60, 0, v59
	v_max_f32_e32 v59, v65, v65
	v_max_f32_e32 v62, 0, v62
	v_max_f32_e32 v63, 0, v63
	v_max_f32_e32 v58, 0, v58
	v_max_f32_e32 v59, 0, v59
	v_max_f32_e32 v61, 0, v61
	v_pk_mul_f32 v[62:63], v[62:63], v[62:63]
	v_pk_mul_f32 v[64:65], v[58:59], v[58:59]
	v_pk_mul_f32 v[70:71], v[60:61], v[60:61]
	v_lshl_add_u64 v[66:67], v[146:147], 1, s[18:19]
	v_cvt_pk_bf16_f32 v58, v62, v63
	v_cvt_pk_bf16_f32 v59, v64, v65
	v_cvt_pk_bf16_f32 v60, v68, v69
	v_cvt_pk_bf16_f32 v61, v70, v71
	v_max_f32_e32 v50, 0, v50
	v_max_f32_e32 v51, 0, v51
	global_store_dwordx4 v[66:67], v[58:61], off
	v_max_f32_e32 v54, v54, v54
	v_max_f32_e32 v55, v55, v55
	v_pk_mul_f32 v[58:59], v[50:51], v[50:51]
	v_max_f32_e32 v51, v52, v52
	v_max_f32_e32 v50, v56, v56
	v_max_f32_e32 v52, 0, v51
	v_max_f32_e32 v51, v57, v57
	v_max_f32_e32 v54, 0, v54
	v_max_f32_e32 v55, 0, v55
	v_max_f32_e32 v50, 0, v50
	v_max_f32_e32 v51, 0, v51
	v_max_f32_e32 v53, 0, v53
	v_pk_mul_f32 v[54:55], v[54:55], v[54:55]
	v_pk_mul_f32 v[56:57], v[50:51], v[50:51]
	v_pk_mul_f32 v[60:61], v[52:53], v[52:53]
	v_cvt_pk_bf16_f32 v50, v54, v55
	v_cvt_pk_bf16_f32 v51, v56, v57
	v_cvt_pk_bf16_f32 v52, v58, v59
	v_cvt_pk_bf16_f32 v53, v60, v61
	v_max_f32_e32 v42, 0, v42
	v_max_f32_e32 v43, 0, v43
	global_store_dwordx4 v[66:67], v[50:53], off offset:256
	v_max_f32_e32 v46, v46, v46
	v_max_f32_e32 v47, v47, v47
	v_pk_mul_f32 v[52:53], v[42:43], v[42:43]
	v_max_f32_e32 v43, v44, v44
	v_max_f32_e32 v42, v48, v48
	v_max_f32_e32 v44, 0, v43
	v_max_f32_e32 v43, v49, v49
	v_max_f32_e32 v46, 0, v46
	v_max_f32_e32 v47, 0, v47
	v_max_f32_e32 v42, 0, v42
	v_max_f32_e32 v43, 0, v43
	v_max_f32_e32 v45, 0, v45
	v_pk_mul_f32 v[46:47], v[46:47], v[46:47]
	v_pk_mul_f32 v[48:49], v[42:43], v[42:43]
	v_pk_mul_f32 v[54:55], v[44:45], v[44:45]
	v_lshl_add_u64 v[50:51], v[148:149], 1, s[18:19]
	v_cvt_pk_bf16_f32 v42, v46, v47
	v_cvt_pk_bf16_f32 v43, v48, v49
	v_cvt_pk_bf16_f32 v44, v52, v53
	v_cvt_pk_bf16_f32 v45, v54, v55
	v_max_f32_e32 v34, 0, v34
	v_max_f32_e32 v35, 0, v35
	global_store_dwordx4 v[50:51], v[42:45], off
	v_max_f32_e32 v38, v38, v38
	v_max_f32_e32 v39, v39, v39
	v_pk_mul_f32 v[42:43], v[34:35], v[34:35]
	v_max_f32_e32 v35, v36, v36
	v_max_f32_e32 v34, v40, v40
	v_max_f32_e32 v36, 0, v35
	v_max_f32_e32 v35, v41, v41
	v_max_f32_e32 v38, 0, v38
	v_max_f32_e32 v39, 0, v39
	v_max_f32_e32 v34, 0, v34
	v_max_f32_e32 v35, 0, v35
	v_max_f32_e32 v37, 0, v37
	v_pk_mul_f32 v[38:39], v[38:39], v[38:39]
	v_pk_mul_f32 v[40:41], v[34:35], v[34:35]
	v_pk_mul_f32 v[44:45], v[36:37], v[36:37]
	v_cvt_pk_bf16_f32 v34, v38, v39
	v_cvt_pk_bf16_f32 v35, v40, v41
	v_cvt_pk_bf16_f32 v36, v42, v43
	v_cvt_pk_bf16_f32 v37, v44, v45
	v_max_f32_e32 v26, 0, v26
	v_max_f32_e32 v27, 0, v27
	global_store_dwordx4 v[50:51], v[34:37], off offset:256
	v_max_f32_e32 v30, v30, v30
	v_max_f32_e32 v31, v31, v31
	v_pk_mul_f32 v[36:37], v[26:27], v[26:27]
	v_max_f32_e32 v27, v28, v28
	v_max_f32_e32 v26, v32, v32
	v_max_f32_e32 v28, 0, v27
	v_max_f32_e32 v27, v33, v33
	v_max_f32_e32 v30, 0, v30
	v_max_f32_e32 v31, 0, v31
	v_max_f32_e32 v26, 0, v26
	v_max_f32_e32 v27, 0, v27
	v_max_f32_e32 v29, 0, v29
	v_pk_mul_f32 v[30:31], v[30:31], v[30:31]
	v_pk_mul_f32 v[32:33], v[26:27], v[26:27]
	v_pk_mul_f32 v[38:39], v[28:29], v[28:29]
	v_lshl_add_u64 v[34:35], v[150:151], 1, s[18:19]
	v_cvt_pk_bf16_f32 v26, v30, v31
	v_cvt_pk_bf16_f32 v27, v32, v33
	v_cvt_pk_bf16_f32 v28, v36, v37
	v_cvt_pk_bf16_f32 v29, v38, v39
	v_max_f32_e32 v18, 0, v18
	v_max_f32_e32 v19, 0, v19
	global_store_dwordx4 v[34:35], v[26:29], off
	v_max_f32_e32 v22, v22, v22
	v_max_f32_e32 v23, v23, v23
	v_pk_mul_f32 v[26:27], v[18:19], v[18:19]
	v_max_f32_e32 v19, v20, v20
	v_max_f32_e32 v18, v24, v24
	v_max_f32_e32 v20, 0, v19
	v_max_f32_e32 v19, v25, v25
	v_max_f32_e32 v22, 0, v22
	v_max_f32_e32 v23, 0, v23
	v_max_f32_e32 v18, 0, v18
	v_max_f32_e32 v19, 0, v19
	v_max_f32_e32 v21, 0, v21
	v_pk_mul_f32 v[22:23], v[22:23], v[22:23]
	v_pk_mul_f32 v[24:25], v[18:19], v[18:19]
	v_pk_mul_f32 v[28:29], v[20:21], v[20:21]
	v_cvt_pk_bf16_f32 v18, v22, v23
	v_cvt_pk_bf16_f32 v19, v24, v25
	v_cvt_pk_bf16_f32 v20, v26, v27
	v_cvt_pk_bf16_f32 v21, v28, v29
	v_max_f32_e32 v10, 0, v10
	v_max_f32_e32 v11, 0, v11
	global_store_dwordx4 v[34:35], v[18:21], off offset:256
	v_max_f32_e32 v14, v14, v14
	v_max_f32_e32 v15, v15, v15
	v_pk_mul_f32 v[20:21], v[10:11], v[10:11]
	v_max_f32_e32 v11, v12, v12
	v_max_f32_e32 v10, v16, v16
	v_max_f32_e32 v12, 0, v11
	v_max_f32_e32 v11, v17, v17
	v_max_f32_e32 v14, 0, v14
	v_max_f32_e32 v15, 0, v15
	v_max_f32_e32 v10, 0, v10
	v_max_f32_e32 v11, 0, v11
	v_max_f32_e32 v13, 0, v13
	v_pk_mul_f32 v[14:15], v[14:15], v[14:15]
	v_pk_mul_f32 v[16:17], v[10:11], v[10:11]
	v_pk_mul_f32 v[22:23], v[12:13], v[12:13]
	v_lshl_add_u64 v[18:19], v[152:153], 1, s[18:19]
	v_cvt_pk_bf16_f32 v10, v14, v15
	v_cvt_pk_bf16_f32 v11, v16, v17
	v_cvt_pk_bf16_f32 v12, v20, v21
	v_cvt_pk_bf16_f32 v13, v22, v23
	v_max_f32_e32 v2, 0, v2
	v_max_f32_e32 v3, 0, v3
	global_store_dwordx4 v[18:19], v[10:13], off
	v_max_f32_e32 v6, v6, v6
	v_max_f32_e32 v7, v7, v7
	v_pk_mul_f32 v[10:11], v[2:3], v[2:3]
	v_max_f32_e32 v3, v4, v4
	v_max_f32_e32 v2, v8, v8
	v_max_f32_e32 v4, 0, v3
	v_max_f32_e32 v3, v9, v9
	v_max_f32_e32 v6, 0, v6
	v_max_f32_e32 v7, 0, v7
	v_max_f32_e32 v2, 0, v2
	v_max_f32_e32 v3, 0, v3
	v_max_f32_e32 v5, 0, v5
	v_pk_mul_f32 v[6:7], v[6:7], v[6:7]
	v_pk_mul_f32 v[8:9], v[2:3], v[2:3]
	v_pk_mul_f32 v[12:13], v[4:5], v[4:5]
	v_cvt_pk_bf16_f32 v2, v6, v7
	v_cvt_pk_bf16_f32 v3, v8, v9
	v_cvt_pk_bf16_f32 v4, v10, v11
	v_cvt_pk_bf16_f32 v5, v12, v13
	s_and_b64 vcc, exec, s[0:1]
	s_mov_b32 s51, s30
	s_mov_b32 s52, s38
	s_mov_b64 s[20:21], s[80:81]
	s_mov_b64 s[18:19], s[42:43]
	global_store_dwordx4 v[18:19], v[2:5], off offset:256
	s_cbranch_vccz .LBB0_742
	s_waitcnt vmcnt(0)
	v_readlane_b32 s38, v255, 28
	s_cmpk_gt_u32 s26, 0xff
	v_readlane_b32 s39, v255, 29
	v_readlane_b32 s42, v255, 32
	s_cbranch_scc1 .LBB0_753
	s_barrier

.LBB0_814:
	s_add_i32 s22, s55, 0xffff0000
	s_and_b32 s22, s22, 0x3e0000
	s_and_b32 s23, s90, 0x100
	s_or_b32 s56, s23, s22
	s_and_b32 s22, s55, 0x7e0000
	s_add_u32 vcc_lo, s90, 0x100
	s_addc_u32 vcc_hi, s91, 0
	s_and_b32 s23, vcc_lo, 0x100
	s_or_b32 s22, s22, s23
	s_add_u32 s22, s84, s22
	s_addc_u32 s23, s85, 0
	s_add_u32 s57, s30, s90
	s_addc_u32 s58, s31, s91
	s_add_u32 s57, s57, 0x100
	s_addc_u32 s58, s58, 0
	s_add_i32 s59, 0, 0x10000
	s_cmpk_eq_i32 s54, 0x7c
	s_cselect_b32 s91, s43, s58
	s_cselect_b32 s90, s53, s57
	s_cselect_b32 s23, s51, s23
	s_cselect_b32 s22, s52, s22
	s_add_u32 s56, s84, s56
	s_addc_u32 s57, s85, 0
	s_add_u32 s56, s56, 0x10080
	s_addc_u32 s57, s57, 0
	v_lshl_add_u64 v[204:205], s[56:57], 0, v[136:137]
	s_add_i32 m0, s28, 0xc000
	ds_read_b128 v[158:161], v140
	ds_read_b128 v[162:165], v140 offset:1024
	ds_read_b128 v[168:171], v140 offset:2048
	ds_read_b128 v[172:175], v140 offset:3072
	ds_read_b128 v[176:179], v140 offset:4096
	ds_read_b128 v[192:195], v140 offset:5120
	ds_read_b128 v[196:199], v140 offset:6144
	ds_read_b128 v[200:203], v140 offset:7168
	global_load_lds_dwordx4 v[204:205], off
	v_lshl_add_u64 v[204:205], s[56:57], 0, v[132:133]
	s_add_i32 m0, s28, 0xe000
	s_nop 0
	global_load_lds_dwordx4 v[204:205], off
	s_waitcnt lgkmcnt(8)
	s_barrier
	s_waitcnt lgkmcnt(0)
	v_mfma_f32_16x16x32_bf16 v[86:89], v[142:145], v[158:161], v[86:89]
	v_mfma_f32_16x16x32_bf16 v[94:97], v[150:153], v[158:161], v[94:97]
	v_mfma_f32_16x16x32_bf16 v[98:101], v[142:145], v[168:171], v[98:101]
	v_mfma_f32_16x16x32_bf16 v[102:105], v[150:153], v[168:171], v[102:105]
	v_mfma_f32_16x16x32_bf16 v[114:117], v[142:145], v[176:179], v[114:117]
	v_mfma_f32_16x16x32_bf16 v[122:125], v[150:153], v[176:179], v[122:125]
	v_mfma_f32_16x16x32_bf16 v[126:129], v[142:145], v[196:199], v[126:129]
	v_mfma_f32_16x16x32_bf16 v[118:121], v[150:153], v[196:199], v[118:121]
	v_mfma_f32_16x16x32_bf16 v[86:89], v[146:149], v[162:165], v[86:89]
	v_mfma_f32_16x16x32_bf16 v[94:97], v[154:157], v[162:165], v[94:97]
	v_mfma_f32_16x16x32_bf16 v[98:101], v[146:149], v[172:175], v[98:101]
	v_mfma_f32_16x16x32_bf16 v[102:105], v[154:157], v[172:175], v[102:105]
	v_mfma_f32_16x16x32_bf16 v[114:117], v[146:149], v[192:195], v[114:117]
	v_mfma_f32_16x16x32_bf16 v[122:125], v[154:157], v[192:195], v[122:125]
	v_mfma_f32_16x16x32_bf16 v[126:129], v[146:149], v[200:203], v[126:129]
	v_mfma_f32_16x16x32_bf16 v[118:121], v[154:157], v[200:203], v[118:121]
	s_barrier
	s_add_i32 s58, 0, 0x14000
	s_add_i32 s56, s59, s81
	v_add_u32_e32 v141, s58, v139
	v_lshl_add_u64 v[212:213], s[90:91], 0, v[134:135]
	s_mov_b32 m0, s56
	ds_read_b128 v[204:207], v141
	ds_read_b128 v[208:211], v141 offset:1024
	ds_read_b128 v[224:227], v141 offset:2048
	ds_read_b128 v[228:231], v141 offset:3072
	global_load_lds_dwordx4 v[212:213], off
	v_lshl_add_u64 v[222:223], s[90:91], 0, v[130:131]
	s_add_i32 m0, s56, 0x2000
	s_nop 0
	global_load_lds_dwordx4 v[222:223], off
	s_mov_b32 m0, s28
	v_lshl_add_u64 v[232:233], s[22:23], 0, v[136:137]
	s_waitcnt lgkmcnt(0)
	s_barrier
	v_mfma_f32_16x16x32_bf16 v[2:5], v[204:207], v[158:161], v[2:5]
	v_mfma_f32_16x16x32_bf16 v[6:9], v[224:227], v[158:161], v[6:9]
	v_mfma_f32_16x16x32_bf16 v[10:13], v[204:207], v[168:171], v[10:13]
	v_mfma_f32_16x16x32_bf16 v[14:17], v[224:227], v[168:171], v[14:17]
	v_mfma_f32_16x16x32_bf16 v[22:25], v[204:207], v[176:179], v[22:25]
	v_mfma_f32_16x16x32_bf16 v[18:21], v[224:227], v[176:179], v[18:21]
	v_mfma_f32_16x16x32_bf16 v[30:33], v[204:207], v[196:199], v[30:33]
	v_mfma_f32_16x16x32_bf16 v[26:29], v[224:227], v[196:199], v[26:29]
	v_mfma_f32_16x16x32_bf16 v[2:5], v[208:211], v[162:165], v[2:5]
	v_mfma_f32_16x16x32_bf16 v[6:9], v[228:231], v[162:165], v[6:9]
	v_mfma_f32_16x16x32_bf16 v[10:13], v[208:211], v[172:175], v[10:13]
	v_mfma_f32_16x16x32_bf16 v[14:17], v[228:231], v[172:175], v[14:17]
	v_mfma_f32_16x16x32_bf16 v[22:25], v[208:211], v[192:195], v[22:25]
	v_mfma_f32_16x16x32_bf16 v[18:21], v[228:231], v[192:195], v[18:21]
	v_mfma_f32_16x16x32_bf16 v[30:33], v[208:211], v[200:203], v[30:33]
	v_mfma_f32_16x16x32_bf16 v[26:29], v[228:231], v[200:203], v[26:29]
	s_barrier
	ds_read_b128 v[158:161], v140 offset:16384
	ds_read_b128 v[162:165], v140 offset:17408
	ds_read_b128 v[168:171], v140 offset:18432
	ds_read_b128 v[172:175], v140 offset:19456
	ds_read_b128 v[176:179], v140 offset:20480
	ds_read_b128 v[192:195], v140 offset:21504
	ds_read_b128 v[196:199], v140 offset:22528
	ds_read_b128 v[200:203], v140 offset:23552
	global_load_lds_dwordx4 v[232:233], off
	v_lshl_add_u64 v[234:235], s[22:23], 0, v[132:133]
	s_mov_b32 m0, s29
	s_nop 0
	global_load_lds_dwordx4 v[234:235], off
	s_waitcnt vmcnt(10)
	s_barrier
	s_waitcnt lgkmcnt(0)
	v_mfma_f32_16x16x32_bf16 v[110:113], v[142:145], v[158:161], v[110:113]
	v_mfma_f32_16x16x32_bf16 v[106:109], v[150:153], v[158:161], v[106:109]
	v_mfma_f32_16x16x32_bf16 v[90:93], v[142:145], v[168:171], v[90:93]
	v_mfma_f32_16x16x32_bf16 v[82:85], v[150:153], v[168:171], v[82:85]
	v_mfma_f32_16x16x32_bf16 v[78:81], v[142:145], v[176:179], v[78:81]
	v_mfma_f32_16x16x32_bf16 v[74:77], v[150:153], v[176:179], v[74:77]
	v_mfma_f32_16x16x32_bf16 v[70:73], v[142:145], v[196:199], v[70:73]
	v_mfma_f32_16x16x32_bf16 v[66:69], v[150:153], v[196:199], v[66:69]
	v_mfma_f32_16x16x32_bf16 v[110:113], v[146:149], v[162:165], v[110:113]
	v_mfma_f32_16x16x32_bf16 v[106:109], v[154:157], v[162:165], v[106:109]
	v_mfma_f32_16x16x32_bf16 v[90:93], v[146:149], v[172:175], v[90:93]
	v_mfma_f32_16x16x32_bf16 v[82:85], v[154:157], v[172:175], v[82:85]
	v_mfma_f32_16x16x32_bf16 v[78:81], v[146:149], v[192:195], v[78:81]
	v_mfma_f32_16x16x32_bf16 v[74:77], v[154:157], v[192:195], v[74:77]
	v_mfma_f32_16x16x32_bf16 v[70:73], v[146:149], v[200:203], v[70:73]
	v_mfma_f32_16x16x32_bf16 v[66:69], v[154:157], v[200:203], v[66:69]
	s_barrier
	s_add_u32 s56, s90, 0x200000
	s_addc_u32 s57, s91, 0
	s_add_i32 s58, s58, s81
	v_lshl_add_u64 v[142:143], s[56:57], 0, v[134:135]
	s_mov_b32 m0, s58
	s_nop 0
	global_load_lds_dwordx4 v[142:143], off
	v_lshl_add_u64 v[142:143], s[56:57], 0, v[130:131]
	s_add_i32 m0, s58, 0x2000
	s_nop 0
	global_load_lds_dwordx4 v[142:143], off
	v_add_u32_e32 v141, 0x18000, v139
	ds_read_b128 v[142:145], v141
	ds_read_b128 v[146:149], v141 offset:1024
	ds_read_b128 v[150:153], v141 offset:2048
	ds_read_b128 v[154:157], v141 offset:3072
	s_add_i32 s56, 0, 0x18000
	s_waitcnt vmcnt(6)
	s_barrier
	v_mfma_f32_16x16x32_bf16 v[38:41], v[204:207], v[158:161], v[38:41]
	v_mfma_f32_16x16x32_bf16 v[34:37], v[224:227], v[158:161], v[34:37]
	v_mfma_f32_16x16x32_bf16 v[46:49], v[204:207], v[168:171], v[46:49]
	v_mfma_f32_16x16x32_bf16 v[42:45], v[224:227], v[168:171], v[42:45]
	v_mfma_f32_16x16x32_bf16 v[54:57], v[204:207], v[176:179], v[54:57]
	v_mfma_f32_16x16x32_bf16 v[50:53], v[224:227], v[176:179], v[50:53]
	v_mfma_f32_16x16x32_bf16 v[62:65], v[204:207], v[196:199], v[62:65]
	v_mfma_f32_16x16x32_bf16 v[58:61], v[224:227], v[196:199], v[58:61]
	v_mfma_f32_16x16x32_bf16 v[38:41], v[208:211], v[162:165], v[38:41]
	v_mfma_f32_16x16x32_bf16 v[34:37], v[228:231], v[162:165], v[34:37]
	v_mfma_f32_16x16x32_bf16 v[46:49], v[208:211], v[172:175], v[46:49]
	v_mfma_f32_16x16x32_bf16 v[42:45], v[228:231], v[172:175], v[42:45]
	v_mfma_f32_16x16x32_bf16 v[54:57], v[208:211], v[192:195], v[54:57]
	v_mfma_f32_16x16x32_bf16 v[50:53], v[228:231], v[192:195], v[50:53]
	v_mfma_f32_16x16x32_bf16 v[62:65], v[208:211], v[200:203], v[62:65]
	v_mfma_f32_16x16x32_bf16 v[58:61], v[228:231], v[200:203], v[58:61]
	s_barrier
	s_add_u32 s22, s22, 0x10000
	s_addc_u32 s23, s23, 0
	s_mov_b32 m0, s44
	v_lshl_add_u64 v[204:205], s[22:23], 0, v[136:137]
	ds_read_b128 v[158:161], v140 offset:32768
	ds_read_b128 v[162:165], v140 offset:33792
	ds_read_b128 v[168:171], v140 offset:34816
	ds_read_b128 v[172:175], v140 offset:35840
	ds_read_b128 v[176:179], v140 offset:36864
	ds_read_b128 v[192:195], v140 offset:37888
	ds_read_b128 v[196:199], v140 offset:38912
	ds_read_b128 v[200:203], v140 offset:39936
	global_load_lds_dwordx4 v[204:205], off
	v_lshl_add_u64 v[204:205], s[22:23], 0, v[132:133]
	s_mov_b32 m0, s45
	s_nop 0
	global_load_lds_dwordx4 v[204:205], off
	s_waitcnt lgkmcnt(8)
	s_barrier
	s_waitcnt lgkmcnt(0)
	v_mfma_f32_16x16x32_bf16 v[86:89], v[142:145], v[158:161], v[86:89]
	v_mfma_f32_16x16x32_bf16 v[94:97], v[150:153], v[158:161], v[94:97]
	v_mfma_f32_16x16x32_bf16 v[98:101], v[142:145], v[168:171], v[98:101]
	v_mfma_f32_16x16x32_bf16 v[102:105], v[150:153], v[168:171], v[102:105]
	v_mfma_f32_16x16x32_bf16 v[114:117], v[142:145], v[176:179], v[114:117]
	v_mfma_f32_16x16x32_bf16 v[122:125], v[150:153], v[176:179], v[122:125]
	v_mfma_f32_16x16x32_bf16 v[126:129], v[142:145], v[196:199], v[126:129]
	v_mfma_f32_16x16x32_bf16 v[118:121], v[150:153], v[196:199], v[118:121]
	v_mfma_f32_16x16x32_bf16 v[86:89], v[146:149], v[162:165], v[86:89]
	v_mfma_f32_16x16x32_bf16 v[94:97], v[154:157], v[162:165], v[94:97]
	v_mfma_f32_16x16x32_bf16 v[98:101], v[146:149], v[172:175], v[98:101]
	v_mfma_f32_16x16x32_bf16 v[102:105], v[154:157], v[172:175], v[102:105]
	v_mfma_f32_16x16x32_bf16 v[114:117], v[146:149], v[192:195], v[114:117]
	v_mfma_f32_16x16x32_bf16 v[122:125], v[154:157], v[192:195], v[122:125]
	v_mfma_f32_16x16x32_bf16 v[126:129], v[146:149], v[200:203], v[126:129]
	v_mfma_f32_16x16x32_bf16 v[118:121], v[154:157], v[200:203], v[118:121]
	s_barrier
	s_add_i32 s57, 0, 0x1c000
	s_add_i32 s22, s56, s81
	v_add_u32_e32 v141, s57, v139
	v_lshl_add_u64 v[212:213], v[212:213], 0, s[78:79]
	s_mov_b32 m0, s22
	ds_read_b128 v[204:207], v141
	ds_read_b128 v[208:211], v141 offset:1024
	ds_read_b128 v[224:227], v141 offset:2048
	ds_read_b128 v[228:231], v141 offset:3072
	global_load_lds_dwordx4 v[212:213], off
	v_lshl_add_u64 v[212:213], v[222:223], 0, s[78:79]
	s_add_i32 m0, s22, 0x2000
	s_nop 0
	global_load_lds_dwordx4 v[212:213], off
	s_mov_b32 m0, s47
	v_lshl_add_u64 v[212:213], v[232:233], 0, s[78:79]
	s_waitcnt lgkmcnt(0)
	s_barrier
	v_mfma_f32_16x16x32_bf16 v[2:5], v[204:207], v[158:161], v[2:5]
	v_mfma_f32_16x16x32_bf16 v[6:9], v[224:227], v[158:161], v[6:9]
	v_mfma_f32_16x16x32_bf16 v[10:13], v[204:207], v[168:171], v[10:13]
	v_mfma_f32_16x16x32_bf16 v[14:17], v[224:227], v[168:171], v[14:17]
	v_mfma_f32_16x16x32_bf16 v[22:25], v[204:207], v[176:179], v[22:25]
	v_mfma_f32_16x16x32_bf16 v[18:21], v[224:227], v[176:179], v[18:21]
	v_mfma_f32_16x16x32_bf16 v[30:33], v[204:207], v[196:199], v[30:33]
	v_mfma_f32_16x16x32_bf16 v[26:29], v[224:227], v[196:199], v[26:29]
	v_mfma_f32_16x16x32_bf16 v[2:5], v[208:211], v[162:165], v[2:5]
	v_mfma_f32_16x16x32_bf16 v[6:9], v[228:231], v[162:165], v[6:9]
	v_mfma_f32_16x16x32_bf16 v[10:13], v[208:211], v[172:175], v[10:13]
	v_mfma_f32_16x16x32_bf16 v[14:17], v[228:231], v[172:175], v[14:17]
	v_mfma_f32_16x16x32_bf16 v[22:25], v[208:211], v[192:195], v[22:25]
	v_mfma_f32_16x16x32_bf16 v[18:21], v[228:231], v[192:195], v[18:21]
	v_mfma_f32_16x16x32_bf16 v[30:33], v[208:211], v[200:203], v[30:33]
	v_mfma_f32_16x16x32_bf16 v[26:29], v[228:231], v[200:203], v[26:29]
	s_barrier
	ds_read_b128 v[158:161], v140 offset:49152
	ds_read_b128 v[162:165], v140 offset:50176
	ds_read_b128 v[168:171], v140 offset:51200
	ds_read_b128 v[172:175], v140 offset:52224
	ds_read_b128 v[176:179], v140 offset:53248
	ds_read_b128 v[192:195], v140 offset:54272
	ds_read_b128 v[196:199], v140 offset:55296
	ds_read_b128 v[200:203], v140 offset:56320
	global_load_lds_dwordx4 v[212:213], off
	v_lshl_add_u64 v[212:213], v[234:235], 0, s[78:79]
	s_mov_b32 m0, s48
	s_nop 0
	global_load_lds_dwordx4 v[212:213], off
	s_waitcnt vmcnt(10)
	s_barrier
	s_waitcnt lgkmcnt(0)
	v_mfma_f32_16x16x32_bf16 v[110:113], v[142:145], v[158:161], v[110:113]
	v_mfma_f32_16x16x32_bf16 v[106:109], v[150:153], v[158:161], v[106:109]
	v_mfma_f32_16x16x32_bf16 v[90:93], v[142:145], v[168:171], v[90:93]
	v_mfma_f32_16x16x32_bf16 v[82:85], v[150:153], v[168:171], v[82:85]
	v_mfma_f32_16x16x32_bf16 v[78:81], v[142:145], v[176:179], v[78:81]
	v_mfma_f32_16x16x32_bf16 v[74:77], v[150:153], v[176:179], v[74:77]
	v_mfma_f32_16x16x32_bf16 v[70:73], v[142:145], v[196:199], v[70:73]
	v_mfma_f32_16x16x32_bf16 v[66:69], v[150:153], v[196:199], v[66:69]
	v_mfma_f32_16x16x32_bf16 v[110:113], v[146:149], v[162:165], v[110:113]
	v_mfma_f32_16x16x32_bf16 v[106:109], v[154:157], v[162:165], v[106:109]
	v_mfma_f32_16x16x32_bf16 v[90:93], v[146:149], v[172:175], v[90:93]
	v_mfma_f32_16x16x32_bf16 v[82:85], v[154:157], v[172:175], v[82:85]
	v_mfma_f32_16x16x32_bf16 v[78:81], v[146:149], v[192:195], v[78:81]
	v_mfma_f32_16x16x32_bf16 v[74:77], v[154:157], v[192:195], v[74:77]
	v_mfma_f32_16x16x32_bf16 v[70:73], v[146:149], v[200:203], v[70:73]
	v_mfma_f32_16x16x32_bf16 v[66:69], v[154:157], v[200:203], v[66:69]
	s_barrier
	s_add_u32 s22, s90, 0x200080
	s_addc_u32 s23, s91, 0
	s_add_i32 s56, s57, s81
	v_lshl_add_u64 v[142:143], s[22:23], 0, v[134:135]
	s_mov_b32 m0, s56
	s_nop 0
	global_load_lds_dwordx4 v[142:143], off
	v_lshl_add_u64 v[142:143], s[22:23], 0, v[130:131]
	s_add_i32 m0, s56, 0x2000
	s_nop 0
	global_load_lds_dwordx4 v[142:143], off
	v_add_u32_e32 v141, 0x10000, v139
	ds_read_b128 v[142:145], v141
	ds_read_b128 v[146:149], v141 offset:1024
	ds_read_b128 v[150:153], v141 offset:2048
	ds_read_b128 v[154:157], v141 offset:3072
	s_add_i32 s54, s54, 2
	s_add_i32 s55, s55, 0x10000
	s_cmpk_gt_u32 s54, 0x7d
	s_mov_b64 s[90:91], vcc
	s_waitcnt vmcnt(6)
	s_barrier
	v_mfma_f32_16x16x32_bf16 v[38:41], v[204:207], v[158:161], v[38:41]
	v_mfma_f32_16x16x32_bf16 v[34:37], v[224:227], v[158:161], v[34:37]
	v_mfma_f32_16x16x32_bf16 v[46:49], v[204:207], v[168:171], v[46:49]
	v_mfma_f32_16x16x32_bf16 v[42:45], v[224:227], v[168:171], v[42:45]
	v_mfma_f32_16x16x32_bf16 v[54:57], v[204:207], v[176:179], v[54:57]
	v_mfma_f32_16x16x32_bf16 v[50:53], v[224:227], v[176:179], v[50:53]
	v_mfma_f32_16x16x32_bf16 v[62:65], v[204:207], v[196:199], v[62:65]
	v_mfma_f32_16x16x32_bf16 v[58:61], v[224:227], v[196:199], v[58:61]
	v_mfma_f32_16x16x32_bf16 v[38:41], v[208:211], v[162:165], v[38:41]
	v_mfma_f32_16x16x32_bf16 v[34:37], v[228:231], v[162:165], v[34:37]
	v_mfma_f32_16x16x32_bf16 v[46:49], v[208:211], v[172:175], v[46:49]
	v_mfma_f32_16x16x32_bf16 v[42:45], v[228:231], v[172:175], v[42:45]
	v_mfma_f32_16x16x32_bf16 v[54:57], v[208:211], v[192:195], v[54:57]
	v_mfma_f32_16x16x32_bf16 v[50:53], v[228:231], v[192:195], v[50:53]
	v_mfma_f32_16x16x32_bf16 v[62:65], v[208:211], v[200:203], v[62:65]
	v_mfma_f32_16x16x32_bf16 v[58:61], v[228:231], v[200:203], v[58:61]
	s_barrier
	s_cbranch_scc0 .LBB0_814
	s_waitcnt lgkmcnt(0)
	s_andn2_b64 vcc, exec, s[38:39]
	s_cbranch_vccnz .LBB0_806
	v_mov_b32_e32 v58, 0
	s_mov_b32 s80, s42
	s_mov_b32 s25, s82
	s_mov_b64 s[30:31], s[20:21]
	s_mov_b64 s[84:85], s[18:19]
	s_mov_b32 s49, s50
	v_mov_b32_e32 v59, v58
	v_mov_b32_e32 v60, v58
	v_mov_b32_e32 v61, v58
	v_mov_b32_e32 v62, v58
	v_mov_b32_e32 v63, v58
	v_mov_b32_e32 v64, v58
	v_mov_b32_e32 v65, v58
	v_mov_b32_e32 v50, v58
	v_mov_b32_e32 v51, v58
	v_mov_b32_e32 v52, v58
	v_mov_b32_e32 v53, v58
	v_mov_b32_e32 v54, v58
	v_mov_b32_e32 v55, v58
	v_mov_b32_e32 v56, v58
	v_mov_b32_e32 v57, v58
	v_mov_b32_e32 v42, v58
	v_mov_b32_e32 v43, v58
	v_mov_b32_e32 v44, v58
	v_mov_b32_e32 v45, v58
	v_mov_b32_e32 v46, v58
	v_mov_b32_e32 v47, v58
	v_mov_b32_e32 v48, v58
	v_mov_b32_e32 v49, v58
	v_mov_b32_e32 v34, v58
	v_mov_b32_e32 v35, v58
	v_mov_b32_e32 v36, v58
	v_mov_b32_e32 v37, v58
	v_mov_b32_e32 v38, v58
	v_mov_b32_e32 v39, v58
	v_mov_b32_e32 v40, v58
	v_mov_b32_e32 v41, v58
	v_mov_b32_e32 v66, v58
	v_mov_b32_e32 v67, v58
	v_mov_b32_e32 v68, v58
	v_mov_b32_e32 v69, v58
	v_mov_b32_e32 v70, v58
	v_mov_b32_e32 v71, v58
	v_mov_b32_e32 v72, v58
	v_mov_b32_e32 v73, v58
	v_mov_b32_e32 v74, v58
	v_mov_b32_e32 v75, v58
	v_mov_b32_e32 v76, v58
	v_mov_b32_e32 v77, v58
	v_mov_b32_e32 v78, v58
	v_mov_b32_e32 v79, v58
	v_mov_b32_e32 v80, v58
	v_mov_b32_e32 v81, v58
	v_mov_b32_e32 v82, v58
	v_mov_b32_e32 v83, v58
	v_mov_b32_e32 v84, v58
	v_mov_b32_e32 v85, v58
	v_mov_b32_e32 v90, v58
	v_mov_b32_e32 v91, v58
	v_mov_b32_e32 v92, v58
	v_mov_b32_e32 v93, v58
	v_mov_b32_e32 v106, v58
	v_mov_b32_e32 v107, v58
	v_mov_b32_e32 v108, v58
	v_mov_b32_e32 v109, v58
	v_mov_b32_e32 v110, v58
	v_mov_b32_e32 v111, v58
	v_mov_b32_e32 v112, v58
	v_mov_b32_e32 v113, v58
	v_mov_b32_e32 v26, v58
	v_mov_b32_e32 v27, v58
	v_mov_b32_e32 v28, v58
	v_mov_b32_e32 v29, v58
	v_mov_b32_e32 v30, v58
	v_mov_b32_e32 v31, v58
	v_mov_b32_e32 v32, v58
	v_mov_b32_e32 v33, v58
	v_mov_b32_e32 v18, v58
	v_mov_b32_e32 v19, v58
	v_mov_b32_e32 v20, v58
	v_mov_b32_e32 v21, v58
	v_mov_b32_e32 v22, v58
	v_mov_b32_e32 v23, v58
	v_mov_b32_e32 v24, v58
	v_mov_b32_e32 v25, v58
	v_mov_b32_e32 v14, v58
	v_mov_b32_e32 v15, v58
	v_mov_b32_e32 v16, v58
	v_mov_b32_e32 v17, v58
	v_mov_b32_e32 v10, v58
	v_mov_b32_e32 v11, v58
	v_mov_b32_e32 v12, v58
	v_mov_b32_e32 v13, v58
	v_mov_b32_e32 v6, v58
	v_mov_b32_e32 v7, v58
	v_mov_b32_e32 v8, v58
	v_mov_b32_e32 v9, v58
	v_mov_b32_e32 v2, v58
	v_mov_b32_e32 v3, v58
	v_mov_b32_e32 v4, v58
	v_mov_b32_e32 v5, v58
	v_mov_b32_e32 v118, v58
	v_mov_b32_e32 v119, v58
	v_mov_b32_e32 v120, v58
	v_mov_b32_e32 v121, v58
	v_mov_b32_e32 v126, v58
	v_mov_b32_e32 v127, v58
	v_mov_b32_e32 v128, v58
	v_mov_b32_e32 v129, v58
	v_mov_b32_e32 v122, v58
	v_mov_b32_e32 v123, v58
	v_mov_b32_e32 v124, v58
	v_mov_b32_e32 v125, v58
	v_mov_b32_e32 v114, v58
	v_mov_b32_e32 v115, v58
	v_mov_b32_e32 v116, v58
	v_mov_b32_e32 v117, v58
	v_mov_b32_e32 v102, v58
	v_mov_b32_e32 v103, v58
	v_mov_b32_e32 v104, v58
	v_mov_b32_e32 v105, v58
	v_mov_b32_e32 v98, v58
	v_mov_b32_e32 v99, v58
	v_mov_b32_e32 v100, v58
	v_mov_b32_e32 v101, v58
	v_mov_b32_e32 v94, v58
	v_mov_b32_e32 v95, v58
	v_mov_b32_e32 v96, v58
	v_mov_b32_e32 v97, v58
	v_mov_b32_e32 v86, v58
	v_mov_b32_e32 v87, v58
	v_mov_b32_e32 v88, v58
	v_mov_b32_e32 v89, v58
	s_branch .LBB0_806
